# attention K-loop rewrite (pipelined LDS reads, in-place softmax, ping-pong stagger, V key-permuted LDS layout), GEMM K-loops re-pipelined + DMA interleaved, out-proj epilogue pipelined
# speedup vs baseline: 1.0472x; 1.0472x over previous
.LBB0_127:
	v_readfirstlane_b32 s6, v136
	s_xor_b32 m0, s20, 1
	s_lshl_b32 m0, m0, 16
	s_add_i32 s6, s6, m0
	v_add3_u32 v178, s10, v149, v150
	v_add_u32_e32 v174, v178, v152
	v_add3_u32 v179, s10, v151, v150
	v_add_u32_e32 v180, v179, v152
	ds_read_b128 v[154:157], v174 offset:32768
	ds_read_b128 v[158:161], v174 offset:34816
	ds_read_b128 v[170:173], v174 offset:36864
	ds_read_b128 v[174:177], v174 offset:38912
	ds_read_b128 v[162:165], v180
	ds_read_b128 v[166:169], v180 offset:2048
	ds_read_b128 v[242:245], v180 offset:4096
	ds_read_b128 v[246:249], v180 offset:6144
	s_mov_b32 m0, s6
	v_lshl_add_u64 v[254:255], v[128:129], 0, s[4:5]
	global_load_lds_dwordx4 v[254:255], off
	s_add_i32 m0, s6, 0x2000
	v_lshl_add_u64 v[254:255], v[130:131], 0, s[4:5]
	global_load_lds_dwordx4 v[254:255], off
	s_waitcnt lgkmcnt(2)
	v_mfma_f32_16x16x32_bf16 v[120:123], v[154:157], v[162:165], v[120:123]
	v_add_u32_e32 v178, v178, v153
	v_add_u32_e32 v179, v179, v153
	v_mfma_f32_16x16x32_bf16 v[104:107], v[154:157], v[166:169], v[104:107]
	v_mfma_f32_16x16x32_bf16 v[116:119], v[158:161], v[162:165], v[116:119]
	v_mfma_f32_16x16x32_bf16 v[100:103], v[158:161], v[166:169], v[100:103]
	s_add_i32 m0, s6, 0x4000
	v_lshl_add_u64 v[254:255], v[132:133], 0, s[4:5]
	global_load_lds_dwordx4 v[254:255], off
	v_mfma_f32_16x16x32_bf16 v[124:127], v[170:173], v[162:165], v[124:127]
	v_mfma_f32_16x16x32_bf16 v[108:111], v[170:173], v[166:169], v[108:111]
	v_mfma_f32_16x16x32_bf16 v[112:115], v[174:177], v[162:165], v[112:115]
	v_mfma_f32_16x16x32_bf16 v[96:99], v[174:177], v[166:169], v[96:99]
	s_add_i32 m0, s6, 0x6000
	v_lshl_add_u64 v[254:255], v[134:135], 0, s[4:5]
	global_load_lds_dwordx4 v[254:255], off
	ds_read_b128 v[162:165], v180 offset:8192
	ds_read_b128 v[166:169], v180 offset:10240
	s_waitcnt lgkmcnt(2)
	v_mfma_f32_16x16x32_bf16 v[88:91], v[154:157], v[242:245], v[88:91]
	v_mfma_f32_16x16x32_bf16 v[72:75], v[154:157], v[246:249], v[72:75]
	v_mfma_f32_16x16x32_bf16 v[84:87], v[158:161], v[242:245], v[84:87]
	v_mfma_f32_16x16x32_bf16 v[68:71], v[158:161], v[246:249], v[68:71]
	s_add_i32 m0, s6, 0x8000
	v_lshl_add_u64 v[254:255], v[138:139], 0, s[4:5]
	global_load_lds_dwordx4 v[254:255], off
	v_mfma_f32_16x16x32_bf16 v[92:95], v[170:173], v[242:245], v[92:95]
	v_mfma_f32_16x16x32_bf16 v[76:79], v[170:173], v[246:249], v[76:79]
	v_mfma_f32_16x16x32_bf16 v[80:83], v[174:177], v[242:245], v[80:83]
	v_mfma_f32_16x16x32_bf16 v[64:67], v[174:177], v[246:249], v[64:67]
	s_add_i32 m0, s6, 0xa000
	v_lshl_add_u64 v[254:255], v[140:141], 0, s[4:5]
	global_load_lds_dwordx4 v[254:255], off
	ds_read_b128 v[242:245], v180 offset:12288
	ds_read_b128 v[246:249], v180 offset:14336
	s_waitcnt lgkmcnt(2)
	v_mfma_f32_16x16x32_bf16 v[56:59], v[154:157], v[162:165], v[56:59]
	v_mfma_f32_16x16x32_bf16 v[40:43], v[154:157], v[166:169], v[40:43]
	v_mfma_f32_16x16x32_bf16 v[52:55], v[158:161], v[162:165], v[52:55]
	v_mfma_f32_16x16x32_bf16 v[36:39], v[158:161], v[166:169], v[36:39]
	s_add_i32 m0, s6, 0xc000
	v_lshl_add_u64 v[254:255], v[142:143], 0, s[4:5]
	global_load_lds_dwordx4 v[254:255], off
	v_mfma_f32_16x16x32_bf16 v[60:63], v[170:173], v[162:165], v[60:63]
	v_mfma_f32_16x16x32_bf16 v[44:47], v[170:173], v[166:169], v[44:47]
	v_mfma_f32_16x16x32_bf16 v[48:51], v[174:177], v[162:165], v[48:51]
	v_mfma_f32_16x16x32_bf16 v[32:35], v[174:177], v[166:169], v[32:35]
	s_add_i32 m0, s6, 0xe000
	v_lshl_add_u64 v[254:255], v[144:145], 0, s[4:5]
	global_load_lds_dwordx4 v[254:255], off
	s_add_u32 s4, s4, 0x80
	s_addc_u32 s5, s5, 0
	s_add_i32 s3, s3, 1
	s_cmpk_lg_i32 s4, 0x800
	ds_read_b128 v[162:165], v179
	ds_read_b128 v[166:169], v179 offset:2048
	s_waitcnt lgkmcnt(2)
	v_mfma_f32_16x16x32_bf16 v[24:27], v[154:157], v[242:245], v[24:27]
	v_mfma_f32_16x16x32_bf16 v[4:7], v[154:157], v[246:249], v[4:7]
	ds_read_b128 v[154:157], v178 offset:32768
	v_mfma_f32_16x16x32_bf16 v[20:23], v[158:161], v[242:245], v[20:23]
	v_mfma_f32_16x16x32_bf16 v[0:3], v[158:161], v[246:249], v[0:3]
	ds_read_b128 v[158:161], v178 offset:34816
	v_mfma_f32_16x16x32_bf16 v[28:31], v[170:173], v[242:245], v[28:31]
	v_mfma_f32_16x16x32_bf16 v[8:11], v[170:173], v[246:249], v[8:11]
	ds_read_b128 v[170:173], v178 offset:36864
	v_mfma_f32_16x16x32_bf16 v[16:19], v[174:177], v[242:245], v[16:19]
	v_mfma_f32_16x16x32_bf16 v[12:15], v[174:177], v[246:249], v[12:15]
	ds_read_b128 v[174:177], v178 offset:38912
	ds_read_b128 v[242:245], v179 offset:4096
	ds_read_b128 v[246:249], v179 offset:6144
	s_waitcnt lgkmcnt(2)
	v_mfma_f32_16x16x32_bf16 v[120:123], v[154:157], v[162:165], v[120:123]
	v_mfma_f32_16x16x32_bf16 v[104:107], v[154:157], v[166:169], v[104:107]
	v_mfma_f32_16x16x32_bf16 v[116:119], v[158:161], v[162:165], v[116:119]
	v_mfma_f32_16x16x32_bf16 v[100:103], v[158:161], v[166:169], v[100:103]
	v_mfma_f32_16x16x32_bf16 v[124:127], v[170:173], v[162:165], v[124:127]
	v_mfma_f32_16x16x32_bf16 v[108:111], v[170:173], v[166:169], v[108:111]
	v_mfma_f32_16x16x32_bf16 v[112:115], v[174:177], v[162:165], v[112:115]
	v_mfma_f32_16x16x32_bf16 v[96:99], v[174:177], v[166:169], v[96:99]
	ds_read_b128 v[162:165], v179 offset:8192
	ds_read_b128 v[166:169], v179 offset:10240
	s_waitcnt lgkmcnt(2)
	v_mfma_f32_16x16x32_bf16 v[88:91], v[154:157], v[242:245], v[88:91]
	v_mfma_f32_16x16x32_bf16 v[72:75], v[154:157], v[246:249], v[72:75]
	v_mfma_f32_16x16x32_bf16 v[84:87], v[158:161], v[242:245], v[84:87]
	v_mfma_f32_16x16x32_bf16 v[68:71], v[158:161], v[246:249], v[68:71]
	v_mfma_f32_16x16x32_bf16 v[92:95], v[170:173], v[242:245], v[92:95]
	v_mfma_f32_16x16x32_bf16 v[76:79], v[170:173], v[246:249], v[76:79]
	v_mfma_f32_16x16x32_bf16 v[80:83], v[174:177], v[242:245], v[80:83]
	v_mfma_f32_16x16x32_bf16 v[64:67], v[174:177], v[246:249], v[64:67]
	ds_read_b128 v[242:245], v179 offset:12288
	ds_read_b128 v[246:249], v179 offset:14336
	s_waitcnt lgkmcnt(2)
	v_mfma_f32_16x16x32_bf16 v[56:59], v[154:157], v[162:165], v[56:59]
	v_mfma_f32_16x16x32_bf16 v[40:43], v[154:157], v[166:169], v[40:43]
	v_mfma_f32_16x16x32_bf16 v[52:55], v[158:161], v[162:165], v[52:55]
	v_mfma_f32_16x16x32_bf16 v[36:39], v[158:161], v[166:169], v[36:39]
	v_mfma_f32_16x16x32_bf16 v[60:63], v[170:173], v[162:165], v[60:63]
	v_mfma_f32_16x16x32_bf16 v[44:47], v[170:173], v[166:169], v[44:47]
	v_mfma_f32_16x16x32_bf16 v[48:51], v[174:177], v[162:165], v[48:51]
	v_mfma_f32_16x16x32_bf16 v[32:35], v[174:177], v[166:169], v[32:35]
	s_waitcnt vmcnt(0)
	s_waitcnt vmcnt(0) lgkmcnt(0)
	v_mfma_f32_16x16x32_bf16 v[24:27], v[154:157], v[242:245], v[24:27]
	s_barrier
	v_mfma_f32_16x16x32_bf16 v[4:7], v[154:157], v[246:249], v[4:7]
	v_mfma_f32_16x16x32_bf16 v[20:23], v[158:161], v[242:245], v[20:23]
	v_mfma_f32_16x16x32_bf16 v[0:3], v[158:161], v[246:249], v[0:3]
	v_mfma_f32_16x16x32_bf16 v[28:31], v[170:173], v[242:245], v[28:31]
	v_mfma_f32_16x16x32_bf16 v[8:11], v[170:173], v[246:249], v[8:11]
	v_mfma_f32_16x16x32_bf16 v[16:19], v[174:177], v[242:245], v[16:19]
	v_mfma_f32_16x16x32_bf16 v[12:15], v[174:177], v[246:249], v[12:15]
	s_cbranch_scc0 .LBB0_132
.LBB0_128:
	s_and_b32 s20, s3, 1
	s_lshl_b32 s10, s20, 16
	s_branch .LBB0_127

.LBB0_389:
	v_readfirstlane_b32 s6, v150
	s_xor_b32 m0, s74, 1
	s_lshl_b32 m0, m0, 16
	s_add_i32 s6, s6, m0
	v_add3_u32 v168, s67, v151, v152
	v_add3_u32 v185, s67, v153, v152
	v_add_u32_e32 v170, v168, v154
	v_add_u32_e32 v186, v185, v154
	ds_read_b128 v[128:131], v170 offset:32768
	ds_read_b128 v[160:163], v170 offset:34816
	ds_read_b128 v[164:167], v170 offset:36864
	ds_read_b128 v[170:173], v170 offset:38912
	ds_read_b128 v[156:159], v186
	ds_read_b128 v[250:253], v186 offset:2048
	ds_read_b128 v[242:245], v186 offset:4096
	ds_read_b128 v[246:249], v186 offset:6144
	s_mov_b32 m0, s6
	v_lshl_add_u64 v[254:255], v[132:133], 0, s[2:3]
	global_load_lds_dwordx4 v[254:255], off
	s_add_i32 m0, s6, 0x2000
	v_lshl_add_u64 v[254:255], v[134:135], 0, s[2:3]
	global_load_lds_dwordx4 v[254:255], off
	s_waitcnt lgkmcnt(2)
	v_mfma_f32_16x16x32_bf16 v[124:127], v[128:131], v[156:159], v[124:127]
	v_add_u32_e32 v241, v168, v155
	v_add_u32_e32 v168, v185, v155
	v_mfma_f32_16x16x32_bf16 v[108:111], v[128:131], v[250:253], v[108:111]
	v_mfma_f32_16x16x32_bf16 v[120:123], v[160:163], v[156:159], v[120:123]
	v_mfma_f32_16x16x32_bf16 v[104:107], v[160:163], v[250:253], v[104:107]
	s_add_i32 m0, s6, 0x4000
	v_lshl_add_u64 v[254:255], v[136:137], 0, s[2:3]
	global_load_lds_dwordx4 v[254:255], off
	v_mfma_f32_16x16x32_bf16 v[116:119], v[164:167], v[156:159], v[116:119]
	v_mfma_f32_16x16x32_bf16 v[100:103], v[164:167], v[250:253], v[100:103]
	v_mfma_f32_16x16x32_bf16 v[112:115], v[170:173], v[156:159], v[112:115]
	v_mfma_f32_16x16x32_bf16 v[96:99], v[170:173], v[250:253], v[96:99]
	s_add_i32 m0, s6, 0x6000
	v_lshl_add_u64 v[254:255], v[138:139], 0, s[2:3]
	global_load_lds_dwordx4 v[254:255], off
	ds_read_b128 v[156:159], v186 offset:8192
	ds_read_b128 v[250:253], v186 offset:10240
	s_waitcnt lgkmcnt(2)
	v_mfma_f32_16x16x32_bf16 v[92:95], v[128:131], v[242:245], v[92:95]
	v_mfma_f32_16x16x32_bf16 v[76:79], v[128:131], v[246:249], v[76:79]
	v_mfma_f32_16x16x32_bf16 v[88:91], v[160:163], v[242:245], v[88:91]
	v_mfma_f32_16x16x32_bf16 v[72:75], v[160:163], v[246:249], v[72:75]
	s_add_i32 m0, s6, 0x8000
	v_lshl_add_u64 v[254:255], v[140:141], 0, s[2:3]
	global_load_lds_dwordx4 v[254:255], off
	v_mfma_f32_16x16x32_bf16 v[84:87], v[164:167], v[242:245], v[84:87]
	v_mfma_f32_16x16x32_bf16 v[68:71], v[164:167], v[246:249], v[68:71]
	v_mfma_f32_16x16x32_bf16 v[80:83], v[170:173], v[242:245], v[80:83]
	v_mfma_f32_16x16x32_bf16 v[64:67], v[170:173], v[246:249], v[64:67]
	s_add_i32 m0, s6, 0xa000
	v_lshl_add_u64 v[254:255], v[142:143], 0, s[2:3]
	global_load_lds_dwordx4 v[254:255], off
	ds_read_b128 v[242:245], v186 offset:12288
	ds_read_b128 v[246:249], v186 offset:14336
	s_waitcnt lgkmcnt(2)
	v_mfma_f32_16x16x32_bf16 v[60:63], v[128:131], v[156:159], v[60:63]
	v_mfma_f32_16x16x32_bf16 v[44:47], v[128:131], v[250:253], v[44:47]
	v_mfma_f32_16x16x32_bf16 v[56:59], v[160:163], v[156:159], v[56:59]
	v_mfma_f32_16x16x32_bf16 v[40:43], v[160:163], v[250:253], v[40:43]
	s_add_i32 m0, s6, 0xc000
	v_lshl_add_u64 v[254:255], v[144:145], 0, s[2:3]
	global_load_lds_dwordx4 v[254:255], off
	v_mfma_f32_16x16x32_bf16 v[52:55], v[164:167], v[156:159], v[52:55]
	v_mfma_f32_16x16x32_bf16 v[36:39], v[164:167], v[250:253], v[36:39]
	v_mfma_f32_16x16x32_bf16 v[48:51], v[170:173], v[156:159], v[48:51]
	v_mfma_f32_16x16x32_bf16 v[32:35], v[170:173], v[250:253], v[32:35]
	s_add_i32 m0, s6, 0xe000
	v_lshl_add_u64 v[254:255], v[146:147], 0, s[2:3]
	global_load_lds_dwordx4 v[254:255], off
	s_add_u32 s2, s2, 0x80
	s_addc_u32 s3, s3, 0
	s_add_i32 s66, s66, 1
	s_cmpk_lg_i32 s2, 0x200
	ds_read_b128 v[156:159], v168
	ds_read_b128 v[250:253], v168 offset:2048
	s_waitcnt lgkmcnt(2)
	v_mfma_f32_16x16x32_bf16 v[28:31], v[128:131], v[242:245], v[28:31]
	v_mfma_f32_16x16x32_bf16 v[12:15], v[128:131], v[246:249], v[12:15]
	ds_read_b128 v[128:131], v241 offset:32768
	v_mfma_f32_16x16x32_bf16 v[24:27], v[160:163], v[242:245], v[24:27]
	v_mfma_f32_16x16x32_bf16 v[8:11], v[160:163], v[246:249], v[8:11]
	ds_read_b128 v[160:163], v241 offset:34816
	v_mfma_f32_16x16x32_bf16 v[20:23], v[164:167], v[242:245], v[20:23]
	v_mfma_f32_16x16x32_bf16 v[0:3], v[164:167], v[246:249], v[0:3]
	ds_read_b128 v[164:167], v241 offset:36864
	v_mfma_f32_16x16x32_bf16 v[16:19], v[170:173], v[242:245], v[16:19]
	v_mfma_f32_16x16x32_bf16 v[4:7], v[170:173], v[246:249], v[4:7]
	ds_read_b128 v[170:173], v241 offset:38912
	ds_read_b128 v[242:245], v168 offset:4096
	ds_read_b128 v[246:249], v168 offset:6144
	s_waitcnt lgkmcnt(2)
	v_mfma_f32_16x16x32_bf16 v[124:127], v[128:131], v[156:159], v[124:127]
	v_mfma_f32_16x16x32_bf16 v[108:111], v[128:131], v[250:253], v[108:111]
	v_mfma_f32_16x16x32_bf16 v[120:123], v[160:163], v[156:159], v[120:123]
	v_mfma_f32_16x16x32_bf16 v[104:107], v[160:163], v[250:253], v[104:107]
	v_mfma_f32_16x16x32_bf16 v[116:119], v[164:167], v[156:159], v[116:119]
	v_mfma_f32_16x16x32_bf16 v[100:103], v[164:167], v[250:253], v[100:103]
	v_mfma_f32_16x16x32_bf16 v[112:115], v[170:173], v[156:159], v[112:115]
	v_mfma_f32_16x16x32_bf16 v[96:99], v[170:173], v[250:253], v[96:99]
	ds_read_b128 v[156:159], v168 offset:8192
	ds_read_b128 v[250:253], v168 offset:10240
	s_waitcnt lgkmcnt(2)
	v_mfma_f32_16x16x32_bf16 v[92:95], v[128:131], v[242:245], v[92:95]
	v_mfma_f32_16x16x32_bf16 v[76:79], v[128:131], v[246:249], v[76:79]
	v_mfma_f32_16x16x32_bf16 v[88:91], v[160:163], v[242:245], v[88:91]
	v_mfma_f32_16x16x32_bf16 v[72:75], v[160:163], v[246:249], v[72:75]
	v_mfma_f32_16x16x32_bf16 v[84:87], v[164:167], v[242:245], v[84:87]
	v_mfma_f32_16x16x32_bf16 v[68:71], v[164:167], v[246:249], v[68:71]
	v_mfma_f32_16x16x32_bf16 v[80:83], v[170:173], v[242:245], v[80:83]
	v_mfma_f32_16x16x32_bf16 v[64:67], v[170:173], v[246:249], v[64:67]
	ds_read_b128 v[242:245], v168 offset:12288
	ds_read_b128 v[246:249], v168 offset:14336
	s_waitcnt lgkmcnt(2)
	v_mfma_f32_16x16x32_bf16 v[60:63], v[128:131], v[156:159], v[60:63]
	v_mfma_f32_16x16x32_bf16 v[44:47], v[128:131], v[250:253], v[44:47]
	v_mfma_f32_16x16x32_bf16 v[56:59], v[160:163], v[156:159], v[56:59]
	v_mfma_f32_16x16x32_bf16 v[40:43], v[160:163], v[250:253], v[40:43]
	v_mfma_f32_16x16x32_bf16 v[52:55], v[164:167], v[156:159], v[52:55]
	v_mfma_f32_16x16x32_bf16 v[36:39], v[164:167], v[250:253], v[36:39]
	v_mfma_f32_16x16x32_bf16 v[48:51], v[170:173], v[156:159], v[48:51]
	v_mfma_f32_16x16x32_bf16 v[32:35], v[170:173], v[250:253], v[32:35]
	s_waitcnt vmcnt(0)
	s_waitcnt vmcnt(0) lgkmcnt(0)
	v_mfma_f32_16x16x32_bf16 v[28:31], v[128:131], v[242:245], v[28:31]
	s_barrier
	v_mfma_f32_16x16x32_bf16 v[12:15], v[128:131], v[246:249], v[12:15]
	v_mfma_f32_16x16x32_bf16 v[24:27], v[160:163], v[242:245], v[24:27]
	v_mfma_f32_16x16x32_bf16 v[8:11], v[160:163], v[246:249], v[8:11]
	v_mfma_f32_16x16x32_bf16 v[20:23], v[164:167], v[242:245], v[20:23]
	v_mfma_f32_16x16x32_bf16 v[0:3], v[164:167], v[246:249], v[0:3]
	v_mfma_f32_16x16x32_bf16 v[16:19], v[170:173], v[242:245], v[16:19]
	v_mfma_f32_16x16x32_bf16 v[4:7], v[170:173], v[246:249], v[4:7]
	s_cbranch_scc0 .LBB0_394
.LBB0_390:
	s_and_b32 s74, s66, 1
	s_lshl_b32 s67, s74, 16
	s_branch .LBB0_389

.LBB0_618:
	v_cmp_lt_i32_e32 vcc, 7, v0
	s_and_saveexec_b64 s[2:3], vcc
	s_xor_b64 s[64:65], exec, s[2:3]
	s_cbranch_execz .LBB0_675
	v_cmp_lt_u32_e32 vcc, 15, v0
	s_and_saveexec_b64 s[2:3], vcc
	s_xor_b64 s[8:9], exec, s[2:3]
	s_cbranch_execz .LBB0_655
	v_add_u32_e32 v2, -16, v0
	v_lshrrev_b32_e32 v2, 1, v2
	v_sub_u32_e32 v14, 31, v2
	v_mov_b32_e32 v18, v198
	v_lshlrev_b32_e32 v15, 8, v14
	v_readlane_b32 s4, v240, 36
	v_and_b32_e32 v12, 31, v18
	v_ashrrev_i32_e32 v2, 1, v18
	v_and_b32_e32 v19, 1, v0
	v_readlane_b32 s2, v240, 21
	v_and_b32_e32 v16, 0xffffffe0, v2
	v_or3_b32 v2, s4, v15, v12
	v_bitop3_b32 v4, v19, 7, s2 bitop3:0xc8
	v_add_u32_e32 v5, v2, v16
	v_mov_b64_e32 v[2:3], s[72:73]
	v_bfe_u32 v13, v18, 5, 1
	v_mad_i64_i32 v[156:157], s[2:3], v5, s77, v[2:3]
	v_lshlrev_b32_e32 v2, 7, v4
	v_mov_b32_e32 v3, v1
	v_lshl_add_u64 v[2:3], v[156:157], 0, v[2:3]
	v_lshlrev_b32_e32 v158, 4, v13
	v_mov_b32_e32 v159, v1
	v_lshl_add_u64 v[2:3], v[2:3], 0, v[158:159]
	s_mov_b64 s[2:3], 0x1000
	v_lshlrev_b32_e32 v0, 6, v4
	v_lshl_add_u64 v[4:5], v[2:3], 0, s[2:3]
	v_add_co_u32_e32 v2, vcc, s78, v2
	s_mov_b64 s[2:3], 0x1400
	s_nop 0
	v_addc_co_u32_e32 v3, vcc, 0, v3, vcc
	global_load_dwordx4 v[112:115], v[4:5], off offset:32
	global_load_dwordx4 v[116:119], v[4:5], off offset:64
	global_load_dwordx4 v[120:123], v[2:3], off
	global_load_dwordx4 v[124:127], v[4:5], off offset:96
	v_lshl_add_u64 v[2:3], v[156:157], 0, v[0:1]
	v_lshl_add_u64 v[2:3], v[2:3], 0, v[158:159]
	v_lshl_add_u64 v[4:5], v[2:3], 0, s[2:3]
	v_add_co_u32_e32 v2, vcc, s78, v2
	s_nop 1
	v_addc_co_u32_e32 v3, vcc, 0, v3, vcc
	global_load_dwordx4 v[128:131], v[2:3], off offset:1024
	global_load_dwordx4 v[132:135], v[4:5], off offset:32
	v_mul_hi_i32 v2, v18, s50
	v_lshrrev_b32_e32 v3, 31, v2
	v_ashrrev_i32_e32 v2, 1, v2
	v_add_u32_e32 v17, v2, v3
	v_mul_lo_u32 v2, v17, 12
	v_sub_u32_e32 v2, v18, v2
	v_add_u32_e32 v160, s4, v17
	v_cmp_lt_i32_e64 s[2:3], 7, v2
	v_ashrrev_i32_e32 v161, 31, v160
	v_lshlrev_b32_e32 v162, 4, v2
	s_and_saveexec_b64 s[4:5], s[2:3]
	s_xor_b64 s[4:5], exec, s[4:5]
	v_mov_b64_e32 v[4:5], s[72:73]
	v_mad_i64_i32 v[4:5], s[6:7], v160, s77, v[4:5]
	v_mov_b32_e32 v163, v1
	v_lshl_add_u64 v[4:5], v[4:5], 0, v[162:163]
	v_lshl_add_u64 v[4:5], v[4:5], 0, s[74:75]
	s_or_saveexec_b64 s[4:5], s[4:5]
	v_lshlrev_b32_e32 v2, 3, v2
	v_lshlrev_b32_e32 v164, 1, v0
	v_ashrrev_i32_e32 v20, 31, v2
	s_xor_b64 exec, exec, s[4:5]
	v_lshlrev_b64 v[4:5], 10, v[160:161]
	v_lshl_add_u64 v[4:5], s[80:81], 0, v[4:5]
	v_mov_b32_e32 v165, v1
	v_lshl_add_u64 v[4:5], v[4:5], 0, v[164:165]
	v_mov_b32_e32 v3, v20
	v_lshl_add_u64 v[4:5], v[2:3], 1, v[4:5]
	s_or_b64 exec, exec, s[4:5]
	global_load_dwordx4 v[136:139], v[4:5], off
	v_add_u32_e32 v3, 0x200, v18
	v_mul_hi_i32 v0, v3, s50
	v_lshrrev_b32_e32 v4, 31, v0
	v_ashrrev_i32_e32 v0, 1, v0
	v_add_u32_e32 v21, v0, v4
	v_mul_lo_u32 v0, v21, 12
	v_readlane_b32 s4, v240, 36
	v_sub_u32_e32 v0, v3, v0
	v_lshlrev_b32_e32 v168, 4, v0
	v_add_u32_e32 v166, s4, v21
	v_cmp_lt_i32_e64 s[4:5], 7, v0
	v_ashrrev_i32_e32 v167, 31, v166
	s_and_saveexec_b64 s[6:7], s[4:5]
	s_xor_b64 s[6:7], exec, s[6:7]
	v_mov_b64_e32 v[4:5], s[72:73]
	v_mad_i64_i32 v[4:5], s[10:11], v166, s77, v[4:5]
	v_mov_b32_e32 v169, v1
	v_lshl_add_u64 v[4:5], v[4:5], 0, v[168:169]
	v_lshl_add_u64 v[6:7], v[4:5], 0, s[74:75]
	s_or_saveexec_b64 s[6:7], s[6:7]
	v_lshlrev_b32_e32 v4, 3, v0
	v_ashrrev_i32_e32 v22, 31, v4
	s_xor_b64 exec, exec, s[6:7]
	v_lshlrev_b64 v[6:7], 10, v[166:167]
	v_lshl_add_u64 v[6:7], s[80:81], 0, v[6:7]
	v_mov_b32_e32 v165, v1
	v_lshl_add_u64 v[6:7], v[6:7], 0, v[164:165]
	v_mov_b32_e32 v5, v22
	v_lshl_add_u64 v[6:7], v[4:5], 1, v[6:7]
	s_or_b64 exec, exec, s[6:7]
	global_load_dwordx4 v[140:143], v[6:7], off
	v_add_u32_e32 v0, 0x400, v18
	v_mul_hi_i32 v5, v0, s50
	v_lshrrev_b32_e32 v6, 31, v5
	v_ashrrev_i32_e32 v5, 1, v5
	v_add_u32_e32 v23, v5, v6
	v_mul_lo_u32 v5, v23, 12
	v_readlane_b32 s6, v240, 36
	v_sub_u32_e32 v5, v0, v5
	v_lshlrev_b32_e32 v0, 3, v5
	v_add_u32_e32 v170, s6, v23
	v_cmp_lt_i32_e64 s[6:7], 7, v5
	v_ashrrev_i32_e32 v171, 31, v170
	v_lshlrev_b32_e32 v172, 4, v5
	s_and_saveexec_b64 s[10:11], s[6:7]
	s_xor_b64 s[10:11], exec, s[10:11]
	v_mov_b64_e32 v[6:7], s[72:73]
	v_mad_i64_i32 v[6:7], s[12:13], v170, s77, v[6:7]
	v_mov_b32_e32 v173, v1
	v_lshl_add_u64 v[6:7], v[6:7], 0, v[172:173]
	v_lshl_add_u64 v[10:11], v[6:7], 0, s[74:75]
	v_mov_b64_e32 v[6:7], v[0:1]
	s_or_saveexec_b64 s[10:11], s[10:11]
	v_mov_b64_e32 v[8:9], v[6:7]
	s_xor_b64 exec, exec, s[10:11]
	v_lshlrev_b64 v[6:7], 10, v[170:171]
	v_lshl_add_u64 v[6:7], s[80:81], 0, v[6:7]
	v_mov_b32_e32 v165, v1
	v_lshl_add_u64 v[8:9], v[6:7], 0, v[164:165]
	v_ashrrev_i32_e32 v7, 31, v0
	v_mov_b32_e32 v6, v0
	v_lshl_add_u64 v[10:11], v[6:7], 1, v[8:9]
	v_mov_b64_e32 v[8:9], v[0:1]
	s_or_b64 exec, exec, s[10:11]
	v_readlane_b32 s10, v240, 21
	global_load_dwordx4 v[144:147], v[10:11], off
	v_ashrrev_i32_e32 v10, 4, v18
	v_or_b32_e32 v0, s10, v19
	v_readlane_b32 s10, v240, 41
	v_lshlrev_b32_e32 v0, 20, v0
	v_readlane_b32 s11, v240, 42
	v_ashrrev_i32_e32 v11, 31, v10
	v_lshlrev_b64 v[26:27], 14, v[10:11]
	v_lshl_add_u64 v[24:25], s[10:11], 0, v[0:1]
	v_lshlrev_b32_e32 v0, 3, v18
	v_and_b32_e32 v161, 0x78, v0
	v_ashrrev_i32_e32 v18, 4, v3
	v_lshl_add_u64 v[26:27], v[24:25], 0, v[26:27]
	v_lshlrev_b32_e32 v0, 1, v161
	v_and_b32_e32 v238, 8, v161
	v_lshrrev_b32_e32 v238, 1, v238
	v_and_b32_e32 v161, 0x70, v161
	v_or_b32_e32 v161, v161, v238
	v_ashrrev_i32_e32 v19, 31, v18
	v_lshl_add_u64 v[174:175], v[26:27], 0, v[0:1]
	v_lshlrev_b64 v[26:27], 14, v[18:19]
	v_lshl_add_u64 v[24:25], v[24:25], 0, v[26:27]
	v_lshl_add_u64 v[176:177], v[24:25], 0, v[0:1]
	global_load_dwordx4 v[148:151], v[174:175], off
	global_load_dwordx4 v[152:155], v[176:177], off
	v_add_u32_e32 v0, v16, v15
	v_and_b32_e32 v3, 64, v202
	v_or_b32_e32 v171, v0, v12
	v_xor_b32_e32 v0, 32, v202
	v_add_u32_e32 v3, 64, v3
	v_cmp_lt_i32_e32 vcc, v0, v3
	v_mov_b32_e32 v3, v1
	v_mov_b32_e32 v165, v1
	v_mov_b32_e32 v5, v1
	v_lshlrev_b32_e32 v167, 1, v14
	v_lshl_add_u64 v[178:179], v[2:3], 1, s[72:73]
	v_lshl_add_u64 v[14:15], s[80:81], 0, v[164:165]
	v_mov_b32_e32 v3, v20
	v_lshl_add_u64 v[182:183], v[4:5], 1, s[72:73]
	v_mov_b32_e32 v5, v22
	v_cndmask_b32_e32 v0, v202, v0, vcc
	v_lshl_add_u64 v[180:181], v[2:3], 1, v[14:15]
	v_lshl_add_u64 v[184:185], v[4:5], 1, v[14:15]
	v_lshl_add_u64 v[188:189], v[6:7], 1, v[14:15]
	s_movk_i32 s10, 0x110
	v_mov_b32_e32 v14, v1
	v_mov_b32_e32 v15, v1
	v_lshlrev_b32_e32 v163, 3, v13
	v_lshlrev_b32_e32 v173, 2, v0
	v_lshl_add_u64 v[186:187], v[8:9], 1, s[72:73]
	v_lshlrev_b32_e32 v159, 2, v13
	v_mul_lo_u32 v165, v17, s51
	v_mul_lo_u32 v209, v21, s51
	v_mul_lo_u32 v210, v23, s51
	v_mul_lo_u32 v211, v10, s10
	v_mul_lo_u32 v212, v18, s10
	v_add_u32_e32 v211, 0xd000, v211
	v_add_u32_e32 v212, 0xd000, v212
	v_mul_u32_u24_e32 v213, 0xd0, v12
	v_mul_u32_u24_e32 v214, 0x110, v12
	v_mov_b32_e32 v0, v1
	v_mov_b32_e32 v2, v1
	v_mov_b32_e32 v3, v1
	v_mov_b32_e32 v4, v1
	v_mov_b32_e32 v5, v1
	v_mov_b32_e32 v6, v1
	v_mov_b32_e32 v7, v1
	v_mov_b32_e32 v8, v1
	v_mov_b32_e32 v9, v1
	v_mov_b32_e32 v10, v1
	v_mov_b32_e32 v11, v1
	v_mov_b32_e32 v12, v1
	v_mov_b32_e32 v13, v1
	v_mov_b64_e32 v[30:31], v[14:15]
	v_mov_b64_e32 v[46:47], v[14:15]
	v_add_u32_e32 v169, 2, v167
	s_mov_b32 s18, 0
	v_mov_b32_e32 v215, 0
	s_movk_i32 s52, 0x80
	s_mov_b64 s[10:11], 0
	v_mov_b64_e32 v[28:29], v[12:13]
	v_mov_b64_e32 v[26:27], v[10:11]
	v_mov_b64_e32 v[24:25], v[8:9]
	v_mov_b64_e32 v[22:23], v[6:7]
	v_mov_b64_e32 v[20:21], v[4:5]
	v_mov_b64_e32 v[18:19], v[2:3]
	v_mov_b64_e32 v[16:17], v[0:1]
	v_mov_b64_e32 v[44:45], v[12:13]
	v_mov_b64_e32 v[42:43], v[10:11]
	v_mov_b64_e32 v[40:41], v[8:9]
	v_mov_b64_e32 v[38:39], v[6:7]
	v_mov_b64_e32 v[36:37], v[4:5]
	v_mov_b64_e32 v[34:35], v[2:3]
	v_mov_b64_e32 v[32:33], v[0:1]
	v_mov_b32_e32 v0, 0
	s_branch .LBB0_634
.LBB0_633:
.LBB0_634:
	v_lshrrev_b32_e32 v2, 8, v198
	v_readfirstlane_b32 s99, v169
	v_readfirstlane_b32 s98, v2
	s_mov_b32 s101, 0
	s_mov_b32 s12, 0
	s_nop 1
	s_and_b32 s98, s98, 1
	s_mul_i32 s13, s12, 0x6800
	s_mul_i32 s12, s12, 0x4400
	v_add3_u32 v2, s13, v165, v162
	s_waitcnt vmcnt(4)
	ds_write_b128 v2, v[136:139]
	v_add3_u32 v2, s13, v209, v168
	s_waitcnt vmcnt(3)
	ds_write_b128 v2, v[140:143]
	v_add3_u32 v2, s13, v210, v172
	s_waitcnt vmcnt(2)
	ds_write_b128 v2, v[144:147]
	v_lshl_add_u32 v2, v161, 1, s12
	v_add_u32_e32 v3, v2, v211
	v_add_u32_e32 v2, v2, v212
	s_waitcnt vmcnt(1)
	ds_write2_b64 v3, v[148:149], v[150:151] offset1:2
	s_waitcnt vmcnt(0)
	ds_write2_b64 v2, v[152:153], v[154:155] offset1:2
.Lat0_loop:
	s_and_b32 s12, s18, 1
	s_mul_i32 s19, s12, 0x6800
	s_add_i32 s16, s18, 1
	v_cmp_lt_u32_e32 vcc, s16, v169
	s_waitcnt lgkmcnt(0)
	s_barrier
	s_and_saveexec_b64 s[12:13], vcc
	s_cbranch_execz .LBB0_648
	v_add_u32_e32 v4, s52, v160
	v_ashrrev_i32_e32 v5, 31, v4
	s_and_saveexec_b64 s[14:15], s[2:3]
	s_xor_b64 s[14:15], exec, s[14:15]
	v_mad_i64_i32 v[2:3], s[20:21], v4, s77, v[178:179]
	v_lshl_add_u64 v[2:3], v[2:3], 0, s[74:75]
	s_andn2_saveexec_b64 s[14:15], s[14:15]
	v_lshlrev_b64 v[2:3], 10, v[4:5]
	v_lshl_add_u64 v[2:3], v[180:181], 0, v[2:3]
	s_or_b64 exec, exec, s[14:15]
	global_load_dwordx4 v[136:139], v[2:3], off
	v_add_u32_e32 v4, s52, v166
	v_ashrrev_i32_e32 v5, 31, v4
	s_and_saveexec_b64 s[14:15], s[4:5]
	s_xor_b64 s[14:15], exec, s[14:15]
	v_mad_i64_i32 v[2:3], s[20:21], v4, s77, v[182:183]
	v_lshl_add_u64 v[2:3], v[2:3], 0, s[74:75]
	s_andn2_saveexec_b64 s[14:15], s[14:15]
	v_lshlrev_b64 v[2:3], 10, v[4:5]
	v_lshl_add_u64 v[2:3], v[184:185], 0, v[2:3]
	s_or_b64 exec, exec, s[14:15]
	global_load_dwordx4 v[140:143], v[2:3], off
	v_add_u32_e32 v4, s52, v170
	v_ashrrev_i32_e32 v5, 31, v4
	s_and_saveexec_b64 s[14:15], s[6:7]
	s_xor_b64 s[14:15], exec, s[14:15]
	v_mad_i64_i32 v[2:3], s[20:21], v4, s77, v[186:187]
	v_lshl_add_u64 v[2:3], v[2:3], 0, s[74:75]
	s_andn2_saveexec_b64 s[14:15], s[14:15]
	v_lshlrev_b64 v[2:3], 10, v[4:5]
	v_lshl_add_u64 v[2:3], v[188:189], 0, v[2:3]
	s_or_b64 exec, exec, s[14:15]
	s_lshl_b64 s[14:15], s[52:53], 1
	global_load_dwordx4 v[144:147], v[2:3], off
	v_lshl_add_u64 v[2:3], v[174:175], 0, s[14:15]
	v_lshl_add_u64 v[4:5], v[176:177], 0, s[14:15]
	global_load_dwordx4 v[148:151], v[2:3], off
	global_load_dwordx4 v[152:155], v[4:5], off
.LBB0_648:
	s_or_b64 exec, exec, s[12:13]
	s_cmp_eq_u32 s98, 0
	s_cbranch_scc1 .Lat0_qk
	s_cmp_eq_u32 s18, 0
	s_cbranch_scc1 .Lat0_qk
	s_branch .Lat0_pv
.Lat0_qk:
	s_add_i32 s12, s18, 2
	s_cmp_ge_u32 s12, s99
	s_cbranch_scc1 .Lat0_qkm
	v_add3_u32 v10, s19, v158, v213
	v_xor_b32_e32 v48, 0x80000000, v0
	v_mov_b32_e32 v49, v48
	v_mov_b32_e32 v50, v48
	v_mov_b32_e32 v51, v48
	v_mov_b32_e32 v52, v48
	v_mov_b32_e32 v53, v48
	v_mov_b32_e32 v54, v48
	v_mov_b32_e32 v55, v48
	v_mov_b32_e32 v56, v48
	v_mov_b32_e32 v57, v48
	v_mov_b32_e32 v58, v48
	v_mov_b32_e32 v59, v48
	v_mov_b32_e32 v60, v48
	v_mov_b32_e32 v61, v48
	v_mov_b32_e32 v62, v48
	v_mov_b32_e32 v63, v48
	ds_read_b128 v[6:9], v10
	ds_read_b128 v[222:225], v10 offset:32
	ds_read_b128 v[226:229], v10 offset:64
	ds_read_b128 v[230:233], v10 offset:96
	ds_read_b128 v[234:237], v10 offset:128
	ds_read_b128 v[242:245], v10 offset:160
	ds_read_b128 v[246:249], v10 offset:6656
	ds_read_b128 v[250:253], v10 offset:6688
	s_waitcnt lgkmcnt(7)
	v_mfma_f32_32x32x16_bf16 v[80:95], v[6:9], v[120:123], v[48:63]
	ds_read_b128 v[6:9], v10 offset:6720
	s_waitcnt lgkmcnt(7)
	v_mfma_f32_32x32x16_bf16 v[80:95], v[222:225], v[112:115], v[80:95]
	ds_read_b128 v[222:225], v10 offset:6752
	s_waitcnt lgkmcnt(7)
	v_mfma_f32_32x32x16_bf16 v[80:95], v[226:229], v[116:119], v[80:95]
	ds_read_b128 v[226:229], v10 offset:6784
	s_waitcnt lgkmcnt(7)
	v_mfma_f32_32x32x16_bf16 v[80:95], v[230:233], v[124:127], v[80:95]
	ds_read_b128 v[230:233], v10 offset:6816
	s_waitcnt lgkmcnt(7)
	v_mfma_f32_32x32x16_bf16 v[80:95], v[234:237], v[128:131], v[80:95]
	ds_read_b128 v[234:237], v10 offset:13312
	s_waitcnt lgkmcnt(7)
	v_mfma_f32_32x32x16_bf16 v[80:95], v[242:245], v[132:135], v[80:95]
	ds_read_b128 v[242:245], v10 offset:13344
	s_waitcnt lgkmcnt(7)
	v_mfma_f32_32x32x16_bf16 v[64:79], v[246:249], v[120:123], v[48:63]
	ds_read_b128 v[246:249], v10 offset:13376
	s_waitcnt lgkmcnt(7)
	v_mfma_f32_32x32x16_bf16 v[64:79], v[250:253], v[112:115], v[64:79]
	ds_read_b128 v[250:253], v10 offset:13408
	s_waitcnt lgkmcnt(7)
	v_mfma_f32_32x32x16_bf16 v[64:79], v[6:9], v[116:119], v[64:79]
	ds_read_b128 v[6:9], v10 offset:13440
	s_waitcnt lgkmcnt(7)
	v_mfma_f32_32x32x16_bf16 v[64:79], v[222:225], v[124:127], v[64:79]
	ds_read_b128 v[222:225], v10 offset:13472
	s_waitcnt lgkmcnt(7)
	v_mfma_f32_32x32x16_bf16 v[64:79], v[226:229], v[128:131], v[64:79]
	ds_read_b128 v[226:229], v10 offset:19968
	v_max3_f32 v11, v80, v81, v82
	v_max3_f32 v11, v11, v83, v84
	v_max3_f32 v11, v11, v85, v86
	v_max3_f32 v11, v11, v87, v88
	v_max3_f32 v11, v11, v89, v90
	v_max3_f32 v11, v11, v91, v92
	s_waitcnt lgkmcnt(7)
	v_mfma_f32_32x32x16_bf16 v[64:79], v[230:233], v[132:135], v[64:79]
	ds_read_b128 v[230:233], v10 offset:20000
	v_max3_f32 v11, v11, v93, v94
	v_max_f32_e32 v11, v11, v95
	v_exp_f32_e32 v80, v80
	v_exp_f32_e32 v81, v81
	v_exp_f32_e32 v82, v82
	v_exp_f32_e32 v83, v83
	s_waitcnt lgkmcnt(7)
	v_mfma_f32_32x32x16_bf16 v[96:111], v[234:237], v[120:123], v[48:63]
	ds_read_b128 v[234:237], v10 offset:20032
	v_mov_b32_e32 v12, v80
	v_mov_b32_e32 v13, v81
	v_mov_b32_e32 v14, v82
	v_mov_b32_e32 v15, v83
	v_exp_f32_e32 v84, v84
	v_exp_f32_e32 v85, v85
	s_waitcnt lgkmcnt(7)
	v_mfma_f32_32x32x16_bf16 v[96:111], v[242:245], v[112:115], v[96:111]
	ds_read_b128 v[242:245], v10 offset:20064
	v_exp_f32_e32 v86, v86
	v_exp_f32_e32 v87, v87
	v_add_f32_e32 v12, v12, v84
	v_add_f32_e32 v13, v13, v85
	v_add_f32_e32 v14, v14, v86
	v_add_f32_e32 v15, v15, v87
	s_waitcnt lgkmcnt(7)
	v_mfma_f32_32x32x16_bf16 v[96:111], v[246:249], v[116:119], v[96:111]
	ds_read_b128 v[246:249], v10 offset:20096
	v_cvt_pk_bf16_f32 v80, v80, v81
	v_cvt_pk_bf16_f32 v81, v82, v83
	v_cvt_pk_bf16_f32 v82, v84, v85
	v_cvt_pk_bf16_f32 v83, v86, v87
	v_exp_f32_e32 v88, v88
	v_exp_f32_e32 v89, v89
	s_waitcnt lgkmcnt(7)
	v_mfma_f32_32x32x16_bf16 v[96:111], v[250:253], v[124:127], v[96:111]
	ds_read_b128 v[250:253], v10 offset:20128
	v_exp_f32_e32 v90, v90
	v_exp_f32_e32 v91, v91
	v_add_f32_e32 v12, v12, v88
	v_add_f32_e32 v13, v13, v89
	v_add_f32_e32 v14, v14, v90
	v_add_f32_e32 v15, v15, v91
	s_waitcnt lgkmcnt(7)
	v_mfma_f32_32x32x16_bf16 v[96:111], v[6:9], v[128:131], v[96:111]
	v_exp_f32_e32 v92, v92
	v_exp_f32_e32 v93, v93
	v_exp_f32_e32 v94, v94
	v_exp_f32_e32 v95, v95
	v_add_f32_e32 v12, v12, v92
	v_add_f32_e32 v13, v13, v93
	s_waitcnt lgkmcnt(6)
	v_mfma_f32_32x32x16_bf16 v[96:111], v[222:225], v[132:135], v[96:111]
	v_add_f32_e32 v14, v14, v94
	v_add_f32_e32 v15, v15, v95
	v_cvt_pk_bf16_f32 v84, v88, v89
	v_cvt_pk_bf16_f32 v85, v90, v91
	v_cvt_pk_bf16_f32 v86, v92, v93
	v_cvt_pk_bf16_f32 v87, v94, v95
	s_waitcnt lgkmcnt(5)
	v_mfma_f32_32x32x16_bf16 v[48:63], v[226:229], v[120:123], v[48:63]
	v_max3_f32 v241, v64, v65, v66
	v_max3_f32 v241, v241, v67, v68
	v_max3_f32 v241, v241, v69, v70
	v_max3_f32 v241, v241, v71, v72
	v_max3_f32 v241, v241, v73, v74
	v_max3_f32 v241, v241, v75, v76
	s_waitcnt lgkmcnt(4)
	v_mfma_f32_32x32x16_bf16 v[48:63], v[230:233], v[112:115], v[48:63]
	v_max3_f32 v241, v241, v77, v78
	v_max_f32_e32 v241, v241, v79
	v_exp_f32_e32 v64, v64
	v_exp_f32_e32 v65, v65
	v_exp_f32_e32 v66, v66
	v_exp_f32_e32 v67, v67
	s_waitcnt lgkmcnt(3)
	v_mfma_f32_32x32x16_bf16 v[48:63], v[234:237], v[116:119], v[48:63]
	v_add_f32_e32 v12, v12, v64
	v_add_f32_e32 v13, v13, v65
	v_add_f32_e32 v14, v14, v66
	v_add_f32_e32 v15, v15, v67
	v_exp_f32_e32 v68, v68
	v_exp_f32_e32 v69, v69
	s_waitcnt lgkmcnt(2)
	v_mfma_f32_32x32x16_bf16 v[48:63], v[242:245], v[124:127], v[48:63]
	v_exp_f32_e32 v70, v70
	v_exp_f32_e32 v71, v71
	v_add_f32_e32 v12, v12, v68
	v_add_f32_e32 v13, v13, v69
	v_add_f32_e32 v14, v14, v70
	v_add_f32_e32 v15, v15, v71
	s_waitcnt lgkmcnt(1)
	v_mfma_f32_32x32x16_bf16 v[48:63], v[246:249], v[128:131], v[48:63]
	v_cvt_pk_bf16_f32 v64, v64, v65
	v_cvt_pk_bf16_f32 v65, v66, v67
	v_cvt_pk_bf16_f32 v66, v68, v69
	v_cvt_pk_bf16_f32 v67, v70, v71
	v_exp_f32_e32 v72, v72
	v_exp_f32_e32 v73, v73
	s_waitcnt lgkmcnt(0)
	v_mfma_f32_32x32x16_bf16 v[48:63], v[250:253], v[132:135], v[48:63]
	v_exp_f32_e32 v74, v74
	v_exp_f32_e32 v75, v75
	v_add_f32_e32 v12, v12, v72
	v_add_f32_e32 v13, v13, v73
	v_add_f32_e32 v14, v14, v74
	v_add_f32_e32 v15, v15, v75
	s_branch .Lat0_qkdone
.Lat0_qkm:
	v_add3_u32 v10, s19, v158, v213
	v_xor_b32_e32 v48, 0x80000000, v0
	v_mov_b32_e32 v49, v48
	v_mov_b32_e32 v50, v48
	v_mov_b32_e32 v51, v48
	v_mov_b32_e32 v52, v48
	v_mov_b32_e32 v53, v48
	v_mov_b32_e32 v54, v48
	v_mov_b32_e32 v55, v48
	v_mov_b32_e32 v56, v48
	v_mov_b32_e32 v57, v48
	v_mov_b32_e32 v58, v48
	v_mov_b32_e32 v59, v48
	v_mov_b32_e32 v60, v48
	v_mov_b32_e32 v61, v48
	v_mov_b32_e32 v62, v48
	v_mov_b32_e32 v63, v48
	ds_read_b128 v[6:9], v10
	ds_read_b128 v[222:225], v10 offset:32
	ds_read_b128 v[226:229], v10 offset:64
	ds_read_b128 v[230:233], v10 offset:96
	ds_read_b128 v[234:237], v10 offset:128
	ds_read_b128 v[242:245], v10 offset:160
	ds_read_b128 v[246:249], v10 offset:6656
	ds_read_b128 v[250:253], v10 offset:6688
	s_waitcnt lgkmcnt(7)
	v_mfma_f32_32x32x16_bf16 v[80:95], v[6:9], v[120:123], v[48:63]
	ds_read_b128 v[6:9], v10 offset:6720
	s_waitcnt lgkmcnt(7)
	v_mfma_f32_32x32x16_bf16 v[80:95], v[222:225], v[112:115], v[80:95]
	ds_read_b128 v[222:225], v10 offset:6752
	s_waitcnt lgkmcnt(7)
	v_mfma_f32_32x32x16_bf16 v[80:95], v[226:229], v[116:119], v[80:95]
	ds_read_b128 v[226:229], v10 offset:6784
	s_waitcnt lgkmcnt(7)
	v_mfma_f32_32x32x16_bf16 v[80:95], v[230:233], v[124:127], v[80:95]
	ds_read_b128 v[230:233], v10 offset:6816
	s_waitcnt lgkmcnt(7)
	v_mfma_f32_32x32x16_bf16 v[80:95], v[234:237], v[128:131], v[80:95]
	ds_read_b128 v[234:237], v10 offset:13312
	s_waitcnt lgkmcnt(7)
	v_mfma_f32_32x32x16_bf16 v[80:95], v[242:245], v[132:135], v[80:95]
	ds_read_b128 v[242:245], v10 offset:13344
	s_waitcnt lgkmcnt(7)
	v_mfma_f32_32x32x16_bf16 v[64:79], v[246:249], v[120:123], v[48:63]
	ds_read_b128 v[246:249], v10 offset:13376
	s_waitcnt lgkmcnt(7)
	v_mfma_f32_32x32x16_bf16 v[64:79], v[250:253], v[112:115], v[64:79]
	ds_read_b128 v[250:253], v10 offset:13408
	s_waitcnt lgkmcnt(7)
	v_mfma_f32_32x32x16_bf16 v[64:79], v[6:9], v[116:119], v[64:79]
	ds_read_b128 v[6:9], v10 offset:13440
	s_waitcnt lgkmcnt(7)
	v_mfma_f32_32x32x16_bf16 v[64:79], v[222:225], v[124:127], v[64:79]
	ds_read_b128 v[222:225], v10 offset:13472
	s_waitcnt lgkmcnt(7)
	v_mfma_f32_32x32x16_bf16 v[64:79], v[226:229], v[128:131], v[64:79]
	ds_read_b128 v[226:229], v10 offset:19968
	s_waitcnt lgkmcnt(7)
	v_mfma_f32_32x32x16_bf16 v[64:79], v[230:233], v[132:135], v[64:79]
	ds_read_b128 v[230:233], v10 offset:20000
	s_waitcnt lgkmcnt(7)
	v_mfma_f32_32x32x16_bf16 v[96:111], v[234:237], v[120:123], v[48:63]
	ds_read_b128 v[234:237], v10 offset:20032
	s_waitcnt lgkmcnt(7)
	v_mfma_f32_32x32x16_bf16 v[96:111], v[242:245], v[112:115], v[96:111]
	ds_read_b128 v[242:245], v10 offset:20064
	s_waitcnt lgkmcnt(7)
	v_mfma_f32_32x32x16_bf16 v[96:111], v[246:249], v[116:119], v[96:111]
	ds_read_b128 v[246:249], v10 offset:20096
	s_waitcnt lgkmcnt(7)
	v_mfma_f32_32x32x16_bf16 v[96:111], v[250:253], v[124:127], v[96:111]
	ds_read_b128 v[250:253], v10 offset:20128
	s_waitcnt lgkmcnt(7)
	v_mfma_f32_32x32x16_bf16 v[96:111], v[6:9], v[128:131], v[96:111]
	s_waitcnt lgkmcnt(6)
	v_mfma_f32_32x32x16_bf16 v[96:111], v[222:225], v[132:135], v[96:111]
	s_waitcnt lgkmcnt(5)
	v_mfma_f32_32x32x16_bf16 v[48:63], v[226:229], v[120:123], v[48:63]
	s_waitcnt lgkmcnt(4)
	v_mfma_f32_32x32x16_bf16 v[48:63], v[230:233], v[112:115], v[48:63]
	s_waitcnt lgkmcnt(3)
	v_mfma_f32_32x32x16_bf16 v[48:63], v[234:237], v[116:119], v[48:63]
	s_waitcnt lgkmcnt(2)
	v_mfma_f32_32x32x16_bf16 v[48:63], v[242:245], v[124:127], v[48:63]
	s_waitcnt lgkmcnt(1)
	v_mfma_f32_32x32x16_bf16 v[48:63], v[246:249], v[128:131], v[48:63]
	s_waitcnt lgkmcnt(0)
	v_mfma_f32_32x32x16_bf16 v[48:63], v[250:253], v[132:135], v[48:63]
.Lat0_qkdone:
	s_mov_b32 s100, s52
	s_cmp_eq_u32 s98, 1
	s_cbranch_scc1 .Lat0_endit
.Lat0_pv:
	s_sub_u32 s12, s18, s98
	s_mov_b32 s13, s101
	s_cmp_eq_u32 s98, 0
	s_cbranch_scc1 .Lat0_pvm3
	s_add_i32 s13, s13, 2
	s_cmp_ge_u32 s13, 3
	s_cbranch_scc0 .Lat0_pvm3
	s_sub_u32 s13, s13, 3
.Lat0_pvm3:
	s_mul_i32 s17, s13, 0x4400
	s_add_i32 s12, s12, 2
	s_cmp_ge_u32 s12, s99
	s_cbranch_scc1 .Lat0_pvmask
	v_add3_u32 v238, s17, v163, v214
	v_add_u32_e32 v238, v238, v163
	ds_read_b128 v[222:225], v238 offset:53248
	ds_read_b128 v[226:229], v238 offset:61952
	ds_read_b128 v[230:233], v238 offset:53280
	ds_read_b128 v[234:237], v238 offset:61984
	ds_read_b128 v[242:245], v238 offset:53312
	ds_read_b128 v[246:249], v238 offset:62016
	ds_read_b128 v[250:253], v238 offset:53344
	s_waitcnt lgkmcnt(6)
	v_mfma_f32_32x32x16_bf16 v[32:47], v[222:225], v[80:83], v[32:47]
	v_exp_f32_e32 v76, v76
	v_exp_f32_e32 v77, v77
	v_exp_f32_e32 v78, v78
	s_waitcnt lgkmcnt(5)
	v_mfma_f32_32x32x16_bf16 v[16:31], v[226:229], v[80:83], v[16:31]
	ds_read_b128 v[222:225], v238 offset:62048
	ds_read_b128 v[226:229], v238 offset:53376
	v_exp_f32_e32 v79, v79
	v_add_f32_e32 v12, v12, v76
	v_add_f32_e32 v13, v13, v77
	s_waitcnt lgkmcnt(6)
	v_mfma_f32_32x32x16_bf16 v[32:47], v[230:233], v[84:87], v[32:47]
	v_add_f32_e32 v14, v14, v78
	v_add_f32_e32 v15, v15, v79
	v_cvt_pk_bf16_f32 v68, v72, v73
	s_waitcnt lgkmcnt(5)
	v_mfma_f32_32x32x16_bf16 v[16:31], v[234:237], v[84:87], v[16:31]
	ds_read_b128 v[230:233], v238 offset:62080
	ds_read_b128 v[234:237], v238 offset:53408
	v_cvt_pk_bf16_f32 v69, v74, v75
	v_cvt_pk_bf16_f32 v70, v76, v77
	v_cvt_pk_bf16_f32 v71, v78, v79
	s_waitcnt lgkmcnt(6)
	v_mfma_f32_32x32x16_bf16 v[32:47], v[242:245], v[64:67], v[32:47]
	v_max3_f32 v254, v96, v97, v98
	v_max3_f32 v254, v254, v99, v100
	v_max3_f32 v254, v254, v101, v102
	v_max3_f32 v254, v254, v103, v104
	v_max3_f32 v254, v254, v105, v106
	v_max3_f32 v254, v254, v107, v108
	v_max3_f32 v254, v254, v109, v110
	v_max_f32_e32 v254, v254, v111
	v_exp_f32_e32 v96, v96
	v_exp_f32_e32 v97, v97
	v_exp_f32_e32 v98, v98
	v_exp_f32_e32 v99, v99
	s_waitcnt lgkmcnt(5)
	v_mfma_f32_32x32x16_bf16 v[16:31], v[246:249], v[64:67], v[16:31]
	ds_read_b128 v[242:245], v238 offset:62112
	ds_read_b128 v[246:249], v238 offset:53440
	v_add_f32_e32 v12, v12, v96
	v_add_f32_e32 v13, v13, v97
	v_add_f32_e32 v14, v14, v98
	v_add_f32_e32 v15, v15, v99
	v_exp_f32_e32 v100, v100
	v_exp_f32_e32 v101, v101
	v_exp_f32_e32 v102, v102
	v_exp_f32_e32 v103, v103
	v_add_f32_e32 v12, v12, v100
	v_add_f32_e32 v13, v13, v101
	v_add_f32_e32 v14, v14, v102
	v_add_f32_e32 v15, v15, v103
	s_waitcnt lgkmcnt(6)
	v_mfma_f32_32x32x16_bf16 v[32:47], v[250:253], v[68:71], v[32:47]
	v_cvt_pk_bf16_f32 v96, v96, v97
	v_cvt_pk_bf16_f32 v97, v98, v99
	v_cvt_pk_bf16_f32 v98, v100, v101
	v_cvt_pk_bf16_f32 v99, v102, v103
	v_exp_f32_e32 v104, v104
	v_exp_f32_e32 v105, v105
	v_exp_f32_e32 v106, v106
	v_exp_f32_e32 v107, v107
	v_add_f32_e32 v12, v12, v104
	v_add_f32_e32 v13, v13, v105
	v_add_f32_e32 v14, v14, v106
	v_add_f32_e32 v15, v15, v107
	s_waitcnt lgkmcnt(5)
	v_mfma_f32_32x32x16_bf16 v[16:31], v[222:225], v[68:71], v[16:31]
	ds_read_b128 v[250:253], v238 offset:62144
	ds_read_b128 v[222:225], v238 offset:53472
	v_exp_f32_e32 v108, v108
	v_exp_f32_e32 v109, v109
	v_exp_f32_e32 v110, v110
	v_exp_f32_e32 v111, v111
	v_add_f32_e32 v12, v12, v108
	v_add_f32_e32 v13, v13, v109
	v_add_f32_e32 v14, v14, v110
	v_add_f32_e32 v15, v15, v111
	v_cvt_pk_bf16_f32 v100, v104, v105
	v_cvt_pk_bf16_f32 v101, v106, v107
	v_cvt_pk_bf16_f32 v102, v108, v109
	v_cvt_pk_bf16_f32 v103, v110, v111
	s_waitcnt lgkmcnt(6)
	v_mfma_f32_32x32x16_bf16 v[32:47], v[226:229], v[96:99], v[32:47]
	v_max3_f32 v255, v48, v49, v50
	v_max3_f32 v255, v255, v51, v52
	v_max3_f32 v255, v255, v53, v54
	v_max3_f32 v255, v255, v55, v56
	v_max3_f32 v255, v255, v57, v58
	v_max3_f32 v255, v255, v59, v60
	v_max3_f32 v255, v255, v61, v62
	v_max_f32_e32 v255, v255, v63
	v_exp_f32_e32 v48, v48
	v_exp_f32_e32 v49, v49
	v_exp_f32_e32 v50, v50
	v_exp_f32_e32 v51, v51
	s_waitcnt lgkmcnt(5)
	v_mfma_f32_32x32x16_bf16 v[16:31], v[230:233], v[96:99], v[16:31]
	ds_read_b128 v[226:229], v238 offset:62176
	v_add_f32_e32 v12, v12, v48
	v_add_f32_e32 v13, v13, v49
	v_add_f32_e32 v14, v14, v50
	v_add_f32_e32 v15, v15, v51
	v_exp_f32_e32 v52, v52
	v_exp_f32_e32 v53, v53
	v_exp_f32_e32 v54, v54
	v_exp_f32_e32 v55, v55
	v_add_f32_e32 v12, v12, v52
	v_add_f32_e32 v13, v13, v53
	v_add_f32_e32 v14, v14, v54
	v_add_f32_e32 v15, v15, v55
	s_waitcnt lgkmcnt(5)
	v_mfma_f32_32x32x16_bf16 v[32:47], v[234:237], v[100:103], v[32:47]
	v_cvt_pk_bf16_f32 v48, v48, v49
	v_cvt_pk_bf16_f32 v49, v50, v51
	v_cvt_pk_bf16_f32 v50, v52, v53
	v_cvt_pk_bf16_f32 v51, v54, v55
	v_exp_f32_e32 v56, v56
	v_exp_f32_e32 v57, v57
	v_exp_f32_e32 v58, v58
	v_exp_f32_e32 v59, v59
	v_add_f32_e32 v12, v12, v56
	v_add_f32_e32 v13, v13, v57
	v_add_f32_e32 v14, v14, v58
	v_add_f32_e32 v15, v15, v59
	s_waitcnt lgkmcnt(4)
	v_mfma_f32_32x32x16_bf16 v[16:31], v[242:245], v[100:103], v[16:31]
	v_exp_f32_e32 v60, v60
	v_exp_f32_e32 v61, v61
	v_exp_f32_e32 v62, v62
	v_exp_f32_e32 v63, v63
	v_add_f32_e32 v12, v12, v60
	v_add_f32_e32 v13, v13, v61
	v_add_f32_e32 v14, v14, v62
	v_add_f32_e32 v15, v15, v63
	v_cvt_pk_bf16_f32 v52, v56, v57
	v_cvt_pk_bf16_f32 v53, v58, v59
	v_cvt_pk_bf16_f32 v54, v60, v61
	v_cvt_pk_bf16_f32 v55, v62, v63
	s_waitcnt lgkmcnt(3)
	v_mfma_f32_32x32x16_bf16 v[32:47], v[246:249], v[48:51], v[32:47]
	s_waitcnt lgkmcnt(2)
	v_mfma_f32_32x32x16_bf16 v[16:31], v[250:253], v[48:51], v[16:31]
	s_waitcnt lgkmcnt(1)
	v_mfma_f32_32x32x16_bf16 v[32:47], v[222:225], v[52:55], v[32:47]
	s_waitcnt lgkmcnt(0)
	v_mfma_f32_32x32x16_bf16 v[16:31], v[226:229], v[52:55], v[16:31]
	v_add_f32_e32 v12, v12, v13
	v_add_f32_e32 v14, v14, v15
	v_max3_f32 v2, v255, v11, v241
	v_add_f32_e32 v12, v12, v14
	v_max_f32_e32 v2, v2, v254
	v_add_f32_e32 v215, v215, v12
	v_mov_b32_e32 v3, v2
	s_nop 1
	v_permlane32_swap_b32_e32 v2, v3
	v_max_f32_e32 v2, v2, v3
	v_cmp_lt_f32_e32 vcc, 0, v2
	s_cbranch_vccz .Lattn_fnr_0
	s_nop 7
	s_nop 3
	v_max_f32_e32 v2, 0, v2
	v_exp_f32_e64 v4, -v2
	v_add_f32_e32 v0, v0, v2
	s_nop 0
	v_mul_f32_e32 v215, v215, v4
	v_mul_f32_e32 v16, v16, v4
	v_mul_f32_e32 v17, v17, v4
	v_mul_f32_e32 v18, v18, v4
	v_mul_f32_e32 v19, v19, v4
	v_mul_f32_e32 v20, v20, v4
	v_mul_f32_e32 v21, v21, v4
	v_mul_f32_e32 v22, v22, v4
	v_mul_f32_e32 v23, v23, v4
	v_mul_f32_e32 v24, v24, v4
	v_mul_f32_e32 v25, v25, v4
	v_mul_f32_e32 v26, v26, v4
	v_mul_f32_e32 v27, v27, v4
	v_mul_f32_e32 v28, v28, v4
	v_mul_f32_e32 v29, v29, v4
	v_mul_f32_e32 v30, v30, v4
	v_mul_f32_e32 v31, v31, v4
	v_mul_f32_e32 v32, v32, v4
	v_mul_f32_e32 v33, v33, v4
	v_mul_f32_e32 v34, v34, v4
	v_mul_f32_e32 v35, v35, v4
	v_mul_f32_e32 v36, v36, v4
	v_mul_f32_e32 v37, v37, v4
	v_mul_f32_e32 v38, v38, v4
	v_mul_f32_e32 v39, v39, v4
	v_mul_f32_e32 v40, v40, v4
	v_mul_f32_e32 v41, v41, v4
	v_mul_f32_e32 v42, v42, v4
	v_mul_f32_e32 v43, v43, v4
	v_mul_f32_e32 v44, v44, v4
	v_mul_f32_e32 v45, v45, v4
	v_mul_f32_e32 v46, v46, v4
	v_mul_f32_e32 v47, v47, v4
.Lattn_fnr_0:
	s_branch .Lat0_pvdone
.Lat0_pvmask:
	v_add3_u32 v238, s17, v163, v214
	v_add_u32_e32 v238, v238, v163
	ds_read_b128 v[222:225], v238 offset:53248
	ds_read_b128 v[226:229], v238 offset:61952
	ds_read_b128 v[230:233], v238 offset:53280
	ds_read_b128 v[234:237], v238 offset:61984
	ds_read_b128 v[242:245], v238 offset:53312
	ds_read_b128 v[246:249], v238 offset:62016
	ds_read_b128 v[250:253], v238 offset:53344
	v_add_u32_e32 v2, s100, v159
	v_add_u32_e32 v3, 0xffffff80, v2
	v_cmp_lt_i32_e32 vcc, v3, v171
	s_nop 1
	v_cndmask_b32_e32 v81, v203, v81, vcc
	v_cmp_le_i32_e32 vcc, v3, v171
	v_add_u32_e32 v3, 0xffffff82, v2
	s_nop 0
	v_cndmask_b32_e32 v80, v203, v80, vcc
	v_cmp_le_i32_e32 vcc, v3, v171
	v_add_u32_e32 v3, 0xffffff83, v2
	s_nop 0
	v_cndmask_b32_e32 v82, v203, v82, vcc
	v_cmp_le_i32_e32 vcc, v3, v171
	v_add_u32_e32 v3, 0xffffff88, v2
	s_nop 0
	v_cndmask_b32_e32 v83, v203, v83, vcc
	v_cmp_le_i32_e32 vcc, v3, v171
	v_add_u32_e32 v3, 0xffffff89, v2
	s_nop 0
	v_cndmask_b32_e32 v84, v203, v84, vcc
	v_cmp_le_i32_e32 vcc, v3, v171
	v_add_u32_e32 v3, 0xffffff8a, v2
	s_nop 0
	v_cndmask_b32_e32 v85, v203, v85, vcc
	v_cmp_le_i32_e32 vcc, v3, v171
	v_add_u32_e32 v3, 0xffffff8b, v2
	s_nop 0
	v_cndmask_b32_e32 v86, v203, v86, vcc
	v_cmp_le_i32_e32 vcc, v3, v171
	v_add_u32_e32 v3, 0xffffff90, v2
	s_nop 0
	v_cndmask_b32_e32 v87, v203, v87, vcc
	v_cmp_le_i32_e32 vcc, v3, v171
	v_add_u32_e32 v3, 0xffffff91, v2
	s_nop 0
	v_cndmask_b32_e32 v88, v203, v88, vcc
	v_cmp_le_i32_e32 vcc, v3, v171
	v_add_u32_e32 v3, 0xffffff92, v2
	s_nop 0
	v_cndmask_b32_e32 v89, v203, v89, vcc
	v_cmp_le_i32_e32 vcc, v3, v171
	v_add_u32_e32 v3, 0xffffff93, v2
	s_nop 0
	v_cndmask_b32_e32 v90, v203, v90, vcc
	v_cmp_le_i32_e32 vcc, v3, v171
	v_add_u32_e32 v3, 0xffffff98, v2
	s_nop 0
	v_cndmask_b32_e32 v91, v203, v91, vcc
	v_cmp_le_i32_e32 vcc, v3, v171
	v_add_u32_e32 v3, 0xffffff99, v2
	s_nop 0
	v_cndmask_b32_e32 v92, v203, v92, vcc
	v_cmp_le_i32_e32 vcc, v3, v171
	v_add_u32_e32 v3, 0xffffff9a, v2
	s_nop 0
	v_cndmask_b32_e32 v93, v203, v93, vcc
	v_cmp_le_i32_e32 vcc, v3, v171
	v_add_u32_e32 v3, 0xffffff9b, v2
	s_nop 0
	v_cndmask_b32_e32 v94, v203, v94, vcc
	v_cmp_le_i32_e32 vcc, v3, v171
	v_add_u32_e32 v3, 0xffffffa0, v2
	s_nop 0
	v_cndmask_b32_e32 v95, v203, v95, vcc
	v_cmp_le_i32_e32 vcc, v3, v171
	v_add_u32_e32 v3, 0xffffffa1, v2
	s_nop 0
	v_cndmask_b32_e32 v64, v203, v64, vcc
	v_cmp_le_i32_e32 vcc, v3, v171
	v_add_u32_e32 v3, 0xffffffa2, v2
	s_nop 0
	v_cndmask_b32_e32 v65, v203, v65, vcc
	v_cmp_le_i32_e32 vcc, v3, v171
	v_add_u32_e32 v3, 0xffffffa3, v2
	s_nop 0
	v_cndmask_b32_e32 v66, v203, v66, vcc
	v_cmp_le_i32_e32 vcc, v3, v171
	v_add_u32_e32 v3, 0xffffffa8, v2
	s_nop 0
	v_cndmask_b32_e32 v67, v203, v67, vcc
	v_cmp_le_i32_e32 vcc, v3, v171
	v_add_u32_e32 v3, 0xffffffa9, v2
	s_nop 0
	v_cndmask_b32_e32 v68, v203, v68, vcc
	v_cmp_le_i32_e32 vcc, v3, v171
	v_add_u32_e32 v3, 0xffffffaa, v2
	s_nop 0
	v_cndmask_b32_e32 v69, v203, v69, vcc
	v_cmp_le_i32_e32 vcc, v3, v171
	v_add_u32_e32 v3, 0xffffffab, v2
	s_nop 0
	v_cndmask_b32_e32 v70, v203, v70, vcc
	v_cmp_le_i32_e32 vcc, v3, v171
	v_add_u32_e32 v3, 0xffffffb0, v2
	s_nop 0
	v_cndmask_b32_e32 v71, v203, v71, vcc
	v_cmp_le_i32_e32 vcc, v3, v171
	v_add_u32_e32 v3, 0xffffffb1, v2
	s_nop 0
	v_cndmask_b32_e32 v72, v203, v72, vcc
	v_cmp_le_i32_e32 vcc, v3, v171
	v_add_u32_e32 v3, 0xffffffb2, v2
	s_nop 0
	v_cndmask_b32_e32 v73, v203, v73, vcc
	v_cmp_le_i32_e32 vcc, v3, v171
	v_add_u32_e32 v3, 0xffffffb3, v2
	s_nop 0
	v_cndmask_b32_e32 v74, v203, v74, vcc
	v_cmp_le_i32_e32 vcc, v3, v171
	v_add_u32_e32 v3, 0xffffffb8, v2
	s_nop 0
	v_cndmask_b32_e32 v75, v203, v75, vcc
	v_cmp_le_i32_e32 vcc, v3, v171
	v_add_u32_e32 v3, 0xffffffb9, v2
	s_nop 0
	v_cndmask_b32_e32 v76, v203, v76, vcc
	v_cmp_le_i32_e32 vcc, v3, v171
	v_add_u32_e32 v3, 0xffffffba, v2
	s_nop 0
	v_cndmask_b32_e32 v77, v203, v77, vcc
	v_cmp_le_i32_e32 vcc, v3, v171
	v_add_u32_e32 v3, 0xffffffbb, v2
	s_nop 0
	v_cndmask_b32_e32 v78, v203, v78, vcc
	v_cmp_le_i32_e32 vcc, v3, v171
	v_subrev_u32_e32 v3, 64, v2
	s_nop 0
	v_cndmask_b32_e32 v79, v203, v79, vcc
	v_cmp_le_i32_e32 vcc, v3, v171
	v_subrev_u32_e32 v3, 63, v2
	s_nop 0
	v_cndmask_b32_e32 v96, v203, v96, vcc
	v_cmp_le_i32_e32 vcc, v3, v171
	v_subrev_u32_e32 v3, 62, v2
	s_nop 0
	v_cndmask_b32_e32 v97, v203, v97, vcc
	v_cmp_le_i32_e32 vcc, v3, v171
	v_subrev_u32_e32 v3, 61, v2
	s_nop 0
	v_cndmask_b32_e32 v98, v203, v98, vcc
	v_cmp_le_i32_e32 vcc, v3, v171
	v_subrev_u32_e32 v3, 56, v2
	s_nop 0
	v_cndmask_b32_e32 v99, v203, v99, vcc
	v_cmp_le_i32_e32 vcc, v3, v171
	v_subrev_u32_e32 v3, 55, v2
	s_nop 0
	v_cndmask_b32_e32 v100, v203, v100, vcc
	v_cmp_le_i32_e32 vcc, v3, v171
	v_subrev_u32_e32 v3, 54, v2
	s_nop 0
	v_cndmask_b32_e32 v101, v203, v101, vcc
	v_cmp_le_i32_e32 vcc, v3, v171
	v_subrev_u32_e32 v3, 53, v2
	s_nop 0
	v_cndmask_b32_e32 v102, v203, v102, vcc
	v_cmp_le_i32_e32 vcc, v3, v171
	v_subrev_u32_e32 v3, 48, v2
	s_nop 0
	v_cndmask_b32_e32 v103, v203, v103, vcc
	v_cmp_le_i32_e32 vcc, v3, v171
	v_subrev_u32_e32 v3, 47, v2
	s_nop 0
	v_cndmask_b32_e32 v104, v203, v104, vcc
	v_cmp_le_i32_e32 vcc, v3, v171
	v_subrev_u32_e32 v3, 46, v2
	s_nop 0
	v_cndmask_b32_e32 v105, v203, v105, vcc
	v_cmp_le_i32_e32 vcc, v3, v171
	v_subrev_u32_e32 v3, 45, v2
	s_nop 0
	v_cndmask_b32_e32 v106, v203, v106, vcc
	v_cmp_le_i32_e32 vcc, v3, v171
	v_subrev_u32_e32 v3, 40, v2
	s_nop 0
	v_cndmask_b32_e32 v107, v203, v107, vcc
	v_cmp_le_i32_e32 vcc, v3, v171
	v_subrev_u32_e32 v3, 39, v2
	s_nop 0
	v_cndmask_b32_e32 v108, v203, v108, vcc
	v_cmp_le_i32_e32 vcc, v3, v171
	v_subrev_u32_e32 v3, 38, v2
	s_nop 0
	v_cndmask_b32_e32 v109, v203, v109, vcc
	v_cmp_le_i32_e32 vcc, v3, v171
	v_subrev_u32_e32 v3, 37, v2
	s_nop 0
	v_cndmask_b32_e32 v110, v203, v110, vcc
	v_cmp_le_i32_e32 vcc, v3, v171
	v_subrev_u32_e32 v3, 32, v2
	s_nop 0
	v_cndmask_b32_e32 v111, v203, v111, vcc
	v_cmp_le_i32_e32 vcc, v3, v171
	v_subrev_u32_e32 v3, 31, v2
	s_nop 0
	v_cndmask_b32_e32 v48, v203, v48, vcc
	v_cmp_le_i32_e32 vcc, v3, v171
	v_subrev_u32_e32 v3, 30, v2
	s_nop 0
	v_cndmask_b32_e32 v49, v203, v49, vcc
	v_cmp_le_i32_e32 vcc, v3, v171
	v_subrev_u32_e32 v3, 29, v2
	s_nop 0
	v_cndmask_b32_e32 v50, v203, v50, vcc
	v_cmp_le_i32_e32 vcc, v3, v171
	v_subrev_u32_e32 v3, 24, v2
	s_nop 0
	v_cndmask_b32_e32 v51, v203, v51, vcc
	v_cmp_le_i32_e32 vcc, v3, v171
	v_subrev_u32_e32 v3, 23, v2
	s_nop 0
	v_cndmask_b32_e32 v52, v203, v52, vcc
	v_cmp_le_i32_e32 vcc, v3, v171
	v_subrev_u32_e32 v3, 22, v2
	s_nop 0
	v_cndmask_b32_e32 v53, v203, v53, vcc
	v_cmp_le_i32_e32 vcc, v3, v171
	v_subrev_u32_e32 v3, 21, v2
	s_nop 0
	v_cndmask_b32_e32 v54, v203, v54, vcc
	v_cmp_le_i32_e32 vcc, v3, v171
	v_add_u32_e32 v3, -16, v2
	s_nop 0
	v_cndmask_b32_e32 v55, v203, v55, vcc
	v_cmp_le_i32_e32 vcc, v3, v171
	v_add_u32_e32 v3, -15, v2
	s_nop 0
	v_cndmask_b32_e32 v56, v203, v56, vcc
	v_cmp_le_i32_e32 vcc, v3, v171
	v_add_u32_e32 v3, -14, v2
	s_nop 0
	v_cndmask_b32_e32 v57, v203, v57, vcc
	v_cmp_le_i32_e32 vcc, v3, v171
	v_add_u32_e32 v3, -13, v2
	s_nop 0
	v_cndmask_b32_e32 v58, v203, v58, vcc
	v_cmp_le_i32_e32 vcc, v3, v171
	v_add_u32_e32 v3, -8, v2
	s_nop 0
	v_cndmask_b32_e32 v59, v203, v59, vcc
	v_cmp_le_i32_e32 vcc, v3, v171
	v_add_u32_e32 v3, -7, v2
	s_nop 0
	v_cndmask_b32_e32 v60, v203, v60, vcc
	v_cmp_le_i32_e32 vcc, v3, v171
	v_add_u32_e32 v3, -6, v2
	v_add_u32_e32 v2, -5, v2
	v_cndmask_b32_e32 v61, v203, v61, vcc
	v_cmp_le_i32_e32 vcc, v3, v171
	s_nop 1
	v_cndmask_b32_e32 v62, v203, v62, vcc
	v_cmp_le_i32_e32 vcc, v2, v171
	s_nop 1
	v_cndmask_b32_e32 v63, v203, v63, vcc
	v_max_f32_e32 v2, v81, v81
	v_max_f32_e32 v3, v80, v80
	v_max_f32_e32 v2, v3, v2
	v_max3_f32 v2, v2, v82, v83
	v_max3_f32 v2, v2, v84, v85
	v_max3_f32 v2, v2, v86, v87
	v_max3_f32 v2, v2, v88, v89
	v_max3_f32 v2, v2, v90, v91
	v_max3_f32 v2, v2, v92, v93
	v_max3_f32 v2, v2, v94, v95
	v_max3_f32 v2, v2, v64, v65
	v_max3_f32 v2, v2, v66, v67
	v_max3_f32 v2, v2, v68, v69
	v_max3_f32 v2, v2, v70, v71
	v_max3_f32 v2, v2, v72, v73
	v_max3_f32 v2, v2, v74, v75
	v_max3_f32 v2, v2, v76, v77
	v_max3_f32 v2, v2, v78, v79
	v_max3_f32 v2, v2, v96, v97
	v_max3_f32 v2, v2, v98, v99
	v_max3_f32 v2, v2, v100, v101
	v_max3_f32 v2, v2, v102, v103
	v_max3_f32 v2, v2, v104, v105
	v_max3_f32 v2, v2, v106, v107
	v_max3_f32 v2, v2, v108, v109
	v_max3_f32 v2, v2, v110, v111
	v_max3_f32 v2, v2, v48, v49
	v_max3_f32 v2, v2, v50, v51
	v_max3_f32 v2, v2, v52, v53
	v_max3_f32 v2, v2, v54, v55
	v_max3_f32 v2, v2, v56, v57
	v_max3_f32 v2, v2, v58, v59
	v_max3_f32 v2, v2, v60, v61
	v_max3_f32 v2, v2, v62, v63
	v_mov_b32_e32 v3, v2
	s_nop 1
	v_permlane32_swap_b32_e32 v2, v3
	v_max_f32_e32 v2, v2, v3
	v_cmp_lt_f32_e32 vcc, 0, v2
	s_cbranch_vccz .Lat0_pvnr
	v_max_f32_e32 v2, v2, v2
	v_max_f32_e32 v2, 0, v2
	v_exp_f32_e64 v4, -v2
	v_add_f32_e32 v0, v0, v2
	v_pk_add_f32 v[80:81], v[80:81], v[2:3] op_sel_hi:[1,0] neg_lo:[0,1] neg_hi:[0,1]
	v_pk_add_f32 v[64:65], v[64:65], v[2:3] op_sel_hi:[1,0] neg_lo:[0,1] neg_hi:[0,1]
	v_pk_add_f32 v[96:97], v[96:97], v[2:3] op_sel_hi:[1,0] neg_lo:[0,1] neg_hi:[0,1]
	v_pk_add_f32 v[48:49], v[48:49], v[2:3] op_sel_hi:[1,0] neg_lo:[0,1] neg_hi:[0,1]
	v_pk_add_f32 v[82:83], v[82:83], v[2:3] op_sel_hi:[1,0] neg_lo:[0,1] neg_hi:[0,1]
	v_pk_add_f32 v[66:67], v[66:67], v[2:3] op_sel_hi:[1,0] neg_lo:[0,1] neg_hi:[0,1]
	v_pk_add_f32 v[98:99], v[98:99], v[2:3] op_sel_hi:[1,0] neg_lo:[0,1] neg_hi:[0,1]
	v_pk_add_f32 v[50:51], v[50:51], v[2:3] op_sel_hi:[1,0] neg_lo:[0,1] neg_hi:[0,1]
	v_pk_add_f32 v[84:85], v[84:85], v[2:3] op_sel_hi:[1,0] neg_lo:[0,1] neg_hi:[0,1]
	v_pk_add_f32 v[68:69], v[68:69], v[2:3] op_sel_hi:[1,0] neg_lo:[0,1] neg_hi:[0,1]
	v_pk_add_f32 v[100:101], v[100:101], v[2:3] op_sel_hi:[1,0] neg_lo:[0,1] neg_hi:[0,1]
	v_pk_add_f32 v[52:53], v[52:53], v[2:3] op_sel_hi:[1,0] neg_lo:[0,1] neg_hi:[0,1]
	v_pk_add_f32 v[86:87], v[86:87], v[2:3] op_sel_hi:[1,0] neg_lo:[0,1] neg_hi:[0,1]
	v_pk_add_f32 v[70:71], v[70:71], v[2:3] op_sel_hi:[1,0] neg_lo:[0,1] neg_hi:[0,1]
	v_pk_add_f32 v[102:103], v[102:103], v[2:3] op_sel_hi:[1,0] neg_lo:[0,1] neg_hi:[0,1]
	v_pk_add_f32 v[54:55], v[54:55], v[2:3] op_sel_hi:[1,0] neg_lo:[0,1] neg_hi:[0,1]
	v_pk_add_f32 v[88:89], v[88:89], v[2:3] op_sel_hi:[1,0] neg_lo:[0,1] neg_hi:[0,1]
	v_pk_add_f32 v[72:73], v[72:73], v[2:3] op_sel_hi:[1,0] neg_lo:[0,1] neg_hi:[0,1]
	v_pk_add_f32 v[104:105], v[104:105], v[2:3] op_sel_hi:[1,0] neg_lo:[0,1] neg_hi:[0,1]
	v_pk_add_f32 v[56:57], v[56:57], v[2:3] op_sel_hi:[1,0] neg_lo:[0,1] neg_hi:[0,1]
	v_pk_add_f32 v[90:91], v[90:91], v[2:3] op_sel_hi:[1,0] neg_lo:[0,1] neg_hi:[0,1]
	v_pk_add_f32 v[74:75], v[74:75], v[2:3] op_sel_hi:[1,0] neg_lo:[0,1] neg_hi:[0,1]
	v_pk_add_f32 v[106:107], v[106:107], v[2:3] op_sel_hi:[1,0] neg_lo:[0,1] neg_hi:[0,1]
	v_pk_add_f32 v[58:59], v[58:59], v[2:3] op_sel_hi:[1,0] neg_lo:[0,1] neg_hi:[0,1]
	v_pk_add_f32 v[92:93], v[92:93], v[2:3] op_sel_hi:[1,0] neg_lo:[0,1] neg_hi:[0,1]
	v_pk_add_f32 v[76:77], v[76:77], v[2:3] op_sel_hi:[1,0] neg_lo:[0,1] neg_hi:[0,1]
	v_pk_add_f32 v[108:109], v[108:109], v[2:3] op_sel_hi:[1,0] neg_lo:[0,1] neg_hi:[0,1]
	v_pk_add_f32 v[60:61], v[60:61], v[2:3] op_sel_hi:[1,0] neg_lo:[0,1] neg_hi:[0,1]
	v_pk_add_f32 v[94:95], v[94:95], v[2:3] op_sel_hi:[1,0] neg_lo:[0,1] neg_hi:[0,1]
	v_pk_add_f32 v[78:79], v[78:79], v[2:3] op_sel_hi:[1,0] neg_lo:[0,1] neg_hi:[0,1]
	v_pk_add_f32 v[110:111], v[110:111], v[2:3] op_sel_hi:[1,0] neg_lo:[0,1] neg_hi:[0,1]
	v_pk_add_f32 v[62:63], v[62:63], v[2:3] op_sel_hi:[1,0] neg_lo:[0,1] neg_hi:[0,1]
	v_pk_mul_f32 v[46:47], v[46:47], v[4:5] op_sel_hi:[1,0]
	v_pk_mul_f32 v[44:45], v[44:45], v[4:5] op_sel_hi:[1,0]
	v_pk_mul_f32 v[42:43], v[42:43], v[4:5] op_sel_hi:[1,0]
	v_pk_mul_f32 v[40:41], v[40:41], v[4:5] op_sel_hi:[1,0]
	v_pk_mul_f32 v[38:39], v[38:39], v[4:5] op_sel_hi:[1,0]
	v_pk_mul_f32 v[36:37], v[36:37], v[4:5] op_sel_hi:[1,0]
	v_pk_mul_f32 v[34:35], v[34:35], v[4:5] op_sel_hi:[1,0]
	v_pk_mul_f32 v[32:33], v[32:33], v[4:5] op_sel_hi:[1,0]
	v_pk_mul_f32 v[30:31], v[30:31], v[4:5] op_sel_hi:[1,0]
	v_pk_mul_f32 v[28:29], v[28:29], v[4:5] op_sel_hi:[1,0]
	v_pk_mul_f32 v[26:27], v[26:27], v[4:5] op_sel_hi:[1,0]
	v_pk_mul_f32 v[24:25], v[24:25], v[4:5] op_sel_hi:[1,0]
	v_pk_mul_f32 v[22:23], v[22:23], v[4:5] op_sel_hi:[1,0]
	v_pk_mul_f32 v[20:21], v[20:21], v[4:5] op_sel_hi:[1,0]
	v_pk_mul_f32 v[18:19], v[18:19], v[4:5] op_sel_hi:[1,0]
	v_pk_mul_f32 v[16:17], v[16:17], v[4:5] op_sel_hi:[1,0]
	v_mul_f32_e32 v215, v215, v4
.Lat0_pvnr:
	v_exp_f32_e32 v80, v80
	v_exp_f32_e32 v81, v81
	v_exp_f32_e32 v82, v82
	v_exp_f32_e32 v83, v83
	v_exp_f32_e32 v84, v84
	v_exp_f32_e32 v85, v85
	v_exp_f32_e32 v86, v86
	v_exp_f32_e32 v87, v87
	v_cvt_pk_bf16_f32 v2, v80, v81
	v_cvt_pk_bf16_f32 v3, v82, v83
	v_cvt_pk_bf16_f32 v4, v84, v85
	v_cvt_pk_bf16_f32 v5, v86, v87
	v_add_f32_e32 v12, v80, v84
	v_add_f32_e32 v13, v81, v85
	v_add_f32_e32 v14, v82, v86
	v_add_f32_e32 v15, v83, v87
	s_waitcnt lgkmcnt(6)
	v_mfma_f32_32x32x16_bf16 v[32:47], v[222:225], v[2:5], v[32:47]
	v_exp_f32_e32 v88, v88
	v_exp_f32_e32 v89, v89
	v_exp_f32_e32 v90, v90
	v_exp_f32_e32 v91, v91
	v_cvt_pk_bf16_f32 v6, v88, v89
	v_cvt_pk_bf16_f32 v7, v90, v91
	v_add_f32_e32 v12, v12, v88
	v_add_f32_e32 v13, v13, v89
	v_add_f32_e32 v14, v14, v90
	v_add_f32_e32 v15, v15, v91
	s_waitcnt lgkmcnt(5)
	v_mfma_f32_32x32x16_bf16 v[16:31], v[226:229], v[2:5], v[16:31]
	v_exp_f32_e32 v92, v92
	v_exp_f32_e32 v93, v93
	v_exp_f32_e32 v94, v94
	v_exp_f32_e32 v95, v95
	v_cvt_pk_bf16_f32 v8, v92, v93
	v_cvt_pk_bf16_f32 v9, v94, v95
	v_add_f32_e32 v12, v12, v92
	v_add_f32_e32 v13, v13, v93
	v_add_f32_e32 v14, v14, v94
	v_add_f32_e32 v15, v15, v95
	ds_read_b128 v[222:225], v238 offset:62048
	ds_read_b128 v[226:229], v238 offset:53376
	s_waitcnt lgkmcnt(6)
	v_mfma_f32_32x32x16_bf16 v[32:47], v[230:233], v[6:9], v[32:47]
	v_exp_f32_e32 v64, v64
	v_exp_f32_e32 v65, v65
	v_exp_f32_e32 v66, v66
	v_exp_f32_e32 v67, v67
	v_cvt_pk_bf16_f32 v2, v64, v65
	v_cvt_pk_bf16_f32 v3, v66, v67
	v_add_f32_e32 v12, v12, v64
	v_add_f32_e32 v13, v13, v65
	v_add_f32_e32 v14, v14, v66
	v_add_f32_e32 v15, v15, v67
	s_waitcnt lgkmcnt(5)
	v_mfma_f32_32x32x16_bf16 v[16:31], v[234:237], v[6:9], v[16:31]
	v_exp_f32_e32 v68, v68
	v_exp_f32_e32 v69, v69
	v_exp_f32_e32 v70, v70
	v_exp_f32_e32 v71, v71
	v_cvt_pk_bf16_f32 v4, v68, v69
	v_cvt_pk_bf16_f32 v5, v70, v71
	v_add_f32_e32 v12, v12, v68
	v_add_f32_e32 v13, v13, v69
	v_add_f32_e32 v14, v14, v70
	v_add_f32_e32 v15, v15, v71
	ds_read_b128 v[230:233], v238 offset:62080
	ds_read_b128 v[234:237], v238 offset:53408
	s_waitcnt lgkmcnt(6)
	v_mfma_f32_32x32x16_bf16 v[32:47], v[242:245], v[2:5], v[32:47]
	v_exp_f32_e32 v72, v72
	v_exp_f32_e32 v73, v73
	v_exp_f32_e32 v74, v74
	v_exp_f32_e32 v75, v75
	v_cvt_pk_bf16_f32 v6, v72, v73
	v_cvt_pk_bf16_f32 v7, v74, v75
	v_add_f32_e32 v12, v12, v72
	v_add_f32_e32 v13, v13, v73
	v_add_f32_e32 v14, v14, v74
	v_add_f32_e32 v15, v15, v75
	s_waitcnt lgkmcnt(5)
	v_mfma_f32_32x32x16_bf16 v[16:31], v[246:249], v[2:5], v[16:31]
	v_exp_f32_e32 v76, v76
	v_exp_f32_e32 v77, v77
	v_exp_f32_e32 v78, v78
	v_exp_f32_e32 v79, v79
	v_cvt_pk_bf16_f32 v8, v76, v77
	v_cvt_pk_bf16_f32 v9, v78, v79
	v_add_f32_e32 v12, v12, v76
	v_add_f32_e32 v13, v13, v77
	v_add_f32_e32 v14, v14, v78
	v_add_f32_e32 v15, v15, v79
	ds_read_b128 v[242:245], v238 offset:62112
	ds_read_b128 v[246:249], v238 offset:53440
	s_waitcnt lgkmcnt(6)
	v_mfma_f32_32x32x16_bf16 v[32:47], v[250:253], v[6:9], v[32:47]
	v_exp_f32_e32 v96, v96
	v_exp_f32_e32 v97, v97
	v_exp_f32_e32 v98, v98
	v_exp_f32_e32 v99, v99
	v_cvt_pk_bf16_f32 v2, v96, v97
	v_cvt_pk_bf16_f32 v3, v98, v99
	v_add_f32_e32 v12, v12, v96
	v_add_f32_e32 v13, v13, v97
	v_add_f32_e32 v14, v14, v98
	v_add_f32_e32 v15, v15, v99
	s_waitcnt lgkmcnt(5)
	v_mfma_f32_32x32x16_bf16 v[16:31], v[222:225], v[6:9], v[16:31]
	v_exp_f32_e32 v100, v100
	v_exp_f32_e32 v101, v101
	v_exp_f32_e32 v102, v102
	v_exp_f32_e32 v103, v103
	v_cvt_pk_bf16_f32 v4, v100, v101
	v_cvt_pk_bf16_f32 v5, v102, v103
	v_add_f32_e32 v12, v12, v100
	v_add_f32_e32 v13, v13, v101
	v_add_f32_e32 v14, v14, v102
	v_add_f32_e32 v15, v15, v103
	ds_read_b128 v[250:253], v238 offset:62144
	ds_read_b128 v[222:225], v238 offset:53472
	s_waitcnt lgkmcnt(6)
	v_mfma_f32_32x32x16_bf16 v[32:47], v[226:229], v[2:5], v[32:47]
	v_exp_f32_e32 v104, v104
	v_exp_f32_e32 v105, v105
	v_exp_f32_e32 v106, v106
	v_exp_f32_e32 v107, v107
	v_cvt_pk_bf16_f32 v6, v104, v105
	v_cvt_pk_bf16_f32 v7, v106, v107
	v_add_f32_e32 v12, v12, v104
	v_add_f32_e32 v13, v13, v105
	v_add_f32_e32 v14, v14, v106
	v_add_f32_e32 v15, v15, v107
	s_waitcnt lgkmcnt(5)
	v_mfma_f32_32x32x16_bf16 v[16:31], v[230:233], v[2:5], v[16:31]
	v_exp_f32_e32 v108, v108
	v_exp_f32_e32 v109, v109
	v_exp_f32_e32 v110, v110
	v_exp_f32_e32 v111, v111
	v_cvt_pk_bf16_f32 v8, v108, v109
	v_cvt_pk_bf16_f32 v9, v110, v111
	v_add_f32_e32 v12, v12, v108
	v_add_f32_e32 v13, v13, v109
	v_add_f32_e32 v14, v14, v110
	v_add_f32_e32 v15, v15, v111
	ds_read_b128 v[226:229], v238 offset:62176
	s_waitcnt lgkmcnt(5)
	v_mfma_f32_32x32x16_bf16 v[32:47], v[234:237], v[6:9], v[32:47]
	v_exp_f32_e32 v48, v48
	v_exp_f32_e32 v49, v49
	v_exp_f32_e32 v50, v50
	v_exp_f32_e32 v51, v51
	v_cvt_pk_bf16_f32 v2, v48, v49
	v_cvt_pk_bf16_f32 v3, v50, v51
	v_add_f32_e32 v12, v12, v48
	v_add_f32_e32 v13, v13, v49
	v_add_f32_e32 v14, v14, v50
	v_add_f32_e32 v15, v15, v51
	s_waitcnt lgkmcnt(4)
	v_mfma_f32_32x32x16_bf16 v[16:31], v[242:245], v[6:9], v[16:31]
	v_exp_f32_e32 v52, v52
	v_exp_f32_e32 v53, v53
	v_exp_f32_e32 v54, v54
	v_exp_f32_e32 v55, v55
	v_cvt_pk_bf16_f32 v4, v52, v53
	v_cvt_pk_bf16_f32 v5, v54, v55
	v_add_f32_e32 v12, v12, v52
	v_add_f32_e32 v13, v13, v53
	v_add_f32_e32 v14, v14, v54
	v_add_f32_e32 v15, v15, v55
	s_waitcnt lgkmcnt(3)
	v_mfma_f32_32x32x16_bf16 v[32:47], v[246:249], v[2:5], v[32:47]
	v_exp_f32_e32 v56, v56
	v_exp_f32_e32 v57, v57
	v_exp_f32_e32 v58, v58
	v_exp_f32_e32 v59, v59
	v_cvt_pk_bf16_f32 v6, v56, v57
	v_cvt_pk_bf16_f32 v7, v58, v59
	v_add_f32_e32 v12, v12, v56
	v_add_f32_e32 v13, v13, v57
	v_add_f32_e32 v14, v14, v58
	v_add_f32_e32 v15, v15, v59
	s_waitcnt lgkmcnt(2)
	v_mfma_f32_32x32x16_bf16 v[16:31], v[250:253], v[2:5], v[16:31]
	v_exp_f32_e32 v60, v60
	v_exp_f32_e32 v61, v61
	v_exp_f32_e32 v62, v62
	v_exp_f32_e32 v63, v63
	v_cvt_pk_bf16_f32 v8, v60, v61
	v_cvt_pk_bf16_f32 v9, v62, v63
	v_add_f32_e32 v12, v12, v60
	v_add_f32_e32 v13, v13, v61
	v_add_f32_e32 v14, v14, v62
	v_add_f32_e32 v15, v15, v63
	s_waitcnt lgkmcnt(1)
	v_mfma_f32_32x32x16_bf16 v[32:47], v[222:225], v[6:9], v[32:47]
	s_waitcnt lgkmcnt(0)
	v_mfma_f32_32x32x16_bf16 v[16:31], v[226:229], v[6:9], v[16:31]
	v_add_f32_e32 v12, v12, v13
	v_add_f32_e32 v14, v14, v15
	v_add_f32_e32 v12, v12, v14
	v_add_f32_e32 v215, v215, v12
.Lat0_pvdone:
	s_cmp_ge_u32 s18, s99
	s_cbranch_scc1 .LBB0_652
	s_cmp_eq_u32 s98, 1
	s_cbranch_scc1 .Lat0_qk
.Lat0_endit:
	s_cmp_ge_u32 s16, s99
	s_cbranch_scc1 .Lat0_nowr
	s_and_b32 s12, s16, 1
	s_add_i32 s13, s101, 1
	s_cmp_ge_u32 s13, 3
	s_cbranch_scc0 .Lat0_wm3
	s_mov_b32 s13, 0
.Lat0_wm3:
	s_mov_b32 s101, s13
	s_mul_i32 s13, s13, 0x4400
	s_mul_i32 s12, s12, 0x6800
	v_add3_u32 v2, s12, v165, v162
	s_waitcnt vmcnt(4)
	ds_write_b128 v2, v[136:139]
	v_add3_u32 v2, s12, v209, v168
	s_waitcnt vmcnt(3)
	ds_write_b128 v2, v[140:143]
	v_add3_u32 v2, s12, v210, v172
	s_waitcnt vmcnt(2)
	ds_write_b128 v2, v[144:147]
	v_lshl_add_u32 v2, v161, 1, s13
	v_add_u32_e32 v3, v2, v211
	v_add_u32_e32 v2, v2, v212
	s_waitcnt vmcnt(1)
	ds_write2_b64 v3, v[148:149], v[150:151] offset1:2
	s_waitcnt vmcnt(0)
	ds_write2_b64 v2, v[152:153], v[154:155] offset1:2
	s_branch .Lat0_adv
.Lat0_nowr:
	s_add_i32 s13, s101, 1
	s_cmp_ge_u32 s13, 3
	s_cbranch_scc0 .Lat0_nm3
	s_mov_b32 s13, 0
.Lat0_nm3:
	s_mov_b32 s101, s13
.Lat0_adv:
	s_addk_i32 s52, 0x80
	s_mov_b32 s18, s16
	s_cmp_lt_u32 s18, s99
	s_cbranch_scc1 .Lat0_loop
	s_cmp_eq_u32 s98, 1
	s_cbranch_scc1 .Lat0_pv
	s_branch .LBB0_652

.LBB0_733:
	v_readfirstlane_b32 s54, v64
	s_xor_b32 m0, s53, 1
	s_mul_i32 m0, m0, 0xc000
	s_add_i32 s54, s54, m0
	s_mul_i32 s53, s53, 0xc000
	s_add_i32 s53, s53, 0
	v_add3_u32 v147, s53, v142, v143
	v_add_u32_e32 v168, v147, v145
	v_add3_u32 v172, s53, v144, v143
	v_add_u32_e32 v173, v172, v145
	ds_read_b128 v[148:151], v168 offset:32768
	ds_read_b128 v[152:155], v168 offset:34816
	ds_read_b128 v[164:167], v168 offset:36864
	ds_read_b128 v[168:171], v168 offset:38912
	ds_read_b128 v[156:159], v173
	ds_read_b128 v[160:163], v173 offset:2048
	ds_read_b128 v[242:245], v173 offset:4096
	ds_read_b128 v[246:249], v173 offset:6144
	s_mov_b32 m0, s54
	v_lshl_add_u64 v[254:255], v[130:131], 0, s[12:13]
	global_load_lds_dwordx4 v[254:255], off
	s_add_i32 m0, s54, 0x2000
	v_lshl_add_u64 v[254:255], v[132:133], 0, s[12:13]
	global_load_lds_dwordx4 v[254:255], off
	s_waitcnt lgkmcnt(2)
	v_mfma_f32_16x16x32_bf16 v[60:63], v[148:151], v[156:159], v[60:63]
	v_add_u32_e32 v147, v147, v146
	v_add_u32_e32 v172, v172, v146
	v_mfma_f32_16x16x32_bf16 v[44:47], v[148:151], v[160:163], v[44:47]
	v_mfma_f32_16x16x32_bf16 v[56:59], v[152:155], v[156:159], v[56:59]
	v_mfma_f32_16x16x32_bf16 v[40:43], v[152:155], v[160:163], v[40:43]
	s_add_i32 m0, s54, 0x4000
	v_lshl_add_u64 v[254:255], v[134:135], 0, s[12:13]
	global_load_lds_dwordx4 v[254:255], off
	v_mfma_f32_16x16x32_bf16 v[52:55], v[164:167], v[156:159], v[52:55]
	v_mfma_f32_16x16x32_bf16 v[36:39], v[164:167], v[160:163], v[36:39]
	v_mfma_f32_16x16x32_bf16 v[48:51], v[168:171], v[156:159], v[48:51]
	v_mfma_f32_16x16x32_bf16 v[32:35], v[168:171], v[160:163], v[32:35]
	s_add_i32 m0, s54, 0x6000
	v_lshl_add_u64 v[254:255], v[136:137], 0, s[12:13]
	global_load_lds_dwordx4 v[254:255], off
	ds_read_b128 v[156:159], v172
	ds_read_b128 v[160:163], v172 offset:2048
	s_waitcnt lgkmcnt(2)
	v_mfma_f32_16x16x32_bf16 v[28:31], v[148:151], v[242:245], v[28:31]
	v_mfma_f32_16x16x32_bf16 v[12:15], v[148:151], v[246:249], v[12:15]
	ds_read_b128 v[148:151], v147 offset:32768
	v_mfma_f32_16x16x32_bf16 v[24:27], v[152:155], v[242:245], v[24:27]
	v_mfma_f32_16x16x32_bf16 v[4:7], v[152:155], v[246:249], v[4:7]
	s_add_i32 m0, s54, 0x8000
	v_lshl_add_u64 v[254:255], v[138:139], 0, s[12:13]
	global_load_lds_dwordx4 v[254:255], off
	ds_read_b128 v[152:155], v147 offset:34816
	v_mfma_f32_16x16x32_bf16 v[20:23], v[164:167], v[242:245], v[20:23]
	v_mfma_f32_16x16x32_bf16 v[0:3], v[164:167], v[246:249], v[0:3]
	ds_read_b128 v[164:167], v147 offset:36864
	v_mfma_f32_16x16x32_bf16 v[16:19], v[168:171], v[242:245], v[16:19]
	v_mfma_f32_16x16x32_bf16 v[8:11], v[168:171], v[246:249], v[8:11]
	s_add_i32 m0, s54, 0xa000
	v_lshl_add_u64 v[254:255], v[140:141], 0, s[12:13]
	global_load_lds_dwordx4 v[254:255], off
	s_add_u32 s12, s12, 0x80
	s_addc_u32 s13, s13, 0
	s_add_i32 s3, s3, 1
	s_cmpk_lg_i32 s12, 0x800
	ds_read_b128 v[168:171], v147 offset:38912
	ds_read_b128 v[242:245], v172 offset:4096
	ds_read_b128 v[246:249], v172 offset:6144
	s_waitcnt lgkmcnt(2)
	v_mfma_f32_16x16x32_bf16 v[60:63], v[148:151], v[156:159], v[60:63]
	v_mfma_f32_16x16x32_bf16 v[44:47], v[148:151], v[160:163], v[44:47]
	v_mfma_f32_16x16x32_bf16 v[56:59], v[152:155], v[156:159], v[56:59]
	v_mfma_f32_16x16x32_bf16 v[40:43], v[152:155], v[160:163], v[40:43]
	v_mfma_f32_16x16x32_bf16 v[52:55], v[164:167], v[156:159], v[52:55]
	v_mfma_f32_16x16x32_bf16 v[36:39], v[164:167], v[160:163], v[36:39]
	v_mfma_f32_16x16x32_bf16 v[48:51], v[168:171], v[156:159], v[48:51]
	v_mfma_f32_16x16x32_bf16 v[32:35], v[168:171], v[160:163], v[32:35]
	s_waitcnt vmcnt(0)
	s_waitcnt vmcnt(0) lgkmcnt(0)
	v_mfma_f32_16x16x32_bf16 v[28:31], v[148:151], v[242:245], v[28:31]
	s_barrier
	v_mfma_f32_16x16x32_bf16 v[12:15], v[148:151], v[246:249], v[12:15]
	v_mfma_f32_16x16x32_bf16 v[24:27], v[152:155], v[242:245], v[24:27]
	v_mfma_f32_16x16x32_bf16 v[4:7], v[152:155], v[246:249], v[4:7]
	v_mfma_f32_16x16x32_bf16 v[20:23], v[164:167], v[242:245], v[20:23]
	v_mfma_f32_16x16x32_bf16 v[0:3], v[164:167], v[246:249], v[0:3]
	v_mfma_f32_16x16x32_bf16 v[16:19], v[168:171], v[242:245], v[16:19]
	v_mfma_f32_16x16x32_bf16 v[8:11], v[168:171], v[246:249], v[8:11]
	s_cbranch_scc0 .LBB0_736
.LBB0_734:
	s_and_b32 s53, s3, 1
	s_branch .LBB0_733

.LBB0_737:
	v_readfirstlane_b32 s54, v208
	s_xor_b32 m0, s53, 1
	s_mul_i32 m0, m0, 0xc000
	s_add_i32 s54, s54, m0
	s_mul_i32 s53, s53, 0xc000
	s_add_i32 s53, s53, 0
	v_add3_u32 v64, s53, v209, v210
	v_add_u32_e32 v234, v64, v212
	v_add3_u32 v238, s53, v211, v210
	v_add_u32_e32 v239, v238, v212
	ds_read_b128 v[214:217], v234 offset:32768
	ds_read_b128 v[218:221], v234 offset:34816
	ds_read_b128 v[230:233], v234 offset:36864
	ds_read_b128 v[234:237], v234 offset:38912
	ds_read_b128 v[222:225], v239
	ds_read_b128 v[226:229], v239 offset:2048
	ds_read_b128 v[242:245], v239 offset:4096
	ds_read_b128 v[246:249], v239 offset:6144
	s_mov_b32 m0, s54
	v_lshl_add_u64 v[254:255], v[130:131], 0, s[12:13]
	global_load_lds_dwordx4 v[254:255], off
	s_add_i32 m0, s54, 0x2000
	v_lshl_add_u64 v[254:255], v[132:133], 0, s[12:13]
	global_load_lds_dwordx4 v[254:255], off
	s_waitcnt lgkmcnt(2)
	v_mfma_f32_16x16x32_bf16 v[60:63], v[214:217], v[222:225], v[60:63]
	v_add_u32_e32 v64, v64, v213
	v_add_u32_e32 v238, v238, v213
	v_mfma_f32_16x16x32_bf16 v[44:47], v[214:217], v[226:229], v[44:47]
	v_mfma_f32_16x16x32_bf16 v[56:59], v[218:221], v[222:225], v[56:59]
	v_mfma_f32_16x16x32_bf16 v[40:43], v[218:221], v[226:229], v[40:43]
	s_add_i32 m0, s54, 0x4000
	v_lshl_add_u64 v[254:255], v[134:135], 0, s[12:13]
	global_load_lds_dwordx4 v[254:255], off
	v_mfma_f32_16x16x32_bf16 v[52:55], v[230:233], v[222:225], v[52:55]
	v_mfma_f32_16x16x32_bf16 v[36:39], v[230:233], v[226:229], v[36:39]
	v_mfma_f32_16x16x32_bf16 v[48:51], v[234:237], v[222:225], v[48:51]
	v_mfma_f32_16x16x32_bf16 v[32:35], v[234:237], v[226:229], v[32:35]
	s_add_i32 m0, s54, 0x6000
	v_lshl_add_u64 v[254:255], v[136:137], 0, s[12:13]
	global_load_lds_dwordx4 v[254:255], off
	ds_read_b128 v[222:225], v238
	ds_read_b128 v[226:229], v238 offset:2048
	s_waitcnt lgkmcnt(2)
	v_mfma_f32_16x16x32_bf16 v[28:31], v[214:217], v[242:245], v[28:31]
	v_mfma_f32_16x16x32_bf16 v[12:15], v[214:217], v[246:249], v[12:15]
	ds_read_b128 v[214:217], v64 offset:32768
	v_mfma_f32_16x16x32_bf16 v[24:27], v[218:221], v[242:245], v[24:27]
	v_mfma_f32_16x16x32_bf16 v[8:11], v[218:221], v[246:249], v[8:11]
	s_add_i32 m0, s54, 0x8000
	v_lshl_add_u64 v[254:255], v[138:139], 0, s[12:13]
	global_load_lds_dwordx4 v[254:255], off
	ds_read_b128 v[218:221], v64 offset:34816
	v_mfma_f32_16x16x32_bf16 v[20:23], v[230:233], v[242:245], v[20:23]
	v_mfma_f32_16x16x32_bf16 v[4:7], v[230:233], v[246:249], v[4:7]
	ds_read_b128 v[230:233], v64 offset:36864
	v_mfma_f32_16x16x32_bf16 v[16:19], v[234:237], v[242:245], v[16:19]
	v_mfma_f32_16x16x32_bf16 v[0:3], v[234:237], v[246:249], v[0:3]
	s_add_i32 m0, s54, 0xa000
	v_lshl_add_u64 v[254:255], v[140:141], 0, s[12:13]
	global_load_lds_dwordx4 v[254:255], off
	s_add_u32 s12, s12, 0x80
	s_addc_u32 s13, s13, 0
	s_add_i32 s3, s3, 1
	s_cmpk_lg_i32 s12, 0x400
	ds_read_b128 v[234:237], v64 offset:38912
	ds_read_b128 v[242:245], v238 offset:4096
	ds_read_b128 v[246:249], v238 offset:6144
	s_waitcnt lgkmcnt(2)
	v_mfma_f32_16x16x32_bf16 v[60:63], v[214:217], v[222:225], v[60:63]
	v_mfma_f32_16x16x32_bf16 v[44:47], v[214:217], v[226:229], v[44:47]
	v_mfma_f32_16x16x32_bf16 v[56:59], v[218:221], v[222:225], v[56:59]
	v_mfma_f32_16x16x32_bf16 v[40:43], v[218:221], v[226:229], v[40:43]
	v_mfma_f32_16x16x32_bf16 v[52:55], v[230:233], v[222:225], v[52:55]
	v_mfma_f32_16x16x32_bf16 v[36:39], v[230:233], v[226:229], v[36:39]
	v_mfma_f32_16x16x32_bf16 v[48:51], v[234:237], v[222:225], v[48:51]
	v_mfma_f32_16x16x32_bf16 v[32:35], v[234:237], v[226:229], v[32:35]
	s_waitcnt vmcnt(0)
	s_waitcnt vmcnt(0) lgkmcnt(0)
	v_mfma_f32_16x16x32_bf16 v[28:31], v[214:217], v[242:245], v[28:31]
	s_barrier
	v_mfma_f32_16x16x32_bf16 v[12:15], v[214:217], v[246:249], v[12:15]
	v_mfma_f32_16x16x32_bf16 v[24:27], v[218:221], v[242:245], v[24:27]
	v_mfma_f32_16x16x32_bf16 v[8:11], v[218:221], v[246:249], v[8:11]
	v_mfma_f32_16x16x32_bf16 v[20:23], v[230:233], v[242:245], v[20:23]
	v_mfma_f32_16x16x32_bf16 v[4:7], v[230:233], v[246:249], v[4:7]
	v_mfma_f32_16x16x32_bf16 v[16:19], v[234:237], v[242:245], v[16:19]
	v_mfma_f32_16x16x32_bf16 v[0:3], v[234:237], v[246:249], v[0:3]
	s_cbranch_scc0 .LBB0_731

.LBB0_765:
	v_readfirstlane_b32 s18, v146
	s_xor_b32 m0, s34, 1
	s_lshl_b32 m0, m0, 16
	s_add_i32 s18, s18, m0
	v_add3_u32 v128, s31, v147, v148
	v_add_u32_e32 v172, v128, v150
	v_add3_u32 v176, s31, v149, v148
	v_add_u32_e32 v177, v176, v150
	ds_read_b128 v[152:155], v172 offset:32768
	ds_read_b128 v[156:159], v172 offset:34816
	ds_read_b128 v[168:171], v172 offset:36864
	ds_read_b128 v[172:175], v172 offset:38912
	ds_read_b128 v[160:163], v177
	ds_read_b128 v[164:167], v177 offset:2048
	ds_read_b128 v[242:245], v177 offset:4096
	ds_read_b128 v[246:249], v177 offset:6144
	s_mov_b32 m0, s18
	v_lshl_add_u64 v[254:255], v[130:131], 0, s[16:17]
	global_load_lds_dwordx4 v[254:255], off
	s_add_i32 m0, s18, 0x2000
	v_lshl_add_u64 v[254:255], v[132:133], 0, s[16:17]
	global_load_lds_dwordx4 v[254:255], off
	s_waitcnt lgkmcnt(2)
	v_mfma_f32_16x16x32_bf16 v[124:127], v[152:155], v[160:163], v[124:127]
	v_add_u32_e32 v128, v128, v151
	v_add_u32_e32 v176, v176, v151
	v_mfma_f32_16x16x32_bf16 v[108:111], v[152:155], v[164:167], v[108:111]
	v_mfma_f32_16x16x32_bf16 v[120:123], v[156:159], v[160:163], v[120:123]
	v_mfma_f32_16x16x32_bf16 v[104:107], v[156:159], v[164:167], v[104:107]
	s_add_i32 m0, s18, 0x4000
	v_lshl_add_u64 v[254:255], v[134:135], 0, s[16:17]
	global_load_lds_dwordx4 v[254:255], off
	v_mfma_f32_16x16x32_bf16 v[116:119], v[168:171], v[160:163], v[116:119]
	v_mfma_f32_16x16x32_bf16 v[100:103], v[168:171], v[164:167], v[100:103]
	v_mfma_f32_16x16x32_bf16 v[112:115], v[172:175], v[160:163], v[112:115]
	v_mfma_f32_16x16x32_bf16 v[96:99], v[172:175], v[164:167], v[96:99]
	s_add_i32 m0, s18, 0x6000
	v_lshl_add_u64 v[254:255], v[136:137], 0, s[16:17]
	global_load_lds_dwordx4 v[254:255], off
	ds_read_b128 v[160:163], v177 offset:8192
	ds_read_b128 v[164:167], v177 offset:10240
	s_waitcnt lgkmcnt(2)
	v_mfma_f32_16x16x32_bf16 v[92:95], v[152:155], v[242:245], v[92:95]
	v_mfma_f32_16x16x32_bf16 v[76:79], v[152:155], v[246:249], v[76:79]
	v_mfma_f32_16x16x32_bf16 v[88:91], v[156:159], v[242:245], v[88:91]
	v_mfma_f32_16x16x32_bf16 v[72:75], v[156:159], v[246:249], v[72:75]
	s_add_i32 m0, s18, 0x8000
	v_lshl_add_u64 v[254:255], v[138:139], 0, s[16:17]
	global_load_lds_dwordx4 v[254:255], off
	v_mfma_f32_16x16x32_bf16 v[84:87], v[168:171], v[242:245], v[84:87]
	v_mfma_f32_16x16x32_bf16 v[68:71], v[168:171], v[246:249], v[68:71]
	v_mfma_f32_16x16x32_bf16 v[80:83], v[172:175], v[242:245], v[80:83]
	v_mfma_f32_16x16x32_bf16 v[64:67], v[172:175], v[246:249], v[64:67]
	s_add_i32 m0, s18, 0xa000
	v_lshl_add_u64 v[254:255], v[140:141], 0, s[16:17]
	global_load_lds_dwordx4 v[254:255], off
	ds_read_b128 v[242:245], v177 offset:12288
	ds_read_b128 v[246:249], v177 offset:14336
	s_waitcnt lgkmcnt(2)
	v_mfma_f32_16x16x32_bf16 v[60:63], v[152:155], v[160:163], v[60:63]
	v_mfma_f32_16x16x32_bf16 v[44:47], v[152:155], v[164:167], v[44:47]
	v_mfma_f32_16x16x32_bf16 v[56:59], v[156:159], v[160:163], v[56:59]
	v_mfma_f32_16x16x32_bf16 v[40:43], v[156:159], v[164:167], v[40:43]
	s_add_i32 m0, s18, 0xc000
	v_lshl_add_u64 v[254:255], v[142:143], 0, s[16:17]
	global_load_lds_dwordx4 v[254:255], off
	v_mfma_f32_16x16x32_bf16 v[52:55], v[168:171], v[160:163], v[52:55]
	v_mfma_f32_16x16x32_bf16 v[36:39], v[168:171], v[164:167], v[36:39]
	v_mfma_f32_16x16x32_bf16 v[48:51], v[172:175], v[160:163], v[48:51]
	v_mfma_f32_16x16x32_bf16 v[32:35], v[172:175], v[164:167], v[32:35]
	s_add_i32 m0, s18, 0xe000
	v_lshl_add_u64 v[254:255], v[144:145], 0, s[16:17]
	global_load_lds_dwordx4 v[254:255], off
	s_add_u32 s16, s16, 0x80
	s_addc_u32 s17, s17, 0
	s_add_i32 s15, s15, 1
	s_cmpk_lg_i32 s16, 0x800
	ds_read_b128 v[160:163], v176
	ds_read_b128 v[164:167], v176 offset:2048
	s_waitcnt lgkmcnt(2)
	v_mfma_f32_16x16x32_bf16 v[28:31], v[152:155], v[242:245], v[28:31]
	v_mfma_f32_16x16x32_bf16 v[8:11], v[152:155], v[246:249], v[8:11]
	ds_read_b128 v[152:155], v128 offset:32768
	v_mfma_f32_16x16x32_bf16 v[20:23], v[156:159], v[242:245], v[20:23]
	v_mfma_f32_16x16x32_bf16 v[4:7], v[156:159], v[246:249], v[4:7]
	ds_read_b128 v[156:159], v128 offset:34816
	v_mfma_f32_16x16x32_bf16 v[16:19], v[168:171], v[242:245], v[16:19]
	v_mfma_f32_16x16x32_bf16 v[0:3], v[168:171], v[246:249], v[0:3]
	ds_read_b128 v[168:171], v128 offset:36864
	v_mfma_f32_16x16x32_bf16 v[12:15], v[172:175], v[242:245], v[12:15]
	v_mfma_f32_16x16x32_bf16 v[24:27], v[172:175], v[246:249], v[24:27]
	ds_read_b128 v[172:175], v128 offset:38912
	ds_read_b128 v[242:245], v176 offset:4096
	ds_read_b128 v[246:249], v176 offset:6144
	s_waitcnt lgkmcnt(2)
	v_mfma_f32_16x16x32_bf16 v[124:127], v[152:155], v[160:163], v[124:127]
	v_mfma_f32_16x16x32_bf16 v[108:111], v[152:155], v[164:167], v[108:111]
	v_mfma_f32_16x16x32_bf16 v[120:123], v[156:159], v[160:163], v[120:123]
	v_mfma_f32_16x16x32_bf16 v[104:107], v[156:159], v[164:167], v[104:107]
	v_mfma_f32_16x16x32_bf16 v[116:119], v[168:171], v[160:163], v[116:119]
	v_mfma_f32_16x16x32_bf16 v[100:103], v[168:171], v[164:167], v[100:103]
	v_mfma_f32_16x16x32_bf16 v[112:115], v[172:175], v[160:163], v[112:115]
	v_mfma_f32_16x16x32_bf16 v[96:99], v[172:175], v[164:167], v[96:99]
	ds_read_b128 v[160:163], v176 offset:8192
	ds_read_b128 v[164:167], v176 offset:10240
	s_waitcnt lgkmcnt(2)
	v_mfma_f32_16x16x32_bf16 v[92:95], v[152:155], v[242:245], v[92:95]
	v_mfma_f32_16x16x32_bf16 v[76:79], v[152:155], v[246:249], v[76:79]
	v_mfma_f32_16x16x32_bf16 v[88:91], v[156:159], v[242:245], v[88:91]
	v_mfma_f32_16x16x32_bf16 v[72:75], v[156:159], v[246:249], v[72:75]
	v_mfma_f32_16x16x32_bf16 v[84:87], v[168:171], v[242:245], v[84:87]
	v_mfma_f32_16x16x32_bf16 v[68:71], v[168:171], v[246:249], v[68:71]
	v_mfma_f32_16x16x32_bf16 v[80:83], v[172:175], v[242:245], v[80:83]
	v_mfma_f32_16x16x32_bf16 v[64:67], v[172:175], v[246:249], v[64:67]
	ds_read_b128 v[242:245], v176 offset:12288
	ds_read_b128 v[246:249], v176 offset:14336
	s_waitcnt lgkmcnt(2)
	v_mfma_f32_16x16x32_bf16 v[60:63], v[152:155], v[160:163], v[60:63]
	v_mfma_f32_16x16x32_bf16 v[44:47], v[152:155], v[164:167], v[44:47]
	v_mfma_f32_16x16x32_bf16 v[56:59], v[156:159], v[160:163], v[56:59]
	v_mfma_f32_16x16x32_bf16 v[40:43], v[156:159], v[164:167], v[40:43]
	v_mfma_f32_16x16x32_bf16 v[52:55], v[168:171], v[160:163], v[52:55]
	v_mfma_f32_16x16x32_bf16 v[36:39], v[168:171], v[164:167], v[36:39]
	v_mfma_f32_16x16x32_bf16 v[48:51], v[172:175], v[160:163], v[48:51]
	v_mfma_f32_16x16x32_bf16 v[32:35], v[172:175], v[164:167], v[32:35]
	s_waitcnt vmcnt(0)
	s_waitcnt vmcnt(0) lgkmcnt(0)
	v_mfma_f32_16x16x32_bf16 v[28:31], v[152:155], v[242:245], v[28:31]
	s_barrier
	v_mfma_f32_16x16x32_bf16 v[8:11], v[152:155], v[246:249], v[8:11]
	v_mfma_f32_16x16x32_bf16 v[20:23], v[156:159], v[242:245], v[20:23]
	v_mfma_f32_16x16x32_bf16 v[4:7], v[156:159], v[246:249], v[4:7]
	v_mfma_f32_16x16x32_bf16 v[16:19], v[168:171], v[242:245], v[16:19]
	v_mfma_f32_16x16x32_bf16 v[0:3], v[168:171], v[246:249], v[0:3]
	v_mfma_f32_16x16x32_bf16 v[12:15], v[172:175], v[242:245], v[12:15]
	v_mfma_f32_16x16x32_bf16 v[24:27], v[172:175], v[246:249], v[24:27]
	s_cbranch_scc0 .LBB0_762
.LBB0_766:
	s_and_b32 s34, s15, 1
	s_lshl_b32 s31, s34, 16
	s_branch .LBB0_765
.LBB0_770:
	v_lshrrev_b32_e32 v131, 2, v198
	v_and_b32_e32 v130, 0xc0, v198
	v_and_b32_e32 v131, 12, v131
	v_or3_b32 v146, v130, v131, s14
	v_ashrrev_i32_e32 v130, 1, v198
	v_and_b32_e32 v130, 0xffffff80, v130
	v_lshl_add_u32 v134, s30, 8, v130
	v_and_or_b32 v132, v198, 15, v134
	v_ashrrev_i32_e32 v128, 13, v134
	v_mul_i32_i24_e32 v134, 0xc00, v128
	v_ashrrev_i32_e32 v133, 31, v132
	v_ashrrev_i32_e32 v135, 31, v134
	v_ashrrev_i32_e32 v147, 31, v146
	v_lshlrev_b64 v[130:131], 12, v[132:133]
	v_lshl_add_u64 v[134:135], v[134:135], 2, s[6:7]
	v_lshl_add_u64 v[134:135], v[134:135], 0, s[12:13]
	v_lshlrev_b64 v[136:137], 2, v[146:147]
	v_lshl_add_u64 v[148:149], v[134:135], 0, v[136:137]
	v_lshl_add_u64 v[150:151], s[2:3], 0, v[130:131]
	v_lshl_add_u64 v[150:151], v[150:151], 0, v[136:137]
	v_lshl_add_u64 v[154:155], s[4:5], 0, v[130:131]
	v_lshl_add_u64 v[154:155], v[154:155], 0, v[136:137]
	global_load_dwordx4 v[138:141], v[148:149], off
	global_load_dwordx4 v[142:145], v[148:149], off offset:64
	global_load_dwordx4 v[156:159], v[148:149], off offset:128
	global_load_dwordx4 v[160:163], v[148:149], off offset:192
	global_load_dwordx4 v[164:167], v[150:151], off
	global_load_dwordx4 v[168:171], v[150:151], off offset:64
	global_load_dwordx4 v[172:175], v[150:151], off offset:128
	global_load_dwordx4 v[242:245], v[150:151], off offset:192
	v_add_co_u32_e32 v150, vcc, 0x10000, v150
	s_nop 1
	v_addc_co_u32_e32 v151, vcc, 0, v151, vcc
	global_load_dwordx4 v[246:249], v[150:151], off
	global_load_dwordx4 v[250:253], v[150:151], off offset:64
	s_waitcnt vmcnt(5)
	v_pk_fma_f32 v[126:127], v[126:127], v[140:141], v[166:167]
	v_pk_fma_f32 v[124:125], v[124:125], v[138:139], v[164:165]
	global_store_dwordx4 v[154:155], v[124:127], off
	global_load_dwordx4 v[164:167], v[150:151], off offset:128
	s_waitcnt vmcnt(6)
	v_pk_fma_f32 v[122:123], v[122:123], v[144:145], v[170:171]
	v_pk_fma_f32 v[120:121], v[120:121], v[142:143], v[168:169]
	global_store_dwordx4 v[154:155], v[120:123], off offset:64
	global_load_dwordx4 v[168:171], v[150:151], off offset:192
	v_add_co_u32_e32 v150, vcc, 0x10000, v150
	s_nop 1
	v_addc_co_u32_e32 v151, vcc, 0, v151, vcc
	s_waitcnt vmcnt(7)
	v_pk_fma_f32 v[118:119], v[118:119], v[158:159], v[174:175]
	v_pk_fma_f32 v[116:117], v[116:117], v[156:157], v[172:173]
	global_store_dwordx4 v[154:155], v[116:119], off offset:128
	global_load_dwordx4 v[172:175], v[150:151], off
	s_waitcnt vmcnt(8)
	v_pk_fma_f32 v[114:115], v[114:115], v[162:163], v[244:245]
	v_pk_fma_f32 v[112:113], v[112:113], v[160:161], v[242:243]
	global_store_dwordx4 v[154:155], v[112:115], off offset:192
	s_nop 0
	v_add_co_u32_e32 v154, vcc, 0x10000, v154
	s_nop 1
	v_addc_co_u32_e32 v155, vcc, 0, v155, vcc
	global_load_dwordx4 v[242:245], v[150:151], off offset:64
	s_waitcnt vmcnt(9)
	v_pk_fma_f32 v[110:111], v[110:111], v[140:141], v[248:249]
	v_pk_fma_f32 v[108:109], v[108:109], v[138:139], v[246:247]
	global_store_dwordx4 v[154:155], v[108:111], off
	global_load_dwordx4 v[246:249], v[150:151], off offset:128
	s_waitcnt vmcnt(10)
	v_pk_fma_f32 v[106:107], v[106:107], v[144:145], v[252:253]
	v_pk_fma_f32 v[104:105], v[104:105], v[142:143], v[250:251]
	global_store_dwordx4 v[154:155], v[104:107], off offset:64
	global_load_dwordx4 v[250:253], v[150:151], off offset:192
	v_add_co_u32_e32 v150, vcc, 0x10000, v150
	s_nop 1
	v_addc_co_u32_e32 v151, vcc, 0, v151, vcc
	s_waitcnt vmcnt(10)
	v_pk_fma_f32 v[102:103], v[102:103], v[158:159], v[166:167]
	v_pk_fma_f32 v[100:101], v[100:101], v[156:157], v[164:165]
	global_store_dwordx4 v[154:155], v[100:103], off offset:128
	global_load_dwordx4 v[164:167], v[150:151], off
	s_waitcnt vmcnt(10)
	v_pk_fma_f32 v[98:99], v[98:99], v[162:163], v[170:171]
	v_pk_fma_f32 v[96:97], v[96:97], v[160:161], v[168:169]
	global_store_dwordx4 v[154:155], v[96:99], off offset:192
	s_nop 0
	v_add_co_u32_e32 v154, vcc, 0x10000, v154
	s_nop 1
	v_addc_co_u32_e32 v155, vcc, 0, v155, vcc
	global_load_dwordx4 v[168:171], v[150:151], off offset:64
	s_waitcnt vmcnt(10)
	v_pk_fma_f32 v[94:95], v[94:95], v[140:141], v[174:175]
	v_pk_fma_f32 v[92:93], v[92:93], v[138:139], v[172:173]
	global_store_dwordx4 v[154:155], v[92:95], off
	global_load_dwordx4 v[172:175], v[150:151], off offset:128
	s_waitcnt vmcnt(10)
	v_pk_fma_f32 v[90:91], v[90:91], v[144:145], v[244:245]
	v_pk_fma_f32 v[88:89], v[88:89], v[142:143], v[242:243]
	global_store_dwordx4 v[154:155], v[88:91], off offset:64
	global_load_dwordx4 v[242:245], v[150:151], off offset:192
	v_add_co_u32_e32 v150, vcc, 0x10000, v150
	s_nop 1
	v_addc_co_u32_e32 v151, vcc, 0, v151, vcc
	s_waitcnt vmcnt(10)
	v_pk_fma_f32 v[86:87], v[86:87], v[158:159], v[248:249]
	v_pk_fma_f32 v[84:85], v[84:85], v[156:157], v[246:247]
	global_store_dwordx4 v[154:155], v[84:87], off offset:128
	global_load_dwordx4 v[246:249], v[150:151], off
	s_waitcnt vmcnt(10)
	v_pk_fma_f32 v[82:83], v[82:83], v[162:163], v[252:253]
	v_pk_fma_f32 v[80:81], v[80:81], v[160:161], v[250:251]
	global_store_dwordx4 v[154:155], v[80:83], off offset:192
	s_nop 0
	v_add_co_u32_e32 v154, vcc, 0x10000, v154
	s_nop 1
	v_addc_co_u32_e32 v155, vcc, 0, v155, vcc
	global_load_dwordx4 v[250:253], v[150:151], off offset:64
	s_waitcnt vmcnt(10)
	v_pk_fma_f32 v[78:79], v[78:79], v[140:141], v[166:167]
	v_pk_fma_f32 v[76:77], v[76:77], v[138:139], v[164:165]
	global_store_dwordx4 v[154:155], v[76:79], off
	global_load_dwordx4 v[164:167], v[150:151], off offset:128
	s_waitcnt vmcnt(10)
	v_pk_fma_f32 v[74:75], v[74:75], v[144:145], v[170:171]
	v_pk_fma_f32 v[72:73], v[72:73], v[142:143], v[168:169]
	global_store_dwordx4 v[154:155], v[72:75], off offset:64
	global_load_dwordx4 v[168:171], v[150:151], off offset:192
	v_add_co_u32_e32 v150, vcc, 0x10000, v150
	s_nop 1
	v_addc_co_u32_e32 v151, vcc, 0, v151, vcc
	s_waitcnt vmcnt(10)
	v_pk_fma_f32 v[70:71], v[70:71], v[158:159], v[174:175]
	v_pk_fma_f32 v[68:69], v[68:69], v[156:157], v[172:173]
	global_store_dwordx4 v[154:155], v[68:71], off offset:128
	global_load_dwordx4 v[172:175], v[150:151], off
	s_waitcnt vmcnt(10)
	v_pk_fma_f32 v[66:67], v[66:67], v[162:163], v[244:245]
	v_pk_fma_f32 v[64:65], v[64:65], v[160:161], v[242:243]
	global_store_dwordx4 v[154:155], v[64:67], off offset:192
	s_nop 0
	v_add_co_u32_e32 v154, vcc, 0x10000, v154
	s_nop 1
	v_addc_co_u32_e32 v155, vcc, 0, v155, vcc
	global_load_dwordx4 v[242:245], v[150:151], off offset:64
	s_waitcnt vmcnt(10)
	v_pk_fma_f32 v[62:63], v[62:63], v[140:141], v[248:249]
	v_pk_fma_f32 v[60:61], v[60:61], v[138:139], v[246:247]
	global_store_dwordx4 v[154:155], v[60:63], off
	global_load_dwordx4 v[246:249], v[150:151], off offset:128
	s_waitcnt vmcnt(10)
	v_pk_fma_f32 v[58:59], v[58:59], v[144:145], v[252:253]
	v_pk_fma_f32 v[56:57], v[56:57], v[142:143], v[250:251]
	global_store_dwordx4 v[154:155], v[56:59], off offset:64
	global_load_dwordx4 v[250:253], v[150:151], off offset:192
	v_add_co_u32_e32 v150, vcc, 0x10000, v150
	s_nop 1
	v_addc_co_u32_e32 v151, vcc, 0, v151, vcc
	s_waitcnt vmcnt(10)
	v_pk_fma_f32 v[54:55], v[54:55], v[158:159], v[166:167]
	v_pk_fma_f32 v[52:53], v[52:53], v[156:157], v[164:165]
	global_store_dwordx4 v[154:155], v[52:55], off offset:128
	global_load_dwordx4 v[164:167], v[150:151], off
	s_waitcnt vmcnt(10)
	v_pk_fma_f32 v[50:51], v[50:51], v[162:163], v[170:171]
	v_pk_fma_f32 v[48:49], v[48:49], v[160:161], v[168:169]
	global_store_dwordx4 v[154:155], v[48:51], off offset:192
	s_nop 0
	v_add_co_u32_e32 v154, vcc, 0x10000, v154
	s_nop 1
	v_addc_co_u32_e32 v155, vcc, 0, v155, vcc
	global_load_dwordx4 v[168:171], v[150:151], off offset:64
	s_waitcnt vmcnt(10)
	v_pk_fma_f32 v[46:47], v[46:47], v[140:141], v[174:175]
	v_pk_fma_f32 v[44:45], v[44:45], v[138:139], v[172:173]
	global_store_dwordx4 v[154:155], v[44:47], off
	global_load_dwordx4 v[172:175], v[150:151], off offset:128
	s_waitcnt vmcnt(10)
	v_pk_fma_f32 v[42:43], v[42:43], v[144:145], v[244:245]
	v_pk_fma_f32 v[40:41], v[40:41], v[142:143], v[242:243]
	global_store_dwordx4 v[154:155], v[40:43], off offset:64
	global_load_dwordx4 v[242:245], v[150:151], off offset:192
	v_add_co_u32_e32 v150, vcc, 0x10000, v150
	s_nop 1
	v_addc_co_u32_e32 v151, vcc, 0, v151, vcc
	s_waitcnt vmcnt(10)
	v_pk_fma_f32 v[38:39], v[38:39], v[158:159], v[248:249]
	v_pk_fma_f32 v[36:37], v[36:37], v[156:157], v[246:247]
	global_store_dwordx4 v[154:155], v[36:39], off offset:128
	global_load_dwordx4 v[246:249], v[150:151], off
	s_waitcnt vmcnt(10)
	v_pk_fma_f32 v[34:35], v[34:35], v[162:163], v[252:253]
	v_pk_fma_f32 v[32:33], v[32:33], v[160:161], v[250:251]
	global_store_dwordx4 v[154:155], v[32:35], off offset:192
	s_nop 0
	v_add_co_u32_e32 v154, vcc, 0x10000, v154
	s_nop 1
	v_addc_co_u32_e32 v155, vcc, 0, v155, vcc
	global_load_dwordx4 v[250:253], v[150:151], off offset:64
	s_waitcnt vmcnt(10)
	v_pk_fma_f32 v[30:31], v[30:31], v[140:141], v[166:167]
	v_pk_fma_f32 v[28:29], v[28:29], v[138:139], v[164:165]
	global_store_dwordx4 v[154:155], v[28:31], off
	global_load_dwordx4 v[164:167], v[150:151], off offset:128
	s_waitcnt vmcnt(10)
	v_pk_fma_f32 v[22:23], v[22:23], v[144:145], v[170:171]
	v_pk_fma_f32 v[20:21], v[20:21], v[142:143], v[168:169]
	global_store_dwordx4 v[154:155], v[20:23], off offset:64
	global_load_dwordx4 v[168:171], v[150:151], off offset:192
	s_waitcnt vmcnt(10)
	v_pk_fma_f32 v[18:19], v[18:19], v[158:159], v[174:175]
	v_pk_fma_f32 v[16:17], v[16:17], v[156:157], v[172:173]
	global_store_dwordx4 v[154:155], v[16:19], off offset:128
	s_waitcnt vmcnt(9)
	v_pk_fma_f32 v[14:15], v[14:15], v[162:163], v[244:245]
	v_pk_fma_f32 v[12:13], v[12:13], v[160:161], v[242:243]
	global_store_dwordx4 v[154:155], v[12:15], off offset:192
	s_nop 0
	v_add_co_u32_e32 v154, vcc, 0x10000, v154
	s_nop 1
	v_addc_co_u32_e32 v155, vcc, 0, v155, vcc
	s_waitcnt vmcnt(8)
	v_pk_fma_f32 v[10:11], v[10:11], v[140:141], v[248:249]
	v_pk_fma_f32 v[8:9], v[8:9], v[138:139], v[246:247]
	global_store_dwordx4 v[154:155], v[8:11], off
	s_waitcnt vmcnt(7)
	v_pk_fma_f32 v[6:7], v[6:7], v[144:145], v[252:253]
	v_pk_fma_f32 v[4:5], v[4:5], v[142:143], v[250:251]
	global_store_dwordx4 v[154:155], v[4:7], off offset:64
	s_waitcnt vmcnt(6)
	v_pk_fma_f32 v[2:3], v[2:3], v[158:159], v[166:167]
	v_pk_fma_f32 v[0:1], v[0:1], v[156:157], v[164:165]
	global_store_dwordx4 v[154:155], v[0:3], off offset:128
	s_waitcnt vmcnt(5)
	v_pk_fma_f32 v[26:27], v[26:27], v[162:163], v[170:171]
	v_pk_fma_f32 v[24:25], v[24:25], v[160:161], v[168:169]
	global_store_dwordx4 v[154:155], v[24:27], off offset:192
	s_branch .LBB0_763

.LBB0_1155:
	v_readfirstlane_b32 s6, v150
	s_xor_b32 m0, s76, 1
	s_lshl_b32 m0, m0, 16
	s_add_i32 s6, s6, m0
	v_add3_u32 v168, s75, v151, v152
	v_add_u32_e32 v170, v168, v154
	v_add3_u32 v186, s75, v153, v152
	v_add_u32_e32 v187, v186, v154
	ds_read_b128 v[128:131], v170 offset:32768
	ds_read_b128 v[160:163], v170 offset:34816
	ds_read_b128 v[164:167], v170 offset:36864
	ds_read_b128 v[170:173], v170 offset:38912
	ds_read_b128 v[156:159], v187
	ds_read_b128 v[250:253], v187 offset:2048
	ds_read_b128 v[242:245], v187 offset:4096
	ds_read_b128 v[246:249], v187 offset:6144
	s_mov_b32 m0, s6
	v_lshl_add_u64 v[254:255], v[132:133], 0, s[2:3]
	global_load_lds_dwordx4 v[254:255], off
	s_add_i32 m0, s6, 0x2000
	v_lshl_add_u64 v[254:255], v[134:135], 0, s[2:3]
	global_load_lds_dwordx4 v[254:255], off
	s_waitcnt lgkmcnt(2)
	v_mfma_f32_16x16x32_bf16 v[124:127], v[128:131], v[156:159], v[124:127]
	v_add_u32_e32 v241, v168, v155
	v_add_u32_e32 v168, v186, v155
	v_mfma_f32_16x16x32_bf16 v[108:111], v[128:131], v[250:253], v[108:111]
	v_mfma_f32_16x16x32_bf16 v[120:123], v[160:163], v[156:159], v[120:123]
	v_mfma_f32_16x16x32_bf16 v[104:107], v[160:163], v[250:253], v[104:107]
	s_add_i32 m0, s6, 0x4000
	v_lshl_add_u64 v[254:255], v[136:137], 0, s[2:3]
	global_load_lds_dwordx4 v[254:255], off
	v_mfma_f32_16x16x32_bf16 v[116:119], v[164:167], v[156:159], v[116:119]
	v_mfma_f32_16x16x32_bf16 v[100:103], v[164:167], v[250:253], v[100:103]
	v_mfma_f32_16x16x32_bf16 v[112:115], v[170:173], v[156:159], v[112:115]
	v_mfma_f32_16x16x32_bf16 v[96:99], v[170:173], v[250:253], v[96:99]
	s_add_i32 m0, s6, 0x6000
	v_lshl_add_u64 v[254:255], v[138:139], 0, s[2:3]
	global_load_lds_dwordx4 v[254:255], off
	ds_read_b128 v[156:159], v187 offset:8192
	ds_read_b128 v[250:253], v187 offset:10240
	s_waitcnt lgkmcnt(2)
	v_mfma_f32_16x16x32_bf16 v[92:95], v[128:131], v[242:245], v[92:95]
	v_mfma_f32_16x16x32_bf16 v[76:79], v[128:131], v[246:249], v[76:79]
	v_mfma_f32_16x16x32_bf16 v[88:91], v[160:163], v[242:245], v[88:91]
	v_mfma_f32_16x16x32_bf16 v[72:75], v[160:163], v[246:249], v[72:75]
	s_add_i32 m0, s6, 0x8000
	v_lshl_add_u64 v[254:255], v[140:141], 0, s[2:3]
	global_load_lds_dwordx4 v[254:255], off
	v_mfma_f32_16x16x32_bf16 v[84:87], v[164:167], v[242:245], v[84:87]
	v_mfma_f32_16x16x32_bf16 v[68:71], v[164:167], v[246:249], v[68:71]
	v_mfma_f32_16x16x32_bf16 v[80:83], v[170:173], v[242:245], v[80:83]
	v_mfma_f32_16x16x32_bf16 v[64:67], v[170:173], v[246:249], v[64:67]
	s_add_i32 m0, s6, 0xa000
	v_lshl_add_u64 v[254:255], v[142:143], 0, s[2:3]
	global_load_lds_dwordx4 v[254:255], off
	ds_read_b128 v[242:245], v187 offset:12288
	ds_read_b128 v[246:249], v187 offset:14336
	s_waitcnt lgkmcnt(2)
	v_mfma_f32_16x16x32_bf16 v[60:63], v[128:131], v[156:159], v[60:63]
	v_mfma_f32_16x16x32_bf16 v[44:47], v[128:131], v[250:253], v[44:47]
	v_mfma_f32_16x16x32_bf16 v[56:59], v[160:163], v[156:159], v[56:59]
	v_mfma_f32_16x16x32_bf16 v[40:43], v[160:163], v[250:253], v[40:43]
	s_add_i32 m0, s6, 0xc000
	v_lshl_add_u64 v[254:255], v[144:145], 0, s[2:3]
	global_load_lds_dwordx4 v[254:255], off
	v_mfma_f32_16x16x32_bf16 v[52:55], v[164:167], v[156:159], v[52:55]
	v_mfma_f32_16x16x32_bf16 v[36:39], v[164:167], v[250:253], v[36:39]
	v_mfma_f32_16x16x32_bf16 v[48:51], v[170:173], v[156:159], v[48:51]
	v_mfma_f32_16x16x32_bf16 v[32:35], v[170:173], v[250:253], v[32:35]
	s_add_i32 m0, s6, 0xe000
	v_lshl_add_u64 v[254:255], v[146:147], 0, s[2:3]
	global_load_lds_dwordx4 v[254:255], off
	s_add_u32 s2, s2, 0x80
	s_addc_u32 s3, s3, 0
	s_add_i32 s74, s74, 1
	s_cmpk_lg_i32 s2, 0x200
	ds_read_b128 v[156:159], v168
	ds_read_b128 v[250:253], v168 offset:2048
	s_waitcnt lgkmcnt(2)
	v_mfma_f32_16x16x32_bf16 v[28:31], v[128:131], v[242:245], v[28:31]
	v_mfma_f32_16x16x32_bf16 v[12:15], v[128:131], v[246:249], v[12:15]
	ds_read_b128 v[128:131], v241 offset:32768
	v_mfma_f32_16x16x32_bf16 v[24:27], v[160:163], v[242:245], v[24:27]
	v_mfma_f32_16x16x32_bf16 v[8:11], v[160:163], v[246:249], v[8:11]
	ds_read_b128 v[160:163], v241 offset:34816
	v_mfma_f32_16x16x32_bf16 v[20:23], v[164:167], v[242:245], v[20:23]
	v_mfma_f32_16x16x32_bf16 v[0:3], v[164:167], v[246:249], v[0:3]
	ds_read_b128 v[164:167], v241 offset:36864
	v_mfma_f32_16x16x32_bf16 v[16:19], v[170:173], v[242:245], v[16:19]
	v_mfma_f32_16x16x32_bf16 v[4:7], v[170:173], v[246:249], v[4:7]
	ds_read_b128 v[170:173], v241 offset:38912
	ds_read_b128 v[242:245], v168 offset:4096
	ds_read_b128 v[246:249], v168 offset:6144
	s_waitcnt lgkmcnt(2)
	v_mfma_f32_16x16x32_bf16 v[124:127], v[128:131], v[156:159], v[124:127]
	v_mfma_f32_16x16x32_bf16 v[108:111], v[128:131], v[250:253], v[108:111]
	v_mfma_f32_16x16x32_bf16 v[120:123], v[160:163], v[156:159], v[120:123]
	v_mfma_f32_16x16x32_bf16 v[104:107], v[160:163], v[250:253], v[104:107]
	v_mfma_f32_16x16x32_bf16 v[116:119], v[164:167], v[156:159], v[116:119]
	v_mfma_f32_16x16x32_bf16 v[100:103], v[164:167], v[250:253], v[100:103]
	v_mfma_f32_16x16x32_bf16 v[112:115], v[170:173], v[156:159], v[112:115]
	v_mfma_f32_16x16x32_bf16 v[96:99], v[170:173], v[250:253], v[96:99]
	ds_read_b128 v[156:159], v168 offset:8192
	ds_read_b128 v[250:253], v168 offset:10240
	s_waitcnt lgkmcnt(2)
	v_mfma_f32_16x16x32_bf16 v[92:95], v[128:131], v[242:245], v[92:95]
	v_mfma_f32_16x16x32_bf16 v[76:79], v[128:131], v[246:249], v[76:79]
	v_mfma_f32_16x16x32_bf16 v[88:91], v[160:163], v[242:245], v[88:91]
	v_mfma_f32_16x16x32_bf16 v[72:75], v[160:163], v[246:249], v[72:75]
	v_mfma_f32_16x16x32_bf16 v[84:87], v[164:167], v[242:245], v[84:87]
	v_mfma_f32_16x16x32_bf16 v[68:71], v[164:167], v[246:249], v[68:71]
	v_mfma_f32_16x16x32_bf16 v[80:83], v[170:173], v[242:245], v[80:83]
	v_mfma_f32_16x16x32_bf16 v[64:67], v[170:173], v[246:249], v[64:67]
	ds_read_b128 v[242:245], v168 offset:12288
	ds_read_b128 v[246:249], v168 offset:14336
	s_waitcnt lgkmcnt(2)
	v_mfma_f32_16x16x32_bf16 v[60:63], v[128:131], v[156:159], v[60:63]
	v_mfma_f32_16x16x32_bf16 v[44:47], v[128:131], v[250:253], v[44:47]
	v_mfma_f32_16x16x32_bf16 v[56:59], v[160:163], v[156:159], v[56:59]
	v_mfma_f32_16x16x32_bf16 v[40:43], v[160:163], v[250:253], v[40:43]
	v_mfma_f32_16x16x32_bf16 v[52:55], v[164:167], v[156:159], v[52:55]
	v_mfma_f32_16x16x32_bf16 v[36:39], v[164:167], v[250:253], v[36:39]
	v_mfma_f32_16x16x32_bf16 v[48:51], v[170:173], v[156:159], v[48:51]
	v_mfma_f32_16x16x32_bf16 v[32:35], v[170:173], v[250:253], v[32:35]
	s_waitcnt vmcnt(0)
	s_waitcnt vmcnt(0) lgkmcnt(0)
	v_mfma_f32_16x16x32_bf16 v[28:31], v[128:131], v[242:245], v[28:31]
	s_barrier
	v_mfma_f32_16x16x32_bf16 v[12:15], v[128:131], v[246:249], v[12:15]
	v_mfma_f32_16x16x32_bf16 v[24:27], v[160:163], v[242:245], v[24:27]
	v_mfma_f32_16x16x32_bf16 v[8:11], v[160:163], v[246:249], v[8:11]
	v_mfma_f32_16x16x32_bf16 v[20:23], v[164:167], v[242:245], v[20:23]
	v_mfma_f32_16x16x32_bf16 v[0:3], v[164:167], v[246:249], v[0:3]
	v_mfma_f32_16x16x32_bf16 v[16:19], v[170:173], v[242:245], v[16:19]
	v_mfma_f32_16x16x32_bf16 v[4:7], v[170:173], v[246:249], v[4:7]
	s_cbranch_scc0 .LBB0_1160
.LBB0_1156:
	s_and_b32 s76, s74, 1
	s_lshl_b32 s75, s76, 16
	s_branch .LBB0_1155

.LBB0_1384:
	v_cmp_lt_i32_e32 vcc, 7, v0
	s_and_saveexec_b64 s[2:3], vcc
	s_xor_b64 s[86:87], exec, s[2:3]
	s_cbranch_execz .LBB0_1441
	v_cmp_lt_u32_e32 vcc, 15, v0
	s_and_saveexec_b64 s[2:3], vcc
	s_xor_b64 s[8:9], exec, s[2:3]
	s_cbranch_execz .LBB0_1421
	v_add_u32_e32 v2, -16, v0
	v_lshrrev_b32_e32 v2, 1, v2
	v_sub_u32_e32 v14, 31, v2
	v_mov_b32_e32 v18, v198
	v_lshlrev_b32_e32 v15, 8, v14
	v_readlane_b32 s4, v240, 36
	v_and_b32_e32 v12, 31, v18
	v_ashrrev_i32_e32 v2, 1, v18
	v_and_b32_e32 v19, 1, v0
	v_readlane_b32 s2, v240, 21
	v_and_b32_e32 v16, 0xffffffe0, v2
	v_or3_b32 v2, s4, v15, v12
	v_bitop3_b32 v4, v19, 7, s2 bitop3:0xc8
	v_add_u32_e32 v5, v2, v16
	v_mov_b64_e32 v[2:3], s[50:51]
	v_bfe_u32 v13, v18, 5, 1
	v_mad_i64_i32 v[156:157], s[2:3], v5, s61, v[2:3]
	v_lshlrev_b32_e32 v2, 7, v4
	v_mov_b32_e32 v3, v1
	v_lshl_add_u64 v[2:3], v[156:157], 0, v[2:3]
	v_lshlrev_b32_e32 v158, 4, v13
	v_mov_b32_e32 v159, v1
	v_lshl_add_u64 v[2:3], v[2:3], 0, v[158:159]
	s_mov_b64 s[2:3], 0x1000
	v_lshlrev_b32_e32 v0, 6, v4
	v_lshl_add_u64 v[4:5], v[2:3], 0, s[2:3]
	v_add_co_u32_e32 v2, vcc, s70, v2
	s_mov_b64 s[2:3], 0x1400
	s_nop 0
	v_addc_co_u32_e32 v3, vcc, 0, v3, vcc
	global_load_dwordx4 v[112:115], v[4:5], off offset:32
	global_load_dwordx4 v[116:119], v[4:5], off offset:64
	global_load_dwordx4 v[120:123], v[2:3], off
	global_load_dwordx4 v[124:127], v[4:5], off offset:96
	v_lshl_add_u64 v[2:3], v[156:157], 0, v[0:1]
	v_lshl_add_u64 v[2:3], v[2:3], 0, v[158:159]
	v_lshl_add_u64 v[4:5], v[2:3], 0, s[2:3]
	v_add_co_u32_e32 v2, vcc, s70, v2
	s_mov_b32 s2, 0x2aaaaaab
	s_nop 0
	v_addc_co_u32_e32 v3, vcc, 0, v3, vcc
	global_load_dwordx4 v[128:131], v[2:3], off offset:1024
	global_load_dwordx4 v[132:135], v[4:5], off offset:32
	v_mul_hi_i32 v2, v18, s2
	v_lshrrev_b32_e32 v3, 31, v2
	v_ashrrev_i32_e32 v2, 1, v2
	v_add_u32_e32 v17, v2, v3
	v_mul_lo_u32 v2, v17, 12
	v_sub_u32_e32 v2, v18, v2
	v_add_u32_e32 v160, s4, v17
	v_cmp_lt_i32_e64 s[2:3], 7, v2
	v_ashrrev_i32_e32 v161, 31, v160
	v_lshlrev_b32_e32 v162, 4, v2
	s_and_saveexec_b64 s[4:5], s[2:3]
	s_xor_b64 s[4:5], exec, s[4:5]
	v_mov_b64_e32 v[4:5], s[50:51]
	v_mad_i64_i32 v[4:5], s[6:7], v160, s61, v[4:5]
	v_mov_b32_e32 v163, v1
	v_lshl_add_u64 v[4:5], v[4:5], 0, v[162:163]
	v_lshl_add_u64 v[4:5], v[4:5], 0, s[84:85]
	s_or_saveexec_b64 s[4:5], s[4:5]
	v_lshlrev_b32_e32 v2, 3, v2
	v_lshlrev_b32_e32 v164, 1, v0
	v_ashrrev_i32_e32 v20, 31, v2
	s_xor_b64 exec, exec, s[4:5]
	v_lshlrev_b64 v[4:5], 10, v[160:161]
	v_lshl_add_u64 v[4:5], s[64:65], 0, v[4:5]
	v_mov_b32_e32 v165, v1
	v_lshl_add_u64 v[4:5], v[4:5], 0, v[164:165]
	v_mov_b32_e32 v3, v20
	v_lshl_add_u64 v[4:5], v[2:3], 1, v[4:5]
	s_or_b64 exec, exec, s[4:5]
	global_load_dwordx4 v[136:139], v[4:5], off
	v_add_u32_e32 v3, 0x200, v18
	s_mov_b32 s4, 0x2aaaaaab
	v_mul_hi_i32 v0, v3, s4
	v_lshrrev_b32_e32 v4, 31, v0
	v_ashrrev_i32_e32 v0, 1, v0
	v_add_u32_e32 v21, v0, v4
	v_mul_lo_u32 v0, v21, 12
	v_readlane_b32 s4, v240, 36
	v_sub_u32_e32 v0, v3, v0
	v_lshlrev_b32_e32 v168, 4, v0
	v_add_u32_e32 v166, s4, v21
	v_cmp_lt_i32_e64 s[4:5], 7, v0
	v_ashrrev_i32_e32 v167, 31, v166
	s_and_saveexec_b64 s[6:7], s[4:5]
	s_xor_b64 s[6:7], exec, s[6:7]
	v_mov_b64_e32 v[4:5], s[50:51]
	v_mad_i64_i32 v[4:5], s[10:11], v166, s61, v[4:5]
	v_mov_b32_e32 v169, v1
	v_lshl_add_u64 v[4:5], v[4:5], 0, v[168:169]
	v_lshl_add_u64 v[6:7], v[4:5], 0, s[84:85]
	s_or_saveexec_b64 s[6:7], s[6:7]
	v_lshlrev_b32_e32 v4, 3, v0
	v_ashrrev_i32_e32 v22, 31, v4
	s_xor_b64 exec, exec, s[6:7]
	v_lshlrev_b64 v[6:7], 10, v[166:167]
	v_lshl_add_u64 v[6:7], s[64:65], 0, v[6:7]
	v_mov_b32_e32 v165, v1
	v_lshl_add_u64 v[6:7], v[6:7], 0, v[164:165]
	v_mov_b32_e32 v5, v22
	v_lshl_add_u64 v[6:7], v[4:5], 1, v[6:7]
	s_or_b64 exec, exec, s[6:7]
	global_load_dwordx4 v[140:143], v[6:7], off
	v_add_u32_e32 v0, 0x400, v18
	s_mov_b32 s6, 0x2aaaaaab
	v_mul_hi_i32 v5, v0, s6
	v_lshrrev_b32_e32 v6, 31, v5
	v_ashrrev_i32_e32 v5, 1, v5
	v_add_u32_e32 v23, v5, v6
	v_mul_lo_u32 v5, v23, 12
	v_readlane_b32 s6, v240, 36
	v_sub_u32_e32 v5, v0, v5
	v_lshlrev_b32_e32 v0, 3, v5
	v_add_u32_e32 v170, s6, v23
	v_cmp_lt_i32_e64 s[6:7], 7, v5
	v_ashrrev_i32_e32 v171, 31, v170
	v_lshlrev_b32_e32 v172, 4, v5
	s_and_saveexec_b64 s[10:11], s[6:7]
	s_xor_b64 s[10:11], exec, s[10:11]
	v_mov_b64_e32 v[6:7], s[50:51]
	v_mad_i64_i32 v[6:7], s[12:13], v170, s61, v[6:7]
	v_mov_b32_e32 v173, v1
	v_lshl_add_u64 v[6:7], v[6:7], 0, v[172:173]
	v_lshl_add_u64 v[10:11], v[6:7], 0, s[84:85]
	v_mov_b64_e32 v[6:7], v[0:1]
	s_or_saveexec_b64 s[10:11], s[10:11]
	v_mov_b64_e32 v[8:9], v[6:7]
	s_xor_b64 exec, exec, s[10:11]
	v_lshlrev_b64 v[6:7], 10, v[170:171]
	v_lshl_add_u64 v[6:7], s[64:65], 0, v[6:7]
	v_mov_b32_e32 v165, v1
	v_lshl_add_u64 v[8:9], v[6:7], 0, v[164:165]
	v_ashrrev_i32_e32 v7, 31, v0
	v_mov_b32_e32 v6, v0
	v_lshl_add_u64 v[10:11], v[6:7], 1, v[8:9]
	v_mov_b64_e32 v[8:9], v[0:1]
	s_or_b64 exec, exec, s[10:11]
	v_readlane_b32 s10, v240, 21
	global_load_dwordx4 v[144:147], v[10:11], off
	v_ashrrev_i32_e32 v10, 4, v18
	v_or_b32_e32 v0, s10, v19
	v_readlane_b32 s10, v240, 47
	v_lshlrev_b32_e32 v0, 20, v0
	v_readlane_b32 s11, v240, 48
	v_ashrrev_i32_e32 v11, 31, v10
	v_lshlrev_b64 v[26:27], 14, v[10:11]
	v_lshl_add_u64 v[24:25], s[10:11], 0, v[0:1]
	v_lshlrev_b32_e32 v0, 3, v18
	v_and_b32_e32 v163, 0x78, v0
	v_ashrrev_i32_e32 v18, 4, v3
	v_lshl_add_u64 v[26:27], v[24:25], 0, v[26:27]
	v_lshlrev_b32_e32 v0, 1, v163
	v_and_b32_e32 v238, 8, v163
	v_lshrrev_b32_e32 v238, 1, v238
	v_and_b32_e32 v163, 0x70, v163
	v_or_b32_e32 v163, v163, v238
	v_ashrrev_i32_e32 v19, 31, v18
	v_lshl_add_u64 v[174:175], v[26:27], 0, v[0:1]
	v_lshlrev_b64 v[26:27], 14, v[18:19]
	v_lshl_add_u64 v[24:25], v[24:25], 0, v[26:27]
	v_lshl_add_u64 v[176:177], v[24:25], 0, v[0:1]
	global_load_dwordx4 v[148:151], v[174:175], off
	global_load_dwordx4 v[152:155], v[176:177], off
	v_add_u32_e32 v0, v16, v15
	v_and_b32_e32 v3, 64, v202
	v_or_b32_e32 v173, v0, v12
	v_xor_b32_e32 v0, 32, v202
	v_add_u32_e32 v3, 64, v3
	v_cmp_lt_i32_e32 vcc, v0, v3
	v_mov_b32_e32 v3, v1
	v_mov_b32_e32 v165, v1
	v_mov_b32_e32 v5, v1
	v_lshlrev_b32_e32 v169, 1, v14
	v_lshl_add_u64 v[178:179], v[2:3], 1, s[50:51]
	v_lshl_add_u64 v[14:15], s[64:65], 0, v[164:165]
	v_mov_b32_e32 v3, v20
	v_lshl_add_u64 v[182:183], v[4:5], 1, s[50:51]
	v_mov_b32_e32 v5, v22
	s_movk_i32 s10, 0xd0
	v_cndmask_b32_e32 v0, v202, v0, vcc
	v_lshl_add_u64 v[180:181], v[2:3], 1, v[14:15]
	v_lshl_add_u64 v[184:185], v[4:5], 1, v[14:15]
	v_lshl_add_u64 v[188:189], v[6:7], 1, v[14:15]
	v_mul_lo_u32 v165, v17, s10
	v_mul_lo_u32 v210, v21, s10
	v_mul_lo_u32 v211, v23, s10
	s_movk_i32 s10, 0x110
	v_mov_b32_e32 v14, v1
	v_mov_b32_e32 v15, v1
	v_lshlrev_b32_e32 v167, 3, v13
	v_lshlrev_b32_e32 v209, 2, v0
	v_lshl_add_u64 v[186:187], v[8:9], 1, s[50:51]
	v_lshlrev_b32_e32 v161, 2, v13
	v_mul_lo_u32 v212, v10, s10
	v_mul_lo_u32 v213, v18, s10
	v_add_u32_e32 v212, 0xd000, v212
	v_add_u32_e32 v213, 0xd000, v213
	v_mul_u32_u24_e32 v214, 0xd0, v12
	v_mul_u32_u24_e32 v215, 0x110, v12
	v_mov_b32_e32 v0, v1
	v_mov_b32_e32 v2, v1
	v_mov_b32_e32 v3, v1
	v_mov_b32_e32 v4, v1
	v_mov_b32_e32 v5, v1
	v_mov_b32_e32 v6, v1
	v_mov_b32_e32 v7, v1
	v_mov_b32_e32 v8, v1
	v_mov_b32_e32 v9, v1
	v_mov_b32_e32 v10, v1
	v_mov_b32_e32 v11, v1
	v_mov_b32_e32 v12, v1
	v_mov_b32_e32 v13, v1
	v_mov_b64_e32 v[30:31], v[14:15]
	v_mov_b64_e32 v[46:47], v[14:15]
	v_add_u32_e32 v171, 2, v169
	s_mov_b32 s18, 0
	v_mov_b32_e32 v159, 0
	s_movk_i32 s44, 0x80
	s_mov_b64 s[10:11], 0
	v_mov_b64_e32 v[28:29], v[12:13]
	v_mov_b64_e32 v[26:27], v[10:11]
	v_mov_b64_e32 v[24:25], v[8:9]
	v_mov_b64_e32 v[22:23], v[6:7]
	v_mov_b64_e32 v[20:21], v[4:5]
	v_mov_b64_e32 v[18:19], v[2:3]
	v_mov_b64_e32 v[16:17], v[0:1]
	v_mov_b64_e32 v[44:45], v[12:13]
	v_mov_b64_e32 v[42:43], v[10:11]
	v_mov_b64_e32 v[40:41], v[8:9]
	v_mov_b64_e32 v[38:39], v[6:7]
	v_mov_b64_e32 v[36:37], v[4:5]
	v_mov_b64_e32 v[34:35], v[2:3]
	v_mov_b64_e32 v[32:33], v[0:1]
	v_mov_b32_e32 v0, 0
	s_branch .LBB0_1400
.LBB0_1399:
.LBB0_1400:
	v_lshrrev_b32_e32 v2, 8, v198
	v_readfirstlane_b32 s99, v171
	v_readfirstlane_b32 s98, v2
	s_mov_b32 s101, 0
	s_mov_b32 s12, 0
	s_nop 1
	s_and_b32 s98, s98, 1
	s_mul_i32 s13, s12, 0x6800
	s_mul_i32 s12, s12, 0x4400
	v_add3_u32 v2, s13, v165, v162
	s_waitcnt vmcnt(4)
	ds_write_b128 v2, v[136:139]
	v_add3_u32 v2, s13, v210, v168
	s_waitcnt vmcnt(3)
	ds_write_b128 v2, v[140:143]
	v_add3_u32 v2, s13, v211, v172
	s_waitcnt vmcnt(2)
	ds_write_b128 v2, v[144:147]
	v_lshl_add_u32 v2, v163, 1, s12
	v_add_u32_e32 v3, v2, v212
	v_add_u32_e32 v2, v2, v213
	s_waitcnt vmcnt(1)
	ds_write2_b64 v3, v[148:149], v[150:151] offset1:2
	s_waitcnt vmcnt(0)
	ds_write2_b64 v2, v[152:153], v[154:155] offset1:2
.Lat1_loop:
	s_and_b32 s12, s18, 1
	s_mul_i32 s19, s12, 0x6800
	s_add_i32 s16, s18, 1
	v_cmp_lt_u32_e32 vcc, s16, v171
	s_waitcnt lgkmcnt(0)
	s_barrier
	s_and_saveexec_b64 s[12:13], vcc
	s_cbranch_execz .LBB0_1414
	v_add_u32_e32 v4, s44, v160
	v_ashrrev_i32_e32 v5, 31, v4
	s_and_saveexec_b64 s[14:15], s[2:3]
	s_xor_b64 s[14:15], exec, s[14:15]
	v_mad_i64_i32 v[2:3], s[20:21], v4, s61, v[178:179]
	v_lshl_add_u64 v[2:3], v[2:3], 0, s[84:85]
	s_andn2_saveexec_b64 s[14:15], s[14:15]
	v_lshlrev_b64 v[2:3], 10, v[4:5]
	v_lshl_add_u64 v[2:3], v[180:181], 0, v[2:3]
	s_or_b64 exec, exec, s[14:15]
	global_load_dwordx4 v[136:139], v[2:3], off
	v_add_u32_e32 v4, s44, v166
	v_ashrrev_i32_e32 v5, 31, v4
	s_and_saveexec_b64 s[14:15], s[4:5]
	s_xor_b64 s[14:15], exec, s[14:15]
	v_mad_i64_i32 v[2:3], s[20:21], v4, s61, v[182:183]
	v_lshl_add_u64 v[2:3], v[2:3], 0, s[84:85]
	s_andn2_saveexec_b64 s[14:15], s[14:15]
	v_lshlrev_b64 v[2:3], 10, v[4:5]
	v_lshl_add_u64 v[2:3], v[184:185], 0, v[2:3]
	s_or_b64 exec, exec, s[14:15]
	global_load_dwordx4 v[140:143], v[2:3], off
	v_add_u32_e32 v4, s44, v170
	v_ashrrev_i32_e32 v5, 31, v4
	s_and_saveexec_b64 s[14:15], s[6:7]
	s_xor_b64 s[14:15], exec, s[14:15]
	v_mad_i64_i32 v[2:3], s[20:21], v4, s61, v[186:187]
	v_lshl_add_u64 v[2:3], v[2:3], 0, s[84:85]
	s_andn2_saveexec_b64 s[14:15], s[14:15]
	v_lshlrev_b64 v[2:3], 10, v[4:5]
	v_lshl_add_u64 v[2:3], v[188:189], 0, v[2:3]
	s_or_b64 exec, exec, s[14:15]
	s_lshl_b64 s[14:15], s[44:45], 1
	global_load_dwordx4 v[144:147], v[2:3], off
	v_lshl_add_u64 v[2:3], v[174:175], 0, s[14:15]
	v_lshl_add_u64 v[4:5], v[176:177], 0, s[14:15]
	global_load_dwordx4 v[148:151], v[2:3], off
	global_load_dwordx4 v[152:155], v[4:5], off

.Lat1_qk:
	s_add_i32 s12, s18, 2
	s_cmp_ge_u32 s12, s99
	s_cbranch_scc1 .Lat1_qkm
	v_add3_u32 v10, s19, v158, v214
	v_xor_b32_e32 v48, 0x80000000, v0
	v_mov_b32_e32 v49, v48
	v_mov_b32_e32 v50, v48
	v_mov_b32_e32 v51, v48
	v_mov_b32_e32 v52, v48
	v_mov_b32_e32 v53, v48
	v_mov_b32_e32 v54, v48
	v_mov_b32_e32 v55, v48
	v_mov_b32_e32 v56, v48
	v_mov_b32_e32 v57, v48
	v_mov_b32_e32 v58, v48
	v_mov_b32_e32 v59, v48
	v_mov_b32_e32 v60, v48
	v_mov_b32_e32 v61, v48
	v_mov_b32_e32 v62, v48
	v_mov_b32_e32 v63, v48
	ds_read_b128 v[6:9], v10
	ds_read_b128 v[222:225], v10 offset:32
	ds_read_b128 v[226:229], v10 offset:64
	ds_read_b128 v[230:233], v10 offset:96
	ds_read_b128 v[234:237], v10 offset:128
	ds_read_b128 v[242:245], v10 offset:160
	ds_read_b128 v[246:249], v10 offset:6656
	ds_read_b128 v[250:253], v10 offset:6688
	s_waitcnt lgkmcnt(7)
	v_mfma_f32_32x32x16_bf16 v[80:95], v[6:9], v[120:123], v[48:63]
	ds_read_b128 v[6:9], v10 offset:6720
	s_waitcnt lgkmcnt(7)
	v_mfma_f32_32x32x16_bf16 v[80:95], v[222:225], v[112:115], v[80:95]
	ds_read_b128 v[222:225], v10 offset:6752
	s_waitcnt lgkmcnt(7)
	v_mfma_f32_32x32x16_bf16 v[80:95], v[226:229], v[116:119], v[80:95]
	ds_read_b128 v[226:229], v10 offset:6784
	s_waitcnt lgkmcnt(7)
	v_mfma_f32_32x32x16_bf16 v[80:95], v[230:233], v[124:127], v[80:95]
	ds_read_b128 v[230:233], v10 offset:6816
	s_waitcnt lgkmcnt(7)
	v_mfma_f32_32x32x16_bf16 v[80:95], v[234:237], v[128:131], v[80:95]
	ds_read_b128 v[234:237], v10 offset:13312
	s_waitcnt lgkmcnt(7)
	v_mfma_f32_32x32x16_bf16 v[80:95], v[242:245], v[132:135], v[80:95]
	ds_read_b128 v[242:245], v10 offset:13344
	s_waitcnt lgkmcnt(7)
	v_mfma_f32_32x32x16_bf16 v[64:79], v[246:249], v[120:123], v[48:63]
	ds_read_b128 v[246:249], v10 offset:13376
	s_waitcnt lgkmcnt(7)
	v_mfma_f32_32x32x16_bf16 v[64:79], v[250:253], v[112:115], v[64:79]
	ds_read_b128 v[250:253], v10 offset:13408
	s_waitcnt lgkmcnt(7)
	v_mfma_f32_32x32x16_bf16 v[64:79], v[6:9], v[116:119], v[64:79]
	ds_read_b128 v[6:9], v10 offset:13440
	s_waitcnt lgkmcnt(7)
	v_mfma_f32_32x32x16_bf16 v[64:79], v[222:225], v[124:127], v[64:79]
	ds_read_b128 v[222:225], v10 offset:13472
	s_waitcnt lgkmcnt(7)
	v_mfma_f32_32x32x16_bf16 v[64:79], v[226:229], v[128:131], v[64:79]
	ds_read_b128 v[226:229], v10 offset:19968
	v_max3_f32 v11, v80, v81, v82
	v_max3_f32 v11, v11, v83, v84
	v_max3_f32 v11, v11, v85, v86
	v_max3_f32 v11, v11, v87, v88
	v_max3_f32 v11, v11, v89, v90
	v_max3_f32 v11, v11, v91, v92
	s_waitcnt lgkmcnt(7)
	v_mfma_f32_32x32x16_bf16 v[64:79], v[230:233], v[132:135], v[64:79]
	ds_read_b128 v[230:233], v10 offset:20000
	v_max3_f32 v11, v11, v93, v94
	v_max_f32_e32 v11, v11, v95
	v_exp_f32_e32 v80, v80
	v_exp_f32_e32 v81, v81
	v_exp_f32_e32 v82, v82
	v_exp_f32_e32 v83, v83
	s_waitcnt lgkmcnt(7)
	v_mfma_f32_32x32x16_bf16 v[96:111], v[234:237], v[120:123], v[48:63]
	ds_read_b128 v[234:237], v10 offset:20032
	v_mov_b32_e32 v12, v80
	v_mov_b32_e32 v13, v81
	v_mov_b32_e32 v14, v82
	v_mov_b32_e32 v15, v83
	v_exp_f32_e32 v84, v84
	v_exp_f32_e32 v85, v85
	s_waitcnt lgkmcnt(7)
	v_mfma_f32_32x32x16_bf16 v[96:111], v[242:245], v[112:115], v[96:111]
	ds_read_b128 v[242:245], v10 offset:20064
	v_exp_f32_e32 v86, v86
	v_exp_f32_e32 v87, v87
	v_add_f32_e32 v12, v12, v84
	v_add_f32_e32 v13, v13, v85
	v_add_f32_e32 v14, v14, v86
	v_add_f32_e32 v15, v15, v87
	s_waitcnt lgkmcnt(7)
	v_mfma_f32_32x32x16_bf16 v[96:111], v[246:249], v[116:119], v[96:111]
	ds_read_b128 v[246:249], v10 offset:20096
	v_cvt_pk_bf16_f32 v80, v80, v81
	v_cvt_pk_bf16_f32 v81, v82, v83
	v_cvt_pk_bf16_f32 v82, v84, v85
	v_cvt_pk_bf16_f32 v83, v86, v87
	v_exp_f32_e32 v88, v88
	v_exp_f32_e32 v89, v89
	s_waitcnt lgkmcnt(7)
	v_mfma_f32_32x32x16_bf16 v[96:111], v[250:253], v[124:127], v[96:111]
	ds_read_b128 v[250:253], v10 offset:20128
	v_exp_f32_e32 v90, v90
	v_exp_f32_e32 v91, v91
	v_add_f32_e32 v12, v12, v88
	v_add_f32_e32 v13, v13, v89
	v_add_f32_e32 v14, v14, v90
	v_add_f32_e32 v15, v15, v91
	s_waitcnt lgkmcnt(7)
	v_mfma_f32_32x32x16_bf16 v[96:111], v[6:9], v[128:131], v[96:111]
	v_exp_f32_e32 v92, v92
	v_exp_f32_e32 v93, v93
	v_exp_f32_e32 v94, v94
	v_exp_f32_e32 v95, v95
	v_add_f32_e32 v12, v12, v92
	v_add_f32_e32 v13, v13, v93
	s_waitcnt lgkmcnt(6)
	v_mfma_f32_32x32x16_bf16 v[96:111], v[222:225], v[132:135], v[96:111]
	v_add_f32_e32 v14, v14, v94
	v_add_f32_e32 v15, v15, v95
	v_cvt_pk_bf16_f32 v84, v88, v89
	v_cvt_pk_bf16_f32 v85, v90, v91
	v_cvt_pk_bf16_f32 v86, v92, v93
	v_cvt_pk_bf16_f32 v87, v94, v95
	s_waitcnt lgkmcnt(5)
	v_mfma_f32_32x32x16_bf16 v[48:63], v[226:229], v[120:123], v[48:63]
	v_max3_f32 v241, v64, v65, v66
	v_max3_f32 v241, v241, v67, v68
	v_max3_f32 v241, v241, v69, v70
	v_max3_f32 v241, v241, v71, v72
	v_max3_f32 v241, v241, v73, v74
	v_max3_f32 v241, v241, v75, v76
	s_waitcnt lgkmcnt(4)
	v_mfma_f32_32x32x16_bf16 v[48:63], v[230:233], v[112:115], v[48:63]
	v_max3_f32 v241, v241, v77, v78
	v_max_f32_e32 v241, v241, v79
	v_exp_f32_e32 v64, v64
	v_exp_f32_e32 v65, v65
	v_exp_f32_e32 v66, v66
	v_exp_f32_e32 v67, v67
	s_waitcnt lgkmcnt(3)
	v_mfma_f32_32x32x16_bf16 v[48:63], v[234:237], v[116:119], v[48:63]
	v_add_f32_e32 v12, v12, v64
	v_add_f32_e32 v13, v13, v65
	v_add_f32_e32 v14, v14, v66
	v_add_f32_e32 v15, v15, v67
	v_exp_f32_e32 v68, v68
	v_exp_f32_e32 v69, v69
	s_waitcnt lgkmcnt(2)
	v_mfma_f32_32x32x16_bf16 v[48:63], v[242:245], v[124:127], v[48:63]
	v_exp_f32_e32 v70, v70
	v_exp_f32_e32 v71, v71
	v_add_f32_e32 v12, v12, v68
	v_add_f32_e32 v13, v13, v69
	v_add_f32_e32 v14, v14, v70
	v_add_f32_e32 v15, v15, v71
	s_waitcnt lgkmcnt(1)
	v_mfma_f32_32x32x16_bf16 v[48:63], v[246:249], v[128:131], v[48:63]
	v_cvt_pk_bf16_f32 v64, v64, v65
	v_cvt_pk_bf16_f32 v65, v66, v67
	v_cvt_pk_bf16_f32 v66, v68, v69
	v_cvt_pk_bf16_f32 v67, v70, v71
	v_exp_f32_e32 v72, v72
	v_exp_f32_e32 v73, v73
	s_waitcnt lgkmcnt(0)
	v_mfma_f32_32x32x16_bf16 v[48:63], v[250:253], v[132:135], v[48:63]
	v_exp_f32_e32 v74, v74
	v_exp_f32_e32 v75, v75
	v_add_f32_e32 v12, v12, v72
	v_add_f32_e32 v13, v13, v73
	v_add_f32_e32 v14, v14, v74
	v_add_f32_e32 v15, v15, v75
	s_branch .Lat1_qkdone
.Lat1_qkm:
	v_add3_u32 v10, s19, v158, v214
	v_xor_b32_e32 v48, 0x80000000, v0
	v_mov_b32_e32 v49, v48
	v_mov_b32_e32 v50, v48
	v_mov_b32_e32 v51, v48
	v_mov_b32_e32 v52, v48
	v_mov_b32_e32 v53, v48
	v_mov_b32_e32 v54, v48
	v_mov_b32_e32 v55, v48
	v_mov_b32_e32 v56, v48
	v_mov_b32_e32 v57, v48
	v_mov_b32_e32 v58, v48
	v_mov_b32_e32 v59, v48
	v_mov_b32_e32 v60, v48
	v_mov_b32_e32 v61, v48
	v_mov_b32_e32 v62, v48
	v_mov_b32_e32 v63, v48
	ds_read_b128 v[6:9], v10
	ds_read_b128 v[222:225], v10 offset:32
	ds_read_b128 v[226:229], v10 offset:64
	ds_read_b128 v[230:233], v10 offset:96
	ds_read_b128 v[234:237], v10 offset:128
	ds_read_b128 v[242:245], v10 offset:160
	ds_read_b128 v[246:249], v10 offset:6656
	ds_read_b128 v[250:253], v10 offset:6688
	s_waitcnt lgkmcnt(7)
	v_mfma_f32_32x32x16_bf16 v[80:95], v[6:9], v[120:123], v[48:63]
	ds_read_b128 v[6:9], v10 offset:6720
	s_waitcnt lgkmcnt(7)
	v_mfma_f32_32x32x16_bf16 v[80:95], v[222:225], v[112:115], v[80:95]
	ds_read_b128 v[222:225], v10 offset:6752
	s_waitcnt lgkmcnt(7)
	v_mfma_f32_32x32x16_bf16 v[80:95], v[226:229], v[116:119], v[80:95]
	ds_read_b128 v[226:229], v10 offset:6784
	s_waitcnt lgkmcnt(7)
	v_mfma_f32_32x32x16_bf16 v[80:95], v[230:233], v[124:127], v[80:95]
	ds_read_b128 v[230:233], v10 offset:6816
	s_waitcnt lgkmcnt(7)
	v_mfma_f32_32x32x16_bf16 v[80:95], v[234:237], v[128:131], v[80:95]
	ds_read_b128 v[234:237], v10 offset:13312
	s_waitcnt lgkmcnt(7)
	v_mfma_f32_32x32x16_bf16 v[80:95], v[242:245], v[132:135], v[80:95]
	ds_read_b128 v[242:245], v10 offset:13344
	s_waitcnt lgkmcnt(7)
	v_mfma_f32_32x32x16_bf16 v[64:79], v[246:249], v[120:123], v[48:63]
	ds_read_b128 v[246:249], v10 offset:13376
	s_waitcnt lgkmcnt(7)
	v_mfma_f32_32x32x16_bf16 v[64:79], v[250:253], v[112:115], v[64:79]
	ds_read_b128 v[250:253], v10 offset:13408
	s_waitcnt lgkmcnt(7)
	v_mfma_f32_32x32x16_bf16 v[64:79], v[6:9], v[116:119], v[64:79]
	ds_read_b128 v[6:9], v10 offset:13440
	s_waitcnt lgkmcnt(7)
	v_mfma_f32_32x32x16_bf16 v[64:79], v[222:225], v[124:127], v[64:79]
	ds_read_b128 v[222:225], v10 offset:13472
	s_waitcnt lgkmcnt(7)
	v_mfma_f32_32x32x16_bf16 v[64:79], v[226:229], v[128:131], v[64:79]
	ds_read_b128 v[226:229], v10 offset:19968
	s_waitcnt lgkmcnt(7)
	v_mfma_f32_32x32x16_bf16 v[64:79], v[230:233], v[132:135], v[64:79]
	ds_read_b128 v[230:233], v10 offset:20000
	s_waitcnt lgkmcnt(7)
	v_mfma_f32_32x32x16_bf16 v[96:111], v[234:237], v[120:123], v[48:63]
	ds_read_b128 v[234:237], v10 offset:20032
	s_waitcnt lgkmcnt(7)
	v_mfma_f32_32x32x16_bf16 v[96:111], v[242:245], v[112:115], v[96:111]
	ds_read_b128 v[242:245], v10 offset:20064
	s_waitcnt lgkmcnt(7)
	v_mfma_f32_32x32x16_bf16 v[96:111], v[246:249], v[116:119], v[96:111]
	ds_read_b128 v[246:249], v10 offset:20096
	s_waitcnt lgkmcnt(7)
	v_mfma_f32_32x32x16_bf16 v[96:111], v[250:253], v[124:127], v[96:111]
	ds_read_b128 v[250:253], v10 offset:20128
	s_waitcnt lgkmcnt(7)
	v_mfma_f32_32x32x16_bf16 v[96:111], v[6:9], v[128:131], v[96:111]
	s_waitcnt lgkmcnt(6)
	v_mfma_f32_32x32x16_bf16 v[96:111], v[222:225], v[132:135], v[96:111]
	s_waitcnt lgkmcnt(5)
	v_mfma_f32_32x32x16_bf16 v[48:63], v[226:229], v[120:123], v[48:63]
	s_waitcnt lgkmcnt(4)
	v_mfma_f32_32x32x16_bf16 v[48:63], v[230:233], v[112:115], v[48:63]
	s_waitcnt lgkmcnt(3)
	v_mfma_f32_32x32x16_bf16 v[48:63], v[234:237], v[116:119], v[48:63]
	s_waitcnt lgkmcnt(2)
	v_mfma_f32_32x32x16_bf16 v[48:63], v[242:245], v[124:127], v[48:63]
	s_waitcnt lgkmcnt(1)
	v_mfma_f32_32x32x16_bf16 v[48:63], v[246:249], v[128:131], v[48:63]
	s_waitcnt lgkmcnt(0)
	v_mfma_f32_32x32x16_bf16 v[48:63], v[250:253], v[132:135], v[48:63]
.Lat1_qkdone:
	s_mov_b32 s100, s44
	s_cmp_eq_u32 s98, 1
	s_cbranch_scc1 .Lat1_endit

.Lat1_pvm3:
	s_mul_i32 s17, s13, 0x4400
	s_add_i32 s12, s12, 2
	s_cmp_ge_u32 s12, s99
	s_cbranch_scc1 .Lat1_pvmask
	v_add3_u32 v238, s17, v167, v215
	v_add_u32_e32 v238, v238, v167
	ds_read_b128 v[222:225], v238 offset:53248
	ds_read_b128 v[226:229], v238 offset:61952
	ds_read_b128 v[230:233], v238 offset:53280
	ds_read_b128 v[234:237], v238 offset:61984
	ds_read_b128 v[242:245], v238 offset:53312
	ds_read_b128 v[246:249], v238 offset:62016
	ds_read_b128 v[250:253], v238 offset:53344
	s_waitcnt lgkmcnt(6)
	v_mfma_f32_32x32x16_bf16 v[32:47], v[222:225], v[80:83], v[32:47]
	v_exp_f32_e32 v76, v76
	v_exp_f32_e32 v77, v77
	v_exp_f32_e32 v78, v78
	s_waitcnt lgkmcnt(5)
	v_mfma_f32_32x32x16_bf16 v[16:31], v[226:229], v[80:83], v[16:31]
	ds_read_b128 v[222:225], v238 offset:62048
	ds_read_b128 v[226:229], v238 offset:53376
	v_exp_f32_e32 v79, v79
	v_add_f32_e32 v12, v12, v76
	v_add_f32_e32 v13, v13, v77
	s_waitcnt lgkmcnt(6)
	v_mfma_f32_32x32x16_bf16 v[32:47], v[230:233], v[84:87], v[32:47]
	v_add_f32_e32 v14, v14, v78
	v_add_f32_e32 v15, v15, v79
	v_cvt_pk_bf16_f32 v68, v72, v73
	s_waitcnt lgkmcnt(5)
	v_mfma_f32_32x32x16_bf16 v[16:31], v[234:237], v[84:87], v[16:31]
	ds_read_b128 v[230:233], v238 offset:62080
	ds_read_b128 v[234:237], v238 offset:53408
	v_cvt_pk_bf16_f32 v69, v74, v75
	v_cvt_pk_bf16_f32 v70, v76, v77
	v_cvt_pk_bf16_f32 v71, v78, v79
	s_waitcnt lgkmcnt(6)
	v_mfma_f32_32x32x16_bf16 v[32:47], v[242:245], v[64:67], v[32:47]
	v_max3_f32 v254, v96, v97, v98
	v_max3_f32 v254, v254, v99, v100
	v_max3_f32 v254, v254, v101, v102
	v_max3_f32 v254, v254, v103, v104
	v_max3_f32 v254, v254, v105, v106
	v_max3_f32 v254, v254, v107, v108
	v_max3_f32 v254, v254, v109, v110
	v_max_f32_e32 v254, v254, v111
	v_exp_f32_e32 v96, v96
	v_exp_f32_e32 v97, v97
	v_exp_f32_e32 v98, v98
	v_exp_f32_e32 v99, v99
	s_waitcnt lgkmcnt(5)
	v_mfma_f32_32x32x16_bf16 v[16:31], v[246:249], v[64:67], v[16:31]
	ds_read_b128 v[242:245], v238 offset:62112
	ds_read_b128 v[246:249], v238 offset:53440
	v_add_f32_e32 v12, v12, v96
	v_add_f32_e32 v13, v13, v97
	v_add_f32_e32 v14, v14, v98
	v_add_f32_e32 v15, v15, v99
	v_exp_f32_e32 v100, v100
	v_exp_f32_e32 v101, v101
	v_exp_f32_e32 v102, v102
	v_exp_f32_e32 v103, v103
	v_add_f32_e32 v12, v12, v100
	v_add_f32_e32 v13, v13, v101
	v_add_f32_e32 v14, v14, v102
	v_add_f32_e32 v15, v15, v103
	s_waitcnt lgkmcnt(6)
	v_mfma_f32_32x32x16_bf16 v[32:47], v[250:253], v[68:71], v[32:47]
	v_cvt_pk_bf16_f32 v96, v96, v97
	v_cvt_pk_bf16_f32 v97, v98, v99
	v_cvt_pk_bf16_f32 v98, v100, v101
	v_cvt_pk_bf16_f32 v99, v102, v103
	v_exp_f32_e32 v104, v104
	v_exp_f32_e32 v105, v105
	v_exp_f32_e32 v106, v106
	v_exp_f32_e32 v107, v107
	v_add_f32_e32 v12, v12, v104
	v_add_f32_e32 v13, v13, v105
	v_add_f32_e32 v14, v14, v106
	v_add_f32_e32 v15, v15, v107
	s_waitcnt lgkmcnt(5)
	v_mfma_f32_32x32x16_bf16 v[16:31], v[222:225], v[68:71], v[16:31]
	ds_read_b128 v[250:253], v238 offset:62144
	ds_read_b128 v[222:225], v238 offset:53472
	v_exp_f32_e32 v108, v108
	v_exp_f32_e32 v109, v109
	v_exp_f32_e32 v110, v110
	v_exp_f32_e32 v111, v111
	v_add_f32_e32 v12, v12, v108
	v_add_f32_e32 v13, v13, v109
	v_add_f32_e32 v14, v14, v110
	v_add_f32_e32 v15, v15, v111
	v_cvt_pk_bf16_f32 v100, v104, v105
	v_cvt_pk_bf16_f32 v101, v106, v107
	v_cvt_pk_bf16_f32 v102, v108, v109
	v_cvt_pk_bf16_f32 v103, v110, v111
	s_waitcnt lgkmcnt(6)
	v_mfma_f32_32x32x16_bf16 v[32:47], v[226:229], v[96:99], v[32:47]
	v_max3_f32 v255, v48, v49, v50
	v_max3_f32 v255, v255, v51, v52
	v_max3_f32 v255, v255, v53, v54
	v_max3_f32 v255, v255, v55, v56
	v_max3_f32 v255, v255, v57, v58
	v_max3_f32 v255, v255, v59, v60
	v_max3_f32 v255, v255, v61, v62
	v_max_f32_e32 v255, v255, v63
	v_exp_f32_e32 v48, v48
	v_exp_f32_e32 v49, v49
	v_exp_f32_e32 v50, v50
	v_exp_f32_e32 v51, v51
	s_waitcnt lgkmcnt(5)
	v_mfma_f32_32x32x16_bf16 v[16:31], v[230:233], v[96:99], v[16:31]
	ds_read_b128 v[226:229], v238 offset:62176
	v_add_f32_e32 v12, v12, v48
	v_add_f32_e32 v13, v13, v49
	v_add_f32_e32 v14, v14, v50
	v_add_f32_e32 v15, v15, v51
	v_exp_f32_e32 v52, v52
	v_exp_f32_e32 v53, v53
	v_exp_f32_e32 v54, v54
	v_exp_f32_e32 v55, v55
	v_add_f32_e32 v12, v12, v52
	v_add_f32_e32 v13, v13, v53
	v_add_f32_e32 v14, v14, v54
	v_add_f32_e32 v15, v15, v55
	s_waitcnt lgkmcnt(5)
	v_mfma_f32_32x32x16_bf16 v[32:47], v[234:237], v[100:103], v[32:47]
	v_cvt_pk_bf16_f32 v48, v48, v49
	v_cvt_pk_bf16_f32 v49, v50, v51
	v_cvt_pk_bf16_f32 v50, v52, v53
	v_cvt_pk_bf16_f32 v51, v54, v55
	v_exp_f32_e32 v56, v56
	v_exp_f32_e32 v57, v57
	v_exp_f32_e32 v58, v58
	v_exp_f32_e32 v59, v59
	v_add_f32_e32 v12, v12, v56
	v_add_f32_e32 v13, v13, v57
	v_add_f32_e32 v14, v14, v58
	v_add_f32_e32 v15, v15, v59
	s_waitcnt lgkmcnt(4)
	v_mfma_f32_32x32x16_bf16 v[16:31], v[242:245], v[100:103], v[16:31]
	v_exp_f32_e32 v60, v60
	v_exp_f32_e32 v61, v61
	v_exp_f32_e32 v62, v62
	v_exp_f32_e32 v63, v63
	v_add_f32_e32 v12, v12, v60
	v_add_f32_e32 v13, v13, v61
	v_add_f32_e32 v14, v14, v62
	v_add_f32_e32 v15, v15, v63
	v_cvt_pk_bf16_f32 v52, v56, v57
	v_cvt_pk_bf16_f32 v53, v58, v59
	v_cvt_pk_bf16_f32 v54, v60, v61
	v_cvt_pk_bf16_f32 v55, v62, v63
	s_waitcnt lgkmcnt(3)
	v_mfma_f32_32x32x16_bf16 v[32:47], v[246:249], v[48:51], v[32:47]
	s_waitcnt lgkmcnt(2)
	v_mfma_f32_32x32x16_bf16 v[16:31], v[250:253], v[48:51], v[16:31]
	s_waitcnt lgkmcnt(1)
	v_mfma_f32_32x32x16_bf16 v[32:47], v[222:225], v[52:55], v[32:47]
	s_waitcnt lgkmcnt(0)
	v_mfma_f32_32x32x16_bf16 v[16:31], v[226:229], v[52:55], v[16:31]
	v_add_f32_e32 v12, v12, v13
	v_add_f32_e32 v14, v14, v15
	v_max3_f32 v2, v255, v11, v241
	v_add_f32_e32 v12, v12, v14
	v_max_f32_e32 v2, v2, v254
	v_add_f32_e32 v159, v159, v12
	v_mov_b32_e32 v3, v2
	s_nop 1
	v_permlane32_swap_b32_e32 v2, v3
	v_max_f32_e32 v2, v2, v3
	v_cmp_lt_f32_e32 vcc, 0, v2
	s_cbranch_vccz .Lattn_fnr_1
	s_nop 7
	s_nop 3
	v_max_f32_e32 v2, 0, v2
	v_exp_f32_e64 v4, -v2
	v_add_f32_e32 v0, v0, v2
	s_nop 0
	v_mul_f32_e32 v159, v159, v4
	v_mul_f32_e32 v16, v16, v4
	v_mul_f32_e32 v17, v17, v4
	v_mul_f32_e32 v18, v18, v4
	v_mul_f32_e32 v19, v19, v4
	v_mul_f32_e32 v20, v20, v4
	v_mul_f32_e32 v21, v21, v4
	v_mul_f32_e32 v22, v22, v4
	v_mul_f32_e32 v23, v23, v4
	v_mul_f32_e32 v24, v24, v4
	v_mul_f32_e32 v25, v25, v4
	v_mul_f32_e32 v26, v26, v4
	v_mul_f32_e32 v27, v27, v4
	v_mul_f32_e32 v28, v28, v4
	v_mul_f32_e32 v29, v29, v4
	v_mul_f32_e32 v30, v30, v4
	v_mul_f32_e32 v31, v31, v4
	v_mul_f32_e32 v32, v32, v4
	v_mul_f32_e32 v33, v33, v4
	v_mul_f32_e32 v34, v34, v4
	v_mul_f32_e32 v35, v35, v4
	v_mul_f32_e32 v36, v36, v4
	v_mul_f32_e32 v37, v37, v4
	v_mul_f32_e32 v38, v38, v4
	v_mul_f32_e32 v39, v39, v4
	v_mul_f32_e32 v40, v40, v4
	v_mul_f32_e32 v41, v41, v4
	v_mul_f32_e32 v42, v42, v4
	v_mul_f32_e32 v43, v43, v4
	v_mul_f32_e32 v44, v44, v4
	v_mul_f32_e32 v45, v45, v4
	v_mul_f32_e32 v46, v46, v4
	v_mul_f32_e32 v47, v47, v4

.Lat1_pvmask:
	v_add3_u32 v238, s17, v167, v215
	v_add_u32_e32 v238, v238, v167
	ds_read_b128 v[222:225], v238 offset:53248
	ds_read_b128 v[226:229], v238 offset:61952
	ds_read_b128 v[230:233], v238 offset:53280
	ds_read_b128 v[234:237], v238 offset:61984
	ds_read_b128 v[242:245], v238 offset:53312
	ds_read_b128 v[246:249], v238 offset:62016
	ds_read_b128 v[250:253], v238 offset:53344
	v_add_u32_e32 v2, s100, v161
	v_add_u32_e32 v3, 0xffffff80, v2
	v_cmp_lt_i32_e32 vcc, v3, v173
	s_nop 1
	v_cndmask_b32_e32 v81, v203, v81, vcc
	v_cmp_le_i32_e32 vcc, v3, v173
	v_add_u32_e32 v3, 0xffffff82, v2
	s_nop 0
	v_cndmask_b32_e32 v80, v203, v80, vcc
	v_cmp_le_i32_e32 vcc, v3, v173
	v_add_u32_e32 v3, 0xffffff83, v2
	s_nop 0
	v_cndmask_b32_e32 v82, v203, v82, vcc
	v_cmp_le_i32_e32 vcc, v3, v173
	v_add_u32_e32 v3, 0xffffff88, v2
	s_nop 0
	v_cndmask_b32_e32 v83, v203, v83, vcc
	v_cmp_le_i32_e32 vcc, v3, v173
	v_add_u32_e32 v3, 0xffffff89, v2
	s_nop 0
	v_cndmask_b32_e32 v84, v203, v84, vcc
	v_cmp_le_i32_e32 vcc, v3, v173
	v_add_u32_e32 v3, 0xffffff8a, v2
	s_nop 0
	v_cndmask_b32_e32 v85, v203, v85, vcc
	v_cmp_le_i32_e32 vcc, v3, v173
	v_add_u32_e32 v3, 0xffffff8b, v2
	s_nop 0
	v_cndmask_b32_e32 v86, v203, v86, vcc
	v_cmp_le_i32_e32 vcc, v3, v173
	v_add_u32_e32 v3, 0xffffff90, v2
	s_nop 0
	v_cndmask_b32_e32 v87, v203, v87, vcc
	v_cmp_le_i32_e32 vcc, v3, v173
	v_add_u32_e32 v3, 0xffffff91, v2
	s_nop 0
	v_cndmask_b32_e32 v88, v203, v88, vcc
	v_cmp_le_i32_e32 vcc, v3, v173
	v_add_u32_e32 v3, 0xffffff92, v2
	s_nop 0
	v_cndmask_b32_e32 v89, v203, v89, vcc
	v_cmp_le_i32_e32 vcc, v3, v173
	v_add_u32_e32 v3, 0xffffff93, v2
	s_nop 0
	v_cndmask_b32_e32 v90, v203, v90, vcc
	v_cmp_le_i32_e32 vcc, v3, v173
	v_add_u32_e32 v3, 0xffffff98, v2
	s_nop 0
	v_cndmask_b32_e32 v91, v203, v91, vcc
	v_cmp_le_i32_e32 vcc, v3, v173
	v_add_u32_e32 v3, 0xffffff99, v2
	s_nop 0
	v_cndmask_b32_e32 v92, v203, v92, vcc
	v_cmp_le_i32_e32 vcc, v3, v173
	v_add_u32_e32 v3, 0xffffff9a, v2
	s_nop 0
	v_cndmask_b32_e32 v93, v203, v93, vcc
	v_cmp_le_i32_e32 vcc, v3, v173
	v_add_u32_e32 v3, 0xffffff9b, v2
	s_nop 0
	v_cndmask_b32_e32 v94, v203, v94, vcc
	v_cmp_le_i32_e32 vcc, v3, v173
	v_add_u32_e32 v3, 0xffffffa0, v2
	s_nop 0
	v_cndmask_b32_e32 v95, v203, v95, vcc
	v_cmp_le_i32_e32 vcc, v3, v173
	v_add_u32_e32 v3, 0xffffffa1, v2
	s_nop 0
	v_cndmask_b32_e32 v64, v203, v64, vcc
	v_cmp_le_i32_e32 vcc, v3, v173
	v_add_u32_e32 v3, 0xffffffa2, v2
	s_nop 0
	v_cndmask_b32_e32 v65, v203, v65, vcc
	v_cmp_le_i32_e32 vcc, v3, v173
	v_add_u32_e32 v3, 0xffffffa3, v2
	s_nop 0
	v_cndmask_b32_e32 v66, v203, v66, vcc
	v_cmp_le_i32_e32 vcc, v3, v173
	v_add_u32_e32 v3, 0xffffffa8, v2
	s_nop 0
	v_cndmask_b32_e32 v67, v203, v67, vcc
	v_cmp_le_i32_e32 vcc, v3, v173
	v_add_u32_e32 v3, 0xffffffa9, v2
	s_nop 0
	v_cndmask_b32_e32 v68, v203, v68, vcc
	v_cmp_le_i32_e32 vcc, v3, v173
	v_add_u32_e32 v3, 0xffffffaa, v2
	s_nop 0
	v_cndmask_b32_e32 v69, v203, v69, vcc
	v_cmp_le_i32_e32 vcc, v3, v173
	v_add_u32_e32 v3, 0xffffffab, v2
	s_nop 0
	v_cndmask_b32_e32 v70, v203, v70, vcc
	v_cmp_le_i32_e32 vcc, v3, v173
	v_add_u32_e32 v3, 0xffffffb0, v2
	s_nop 0
	v_cndmask_b32_e32 v71, v203, v71, vcc
	v_cmp_le_i32_e32 vcc, v3, v173
	v_add_u32_e32 v3, 0xffffffb1, v2
	s_nop 0
	v_cndmask_b32_e32 v72, v203, v72, vcc
	v_cmp_le_i32_e32 vcc, v3, v173
	v_add_u32_e32 v3, 0xffffffb2, v2
	s_nop 0
	v_cndmask_b32_e32 v73, v203, v73, vcc
	v_cmp_le_i32_e32 vcc, v3, v173
	v_add_u32_e32 v3, 0xffffffb3, v2
	s_nop 0
	v_cndmask_b32_e32 v74, v203, v74, vcc
	v_cmp_le_i32_e32 vcc, v3, v173
	v_add_u32_e32 v3, 0xffffffb8, v2
	s_nop 0
	v_cndmask_b32_e32 v75, v203, v75, vcc
	v_cmp_le_i32_e32 vcc, v3, v173
	v_add_u32_e32 v3, 0xffffffb9, v2
	s_nop 0
	v_cndmask_b32_e32 v76, v203, v76, vcc
	v_cmp_le_i32_e32 vcc, v3, v173
	v_add_u32_e32 v3, 0xffffffba, v2
	s_nop 0
	v_cndmask_b32_e32 v77, v203, v77, vcc
	v_cmp_le_i32_e32 vcc, v3, v173
	v_add_u32_e32 v3, 0xffffffbb, v2
	s_nop 0
	v_cndmask_b32_e32 v78, v203, v78, vcc
	v_cmp_le_i32_e32 vcc, v3, v173
	v_subrev_u32_e32 v3, 64, v2
	s_nop 0
	v_cndmask_b32_e32 v79, v203, v79, vcc
	v_cmp_le_i32_e32 vcc, v3, v173
	v_subrev_u32_e32 v3, 63, v2
	s_nop 0
	v_cndmask_b32_e32 v96, v203, v96, vcc
	v_cmp_le_i32_e32 vcc, v3, v173
	v_subrev_u32_e32 v3, 62, v2
	s_nop 0
	v_cndmask_b32_e32 v97, v203, v97, vcc
	v_cmp_le_i32_e32 vcc, v3, v173
	v_subrev_u32_e32 v3, 61, v2
	s_nop 0
	v_cndmask_b32_e32 v98, v203, v98, vcc
	v_cmp_le_i32_e32 vcc, v3, v173
	v_subrev_u32_e32 v3, 56, v2
	s_nop 0
	v_cndmask_b32_e32 v99, v203, v99, vcc
	v_cmp_le_i32_e32 vcc, v3, v173
	v_subrev_u32_e32 v3, 55, v2
	s_nop 0
	v_cndmask_b32_e32 v100, v203, v100, vcc
	v_cmp_le_i32_e32 vcc, v3, v173
	v_subrev_u32_e32 v3, 54, v2
	s_nop 0
	v_cndmask_b32_e32 v101, v203, v101, vcc
	v_cmp_le_i32_e32 vcc, v3, v173
	v_subrev_u32_e32 v3, 53, v2
	s_nop 0
	v_cndmask_b32_e32 v102, v203, v102, vcc
	v_cmp_le_i32_e32 vcc, v3, v173
	v_subrev_u32_e32 v3, 48, v2
	s_nop 0
	v_cndmask_b32_e32 v103, v203, v103, vcc
	v_cmp_le_i32_e32 vcc, v3, v173
	v_subrev_u32_e32 v3, 47, v2
	s_nop 0
	v_cndmask_b32_e32 v104, v203, v104, vcc
	v_cmp_le_i32_e32 vcc, v3, v173
	v_subrev_u32_e32 v3, 46, v2
	s_nop 0
	v_cndmask_b32_e32 v105, v203, v105, vcc
	v_cmp_le_i32_e32 vcc, v3, v173
	v_subrev_u32_e32 v3, 45, v2
	s_nop 0
	v_cndmask_b32_e32 v106, v203, v106, vcc
	v_cmp_le_i32_e32 vcc, v3, v173
	v_subrev_u32_e32 v3, 40, v2
	s_nop 0
	v_cndmask_b32_e32 v107, v203, v107, vcc
	v_cmp_le_i32_e32 vcc, v3, v173
	v_subrev_u32_e32 v3, 39, v2
	s_nop 0
	v_cndmask_b32_e32 v108, v203, v108, vcc
	v_cmp_le_i32_e32 vcc, v3, v173
	v_subrev_u32_e32 v3, 38, v2
	s_nop 0
	v_cndmask_b32_e32 v109, v203, v109, vcc
	v_cmp_le_i32_e32 vcc, v3, v173
	v_subrev_u32_e32 v3, 37, v2
	s_nop 0
	v_cndmask_b32_e32 v110, v203, v110, vcc
	v_cmp_le_i32_e32 vcc, v3, v173
	v_subrev_u32_e32 v3, 32, v2
	s_nop 0
	v_cndmask_b32_e32 v111, v203, v111, vcc
	v_cmp_le_i32_e32 vcc, v3, v173
	v_subrev_u32_e32 v3, 31, v2
	s_nop 0
	v_cndmask_b32_e32 v48, v203, v48, vcc
	v_cmp_le_i32_e32 vcc, v3, v173
	v_subrev_u32_e32 v3, 30, v2
	s_nop 0
	v_cndmask_b32_e32 v49, v203, v49, vcc
	v_cmp_le_i32_e32 vcc, v3, v173
	v_subrev_u32_e32 v3, 29, v2
	s_nop 0
	v_cndmask_b32_e32 v50, v203, v50, vcc
	v_cmp_le_i32_e32 vcc, v3, v173
	v_subrev_u32_e32 v3, 24, v2
	s_nop 0
	v_cndmask_b32_e32 v51, v203, v51, vcc
	v_cmp_le_i32_e32 vcc, v3, v173
	v_subrev_u32_e32 v3, 23, v2
	s_nop 0
	v_cndmask_b32_e32 v52, v203, v52, vcc
	v_cmp_le_i32_e32 vcc, v3, v173
	v_subrev_u32_e32 v3, 22, v2
	s_nop 0
	v_cndmask_b32_e32 v53, v203, v53, vcc
	v_cmp_le_i32_e32 vcc, v3, v173
	v_subrev_u32_e32 v3, 21, v2
	s_nop 0
	v_cndmask_b32_e32 v54, v203, v54, vcc
	v_cmp_le_i32_e32 vcc, v3, v173
	v_add_u32_e32 v3, -16, v2
	s_nop 0
	v_cndmask_b32_e32 v55, v203, v55, vcc
	v_cmp_le_i32_e32 vcc, v3, v173
	v_add_u32_e32 v3, -15, v2
	s_nop 0
	v_cndmask_b32_e32 v56, v203, v56, vcc
	v_cmp_le_i32_e32 vcc, v3, v173
	v_add_u32_e32 v3, -14, v2
	s_nop 0
	v_cndmask_b32_e32 v57, v203, v57, vcc
	v_cmp_le_i32_e32 vcc, v3, v173
	v_add_u32_e32 v3, -13, v2
	s_nop 0
	v_cndmask_b32_e32 v58, v203, v58, vcc
	v_cmp_le_i32_e32 vcc, v3, v173
	v_add_u32_e32 v3, -8, v2
	s_nop 0
	v_cndmask_b32_e32 v59, v203, v59, vcc
	v_cmp_le_i32_e32 vcc, v3, v173
	v_add_u32_e32 v3, -7, v2
	s_nop 0
	v_cndmask_b32_e32 v60, v203, v60, vcc
	v_cmp_le_i32_e32 vcc, v3, v173
	v_add_u32_e32 v3, -6, v2
	v_add_u32_e32 v2, -5, v2
	v_cndmask_b32_e32 v61, v203, v61, vcc
	v_cmp_le_i32_e32 vcc, v3, v173
	s_nop 1
	v_cndmask_b32_e32 v62, v203, v62, vcc
	v_cmp_le_i32_e32 vcc, v2, v173
	s_nop 1
	v_cndmask_b32_e32 v63, v203, v63, vcc
	v_max_f32_e32 v2, v81, v81
	v_max_f32_e32 v3, v80, v80
	v_max_f32_e32 v2, v3, v2
	v_max3_f32 v2, v2, v82, v83
	v_max3_f32 v2, v2, v84, v85
	v_max3_f32 v2, v2, v86, v87
	v_max3_f32 v2, v2, v88, v89
	v_max3_f32 v2, v2, v90, v91
	v_max3_f32 v2, v2, v92, v93
	v_max3_f32 v2, v2, v94, v95
	v_max3_f32 v2, v2, v64, v65
	v_max3_f32 v2, v2, v66, v67
	v_max3_f32 v2, v2, v68, v69
	v_max3_f32 v2, v2, v70, v71
	v_max3_f32 v2, v2, v72, v73
	v_max3_f32 v2, v2, v74, v75
	v_max3_f32 v2, v2, v76, v77
	v_max3_f32 v2, v2, v78, v79
	v_max3_f32 v2, v2, v96, v97
	v_max3_f32 v2, v2, v98, v99
	v_max3_f32 v2, v2, v100, v101
	v_max3_f32 v2, v2, v102, v103
	v_max3_f32 v2, v2, v104, v105
	v_max3_f32 v2, v2, v106, v107
	v_max3_f32 v2, v2, v108, v109
	v_max3_f32 v2, v2, v110, v111
	v_max3_f32 v2, v2, v48, v49
	v_max3_f32 v2, v2, v50, v51
	v_max3_f32 v2, v2, v52, v53
	v_max3_f32 v2, v2, v54, v55
	v_max3_f32 v2, v2, v56, v57
	v_max3_f32 v2, v2, v58, v59
	v_max3_f32 v2, v2, v60, v61
	v_max3_f32 v2, v2, v62, v63
	v_mov_b32_e32 v3, v2
	s_nop 1
	v_permlane32_swap_b32_e32 v2, v3
	v_max_f32_e32 v2, v2, v3
	v_cmp_lt_f32_e32 vcc, 0, v2
	s_cbranch_vccz .Lat1_pvnr
	v_max_f32_e32 v2, v2, v2
	v_max_f32_e32 v2, 0, v2
	v_exp_f32_e64 v4, -v2
	v_add_f32_e32 v0, v0, v2
	v_pk_add_f32 v[80:81], v[80:81], v[2:3] op_sel_hi:[1,0] neg_lo:[0,1] neg_hi:[0,1]
	v_pk_add_f32 v[64:65], v[64:65], v[2:3] op_sel_hi:[1,0] neg_lo:[0,1] neg_hi:[0,1]
	v_pk_add_f32 v[96:97], v[96:97], v[2:3] op_sel_hi:[1,0] neg_lo:[0,1] neg_hi:[0,1]
	v_pk_add_f32 v[48:49], v[48:49], v[2:3] op_sel_hi:[1,0] neg_lo:[0,1] neg_hi:[0,1]
	v_pk_add_f32 v[82:83], v[82:83], v[2:3] op_sel_hi:[1,0] neg_lo:[0,1] neg_hi:[0,1]
	v_pk_add_f32 v[66:67], v[66:67], v[2:3] op_sel_hi:[1,0] neg_lo:[0,1] neg_hi:[0,1]
	v_pk_add_f32 v[98:99], v[98:99], v[2:3] op_sel_hi:[1,0] neg_lo:[0,1] neg_hi:[0,1]
	v_pk_add_f32 v[50:51], v[50:51], v[2:3] op_sel_hi:[1,0] neg_lo:[0,1] neg_hi:[0,1]
	v_pk_add_f32 v[84:85], v[84:85], v[2:3] op_sel_hi:[1,0] neg_lo:[0,1] neg_hi:[0,1]
	v_pk_add_f32 v[68:69], v[68:69], v[2:3] op_sel_hi:[1,0] neg_lo:[0,1] neg_hi:[0,1]
	v_pk_add_f32 v[100:101], v[100:101], v[2:3] op_sel_hi:[1,0] neg_lo:[0,1] neg_hi:[0,1]
	v_pk_add_f32 v[52:53], v[52:53], v[2:3] op_sel_hi:[1,0] neg_lo:[0,1] neg_hi:[0,1]
	v_pk_add_f32 v[86:87], v[86:87], v[2:3] op_sel_hi:[1,0] neg_lo:[0,1] neg_hi:[0,1]
	v_pk_add_f32 v[70:71], v[70:71], v[2:3] op_sel_hi:[1,0] neg_lo:[0,1] neg_hi:[0,1]
	v_pk_add_f32 v[102:103], v[102:103], v[2:3] op_sel_hi:[1,0] neg_lo:[0,1] neg_hi:[0,1]
	v_pk_add_f32 v[54:55], v[54:55], v[2:3] op_sel_hi:[1,0] neg_lo:[0,1] neg_hi:[0,1]
	v_pk_add_f32 v[88:89], v[88:89], v[2:3] op_sel_hi:[1,0] neg_lo:[0,1] neg_hi:[0,1]
	v_pk_add_f32 v[72:73], v[72:73], v[2:3] op_sel_hi:[1,0] neg_lo:[0,1] neg_hi:[0,1]
	v_pk_add_f32 v[104:105], v[104:105], v[2:3] op_sel_hi:[1,0] neg_lo:[0,1] neg_hi:[0,1]
	v_pk_add_f32 v[56:57], v[56:57], v[2:3] op_sel_hi:[1,0] neg_lo:[0,1] neg_hi:[0,1]
	v_pk_add_f32 v[90:91], v[90:91], v[2:3] op_sel_hi:[1,0] neg_lo:[0,1] neg_hi:[0,1]
	v_pk_add_f32 v[74:75], v[74:75], v[2:3] op_sel_hi:[1,0] neg_lo:[0,1] neg_hi:[0,1]
	v_pk_add_f32 v[106:107], v[106:107], v[2:3] op_sel_hi:[1,0] neg_lo:[0,1] neg_hi:[0,1]
	v_pk_add_f32 v[58:59], v[58:59], v[2:3] op_sel_hi:[1,0] neg_lo:[0,1] neg_hi:[0,1]
	v_pk_add_f32 v[92:93], v[92:93], v[2:3] op_sel_hi:[1,0] neg_lo:[0,1] neg_hi:[0,1]
	v_pk_add_f32 v[76:77], v[76:77], v[2:3] op_sel_hi:[1,0] neg_lo:[0,1] neg_hi:[0,1]
	v_pk_add_f32 v[108:109], v[108:109], v[2:3] op_sel_hi:[1,0] neg_lo:[0,1] neg_hi:[0,1]
	v_pk_add_f32 v[60:61], v[60:61], v[2:3] op_sel_hi:[1,0] neg_lo:[0,1] neg_hi:[0,1]
	v_pk_add_f32 v[94:95], v[94:95], v[2:3] op_sel_hi:[1,0] neg_lo:[0,1] neg_hi:[0,1]
	v_pk_add_f32 v[78:79], v[78:79], v[2:3] op_sel_hi:[1,0] neg_lo:[0,1] neg_hi:[0,1]
	v_pk_add_f32 v[110:111], v[110:111], v[2:3] op_sel_hi:[1,0] neg_lo:[0,1] neg_hi:[0,1]
	v_pk_add_f32 v[62:63], v[62:63], v[2:3] op_sel_hi:[1,0] neg_lo:[0,1] neg_hi:[0,1]
	v_pk_mul_f32 v[46:47], v[46:47], v[4:5] op_sel_hi:[1,0]
	v_pk_mul_f32 v[44:45], v[44:45], v[4:5] op_sel_hi:[1,0]
	v_pk_mul_f32 v[42:43], v[42:43], v[4:5] op_sel_hi:[1,0]
	v_pk_mul_f32 v[40:41], v[40:41], v[4:5] op_sel_hi:[1,0]
	v_pk_mul_f32 v[38:39], v[38:39], v[4:5] op_sel_hi:[1,0]
	v_pk_mul_f32 v[36:37], v[36:37], v[4:5] op_sel_hi:[1,0]
	v_pk_mul_f32 v[34:35], v[34:35], v[4:5] op_sel_hi:[1,0]
	v_pk_mul_f32 v[32:33], v[32:33], v[4:5] op_sel_hi:[1,0]
	v_pk_mul_f32 v[30:31], v[30:31], v[4:5] op_sel_hi:[1,0]
	v_pk_mul_f32 v[28:29], v[28:29], v[4:5] op_sel_hi:[1,0]
	v_pk_mul_f32 v[26:27], v[26:27], v[4:5] op_sel_hi:[1,0]
	v_pk_mul_f32 v[24:25], v[24:25], v[4:5] op_sel_hi:[1,0]
	v_pk_mul_f32 v[22:23], v[22:23], v[4:5] op_sel_hi:[1,0]
	v_pk_mul_f32 v[20:21], v[20:21], v[4:5] op_sel_hi:[1,0]
	v_pk_mul_f32 v[18:19], v[18:19], v[4:5] op_sel_hi:[1,0]
	v_pk_mul_f32 v[16:17], v[16:17], v[4:5] op_sel_hi:[1,0]
	v_mul_f32_e32 v159, v159, v4
.Lat1_pvnr:
	v_exp_f32_e32 v80, v80
	v_exp_f32_e32 v81, v81
	v_exp_f32_e32 v82, v82
	v_exp_f32_e32 v83, v83
	v_exp_f32_e32 v84, v84
	v_exp_f32_e32 v85, v85
	v_exp_f32_e32 v86, v86
	v_exp_f32_e32 v87, v87
	v_cvt_pk_bf16_f32 v2, v80, v81
	v_cvt_pk_bf16_f32 v3, v82, v83
	v_cvt_pk_bf16_f32 v4, v84, v85
	v_cvt_pk_bf16_f32 v5, v86, v87
	v_add_f32_e32 v12, v80, v84
	v_add_f32_e32 v13, v81, v85
	v_add_f32_e32 v14, v82, v86
	v_add_f32_e32 v15, v83, v87
	s_waitcnt lgkmcnt(6)
	v_mfma_f32_32x32x16_bf16 v[32:47], v[222:225], v[2:5], v[32:47]
	v_exp_f32_e32 v88, v88
	v_exp_f32_e32 v89, v89
	v_exp_f32_e32 v90, v90
	v_exp_f32_e32 v91, v91
	v_cvt_pk_bf16_f32 v6, v88, v89
	v_cvt_pk_bf16_f32 v7, v90, v91
	v_add_f32_e32 v12, v12, v88
	v_add_f32_e32 v13, v13, v89
	v_add_f32_e32 v14, v14, v90
	v_add_f32_e32 v15, v15, v91
	s_waitcnt lgkmcnt(5)
	v_mfma_f32_32x32x16_bf16 v[16:31], v[226:229], v[2:5], v[16:31]
	v_exp_f32_e32 v92, v92
	v_exp_f32_e32 v93, v93
	v_exp_f32_e32 v94, v94
	v_exp_f32_e32 v95, v95
	v_cvt_pk_bf16_f32 v8, v92, v93
	v_cvt_pk_bf16_f32 v9, v94, v95
	v_add_f32_e32 v12, v12, v92
	v_add_f32_e32 v13, v13, v93
	v_add_f32_e32 v14, v14, v94
	v_add_f32_e32 v15, v15, v95
	ds_read_b128 v[222:225], v238 offset:62048
	ds_read_b128 v[226:229], v238 offset:53376
	s_waitcnt lgkmcnt(6)
	v_mfma_f32_32x32x16_bf16 v[32:47], v[230:233], v[6:9], v[32:47]
	v_exp_f32_e32 v64, v64
	v_exp_f32_e32 v65, v65
	v_exp_f32_e32 v66, v66
	v_exp_f32_e32 v67, v67
	v_cvt_pk_bf16_f32 v2, v64, v65
	v_cvt_pk_bf16_f32 v3, v66, v67
	v_add_f32_e32 v12, v12, v64
	v_add_f32_e32 v13, v13, v65
	v_add_f32_e32 v14, v14, v66
	v_add_f32_e32 v15, v15, v67
	s_waitcnt lgkmcnt(5)
	v_mfma_f32_32x32x16_bf16 v[16:31], v[234:237], v[6:9], v[16:31]
	v_exp_f32_e32 v68, v68
	v_exp_f32_e32 v69, v69
	v_exp_f32_e32 v70, v70
	v_exp_f32_e32 v71, v71
	v_cvt_pk_bf16_f32 v4, v68, v69
	v_cvt_pk_bf16_f32 v5, v70, v71
	v_add_f32_e32 v12, v12, v68
	v_add_f32_e32 v13, v13, v69
	v_add_f32_e32 v14, v14, v70
	v_add_f32_e32 v15, v15, v71
	ds_read_b128 v[230:233], v238 offset:62080
	ds_read_b128 v[234:237], v238 offset:53408
	s_waitcnt lgkmcnt(6)
	v_mfma_f32_32x32x16_bf16 v[32:47], v[242:245], v[2:5], v[32:47]
	v_exp_f32_e32 v72, v72
	v_exp_f32_e32 v73, v73
	v_exp_f32_e32 v74, v74
	v_exp_f32_e32 v75, v75
	v_cvt_pk_bf16_f32 v6, v72, v73
	v_cvt_pk_bf16_f32 v7, v74, v75
	v_add_f32_e32 v12, v12, v72
	v_add_f32_e32 v13, v13, v73
	v_add_f32_e32 v14, v14, v74
	v_add_f32_e32 v15, v15, v75
	s_waitcnt lgkmcnt(5)
	v_mfma_f32_32x32x16_bf16 v[16:31], v[246:249], v[2:5], v[16:31]
	v_exp_f32_e32 v76, v76
	v_exp_f32_e32 v77, v77
	v_exp_f32_e32 v78, v78
	v_exp_f32_e32 v79, v79
	v_cvt_pk_bf16_f32 v8, v76, v77
	v_cvt_pk_bf16_f32 v9, v78, v79
	v_add_f32_e32 v12, v12, v76
	v_add_f32_e32 v13, v13, v77
	v_add_f32_e32 v14, v14, v78
	v_add_f32_e32 v15, v15, v79
	ds_read_b128 v[242:245], v238 offset:62112
	ds_read_b128 v[246:249], v238 offset:53440
	s_waitcnt lgkmcnt(6)
	v_mfma_f32_32x32x16_bf16 v[32:47], v[250:253], v[6:9], v[32:47]
	v_exp_f32_e32 v96, v96
	v_exp_f32_e32 v97, v97
	v_exp_f32_e32 v98, v98
	v_exp_f32_e32 v99, v99
	v_cvt_pk_bf16_f32 v2, v96, v97
	v_cvt_pk_bf16_f32 v3, v98, v99
	v_add_f32_e32 v12, v12, v96
	v_add_f32_e32 v13, v13, v97
	v_add_f32_e32 v14, v14, v98
	v_add_f32_e32 v15, v15, v99
	s_waitcnt lgkmcnt(5)
	v_mfma_f32_32x32x16_bf16 v[16:31], v[222:225], v[6:9], v[16:31]
	v_exp_f32_e32 v100, v100
	v_exp_f32_e32 v101, v101
	v_exp_f32_e32 v102, v102
	v_exp_f32_e32 v103, v103
	v_cvt_pk_bf16_f32 v4, v100, v101
	v_cvt_pk_bf16_f32 v5, v102, v103
	v_add_f32_e32 v12, v12, v100
	v_add_f32_e32 v13, v13, v101
	v_add_f32_e32 v14, v14, v102
	v_add_f32_e32 v15, v15, v103
	ds_read_b128 v[250:253], v238 offset:62144
	ds_read_b128 v[222:225], v238 offset:53472
	s_waitcnt lgkmcnt(6)
	v_mfma_f32_32x32x16_bf16 v[32:47], v[226:229], v[2:5], v[32:47]
	v_exp_f32_e32 v104, v104
	v_exp_f32_e32 v105, v105
	v_exp_f32_e32 v106, v106
	v_exp_f32_e32 v107, v107
	v_cvt_pk_bf16_f32 v6, v104, v105
	v_cvt_pk_bf16_f32 v7, v106, v107
	v_add_f32_e32 v12, v12, v104
	v_add_f32_e32 v13, v13, v105
	v_add_f32_e32 v14, v14, v106
	v_add_f32_e32 v15, v15, v107
	s_waitcnt lgkmcnt(5)
	v_mfma_f32_32x32x16_bf16 v[16:31], v[230:233], v[2:5], v[16:31]
	v_exp_f32_e32 v108, v108
	v_exp_f32_e32 v109, v109
	v_exp_f32_e32 v110, v110
	v_exp_f32_e32 v111, v111
	v_cvt_pk_bf16_f32 v8, v108, v109
	v_cvt_pk_bf16_f32 v9, v110, v111
	v_add_f32_e32 v12, v12, v108
	v_add_f32_e32 v13, v13, v109
	v_add_f32_e32 v14, v14, v110
	v_add_f32_e32 v15, v15, v111
	ds_read_b128 v[226:229], v238 offset:62176
	s_waitcnt lgkmcnt(5)
	v_mfma_f32_32x32x16_bf16 v[32:47], v[234:237], v[6:9], v[32:47]
	v_exp_f32_e32 v48, v48
	v_exp_f32_e32 v49, v49
	v_exp_f32_e32 v50, v50
	v_exp_f32_e32 v51, v51
	v_cvt_pk_bf16_f32 v2, v48, v49
	v_cvt_pk_bf16_f32 v3, v50, v51
	v_add_f32_e32 v12, v12, v48
	v_add_f32_e32 v13, v13, v49
	v_add_f32_e32 v14, v14, v50
	v_add_f32_e32 v15, v15, v51
	s_waitcnt lgkmcnt(4)
	v_mfma_f32_32x32x16_bf16 v[16:31], v[242:245], v[6:9], v[16:31]
	v_exp_f32_e32 v52, v52
	v_exp_f32_e32 v53, v53
	v_exp_f32_e32 v54, v54
	v_exp_f32_e32 v55, v55
	v_cvt_pk_bf16_f32 v4, v52, v53
	v_cvt_pk_bf16_f32 v5, v54, v55
	v_add_f32_e32 v12, v12, v52
	v_add_f32_e32 v13, v13, v53
	v_add_f32_e32 v14, v14, v54
	v_add_f32_e32 v15, v15, v55
	s_waitcnt lgkmcnt(3)
	v_mfma_f32_32x32x16_bf16 v[32:47], v[246:249], v[2:5], v[32:47]
	v_exp_f32_e32 v56, v56
	v_exp_f32_e32 v57, v57
	v_exp_f32_e32 v58, v58
	v_exp_f32_e32 v59, v59
	v_cvt_pk_bf16_f32 v6, v56, v57
	v_cvt_pk_bf16_f32 v7, v58, v59
	v_add_f32_e32 v12, v12, v56
	v_add_f32_e32 v13, v13, v57
	v_add_f32_e32 v14, v14, v58
	v_add_f32_e32 v15, v15, v59
	s_waitcnt lgkmcnt(2)
	v_mfma_f32_32x32x16_bf16 v[16:31], v[250:253], v[2:5], v[16:31]
	v_exp_f32_e32 v60, v60
	v_exp_f32_e32 v61, v61
	v_exp_f32_e32 v62, v62
	v_exp_f32_e32 v63, v63
	v_cvt_pk_bf16_f32 v8, v60, v61
	v_cvt_pk_bf16_f32 v9, v62, v63
	v_add_f32_e32 v12, v12, v60
	v_add_f32_e32 v13, v13, v61
	v_add_f32_e32 v14, v14, v62
	v_add_f32_e32 v15, v15, v63
	s_waitcnt lgkmcnt(1)
	v_mfma_f32_32x32x16_bf16 v[32:47], v[222:225], v[6:9], v[32:47]
	s_waitcnt lgkmcnt(0)
	v_mfma_f32_32x32x16_bf16 v[16:31], v[226:229], v[6:9], v[16:31]
	v_add_f32_e32 v12, v12, v13
	v_add_f32_e32 v14, v14, v15
	v_add_f32_e32 v12, v12, v14
	v_add_f32_e32 v159, v159, v12

.Lat1_wm3:
	s_mov_b32 s101, s13
	s_mul_i32 s13, s13, 0x4400
	s_mul_i32 s12, s12, 0x6800
	v_add3_u32 v2, s12, v165, v162
	s_waitcnt vmcnt(4)
	ds_write_b128 v2, v[136:139]
	v_add3_u32 v2, s12, v210, v168
	s_waitcnt vmcnt(3)
	ds_write_b128 v2, v[140:143]
	v_add3_u32 v2, s12, v211, v172
	s_waitcnt vmcnt(2)
	ds_write_b128 v2, v[144:147]
	v_lshl_add_u32 v2, v163, 1, s13
	v_add_u32_e32 v3, v2, v212
	v_add_u32_e32 v2, v2, v213
	s_waitcnt vmcnt(1)
	ds_write2_b64 v3, v[148:149], v[150:151] offset1:2
	s_waitcnt vmcnt(0)
	ds_write2_b64 v2, v[152:153], v[154:155] offset1:2
	s_branch .Lat1_adv

.Lat1_adv:
	s_addk_i32 s44, 0x80
	s_mov_b32 s18, s16
	s_cmp_lt_u32 s18, s99
	s_cbranch_scc1 .Lat1_loop
	s_cmp_eq_u32 s98, 1
	s_cbranch_scc1 .Lat1_pv
	s_branch .LBB0_1418

.LBB0_1499:
	v_readfirstlane_b32 s46, v64
	s_xor_b32 m0, s45, 1
	s_mul_i32 m0, m0, 0xc000
	s_add_i32 s46, s46, m0
	s_mul_i32 s45, s45, 0xc000
	s_add_i32 s45, s45, 0
	v_add3_u32 v147, s45, v142, v143
	v_add_u32_e32 v168, v147, v145
	v_add3_u32 v172, s45, v144, v143
	v_add_u32_e32 v173, v172, v145
	ds_read_b128 v[148:151], v168 offset:32768
	ds_read_b128 v[152:155], v168 offset:34816
	ds_read_b128 v[164:167], v168 offset:36864
	ds_read_b128 v[168:171], v168 offset:38912
	ds_read_b128 v[156:159], v173
	ds_read_b128 v[160:163], v173 offset:2048
	ds_read_b128 v[242:245], v173 offset:4096
	ds_read_b128 v[246:249], v173 offset:6144
	s_mov_b32 m0, s46
	v_lshl_add_u64 v[254:255], v[130:131], 0, s[12:13]
	global_load_lds_dwordx4 v[254:255], off
	s_add_i32 m0, s46, 0x2000
	v_lshl_add_u64 v[254:255], v[132:133], 0, s[12:13]
	global_load_lds_dwordx4 v[254:255], off
	s_waitcnt lgkmcnt(2)
	v_mfma_f32_16x16x32_bf16 v[60:63], v[148:151], v[156:159], v[60:63]
	v_add_u32_e32 v147, v147, v146
	v_add_u32_e32 v172, v172, v146
	v_mfma_f32_16x16x32_bf16 v[44:47], v[148:151], v[160:163], v[44:47]
	v_mfma_f32_16x16x32_bf16 v[56:59], v[152:155], v[156:159], v[56:59]
	v_mfma_f32_16x16x32_bf16 v[40:43], v[152:155], v[160:163], v[40:43]
	s_add_i32 m0, s46, 0x4000
	v_lshl_add_u64 v[254:255], v[134:135], 0, s[12:13]
	global_load_lds_dwordx4 v[254:255], off
	v_mfma_f32_16x16x32_bf16 v[52:55], v[164:167], v[156:159], v[52:55]
	v_mfma_f32_16x16x32_bf16 v[36:39], v[164:167], v[160:163], v[36:39]
	v_mfma_f32_16x16x32_bf16 v[48:51], v[168:171], v[156:159], v[48:51]
	v_mfma_f32_16x16x32_bf16 v[32:35], v[168:171], v[160:163], v[32:35]
	s_add_i32 m0, s46, 0x6000
	v_lshl_add_u64 v[254:255], v[136:137], 0, s[12:13]
	global_load_lds_dwordx4 v[254:255], off
	ds_read_b128 v[156:159], v172
	ds_read_b128 v[160:163], v172 offset:2048
	s_waitcnt lgkmcnt(2)
	v_mfma_f32_16x16x32_bf16 v[28:31], v[148:151], v[242:245], v[28:31]
	v_mfma_f32_16x16x32_bf16 v[12:15], v[148:151], v[246:249], v[12:15]
	ds_read_b128 v[148:151], v147 offset:32768
	v_mfma_f32_16x16x32_bf16 v[24:27], v[152:155], v[242:245], v[24:27]
	v_mfma_f32_16x16x32_bf16 v[4:7], v[152:155], v[246:249], v[4:7]
	s_add_i32 m0, s46, 0x8000
	v_lshl_add_u64 v[254:255], v[138:139], 0, s[12:13]
	global_load_lds_dwordx4 v[254:255], off
	ds_read_b128 v[152:155], v147 offset:34816
	v_mfma_f32_16x16x32_bf16 v[20:23], v[164:167], v[242:245], v[20:23]
	v_mfma_f32_16x16x32_bf16 v[0:3], v[164:167], v[246:249], v[0:3]
	ds_read_b128 v[164:167], v147 offset:36864
	v_mfma_f32_16x16x32_bf16 v[16:19], v[168:171], v[242:245], v[16:19]
	v_mfma_f32_16x16x32_bf16 v[8:11], v[168:171], v[246:249], v[8:11]
	s_add_i32 m0, s46, 0xa000
	v_lshl_add_u64 v[254:255], v[140:141], 0, s[12:13]
	global_load_lds_dwordx4 v[254:255], off
	s_add_u32 s12, s12, 0x80
	s_addc_u32 s13, s13, 0
	s_add_i32 s3, s3, 1
	s_cmpk_lg_i32 s12, 0x800
	ds_read_b128 v[168:171], v147 offset:38912
	ds_read_b128 v[242:245], v172 offset:4096
	ds_read_b128 v[246:249], v172 offset:6144
	s_waitcnt lgkmcnt(2)
	v_mfma_f32_16x16x32_bf16 v[60:63], v[148:151], v[156:159], v[60:63]
	v_mfma_f32_16x16x32_bf16 v[44:47], v[148:151], v[160:163], v[44:47]
	v_mfma_f32_16x16x32_bf16 v[56:59], v[152:155], v[156:159], v[56:59]
	v_mfma_f32_16x16x32_bf16 v[40:43], v[152:155], v[160:163], v[40:43]
	v_mfma_f32_16x16x32_bf16 v[52:55], v[164:167], v[156:159], v[52:55]
	v_mfma_f32_16x16x32_bf16 v[36:39], v[164:167], v[160:163], v[36:39]
	v_mfma_f32_16x16x32_bf16 v[48:51], v[168:171], v[156:159], v[48:51]
	v_mfma_f32_16x16x32_bf16 v[32:35], v[168:171], v[160:163], v[32:35]
	s_waitcnt vmcnt(0)
	s_waitcnt vmcnt(0) lgkmcnt(0)
	v_mfma_f32_16x16x32_bf16 v[28:31], v[148:151], v[242:245], v[28:31]
	s_barrier
	v_mfma_f32_16x16x32_bf16 v[12:15], v[148:151], v[246:249], v[12:15]
	v_mfma_f32_16x16x32_bf16 v[24:27], v[152:155], v[242:245], v[24:27]
	v_mfma_f32_16x16x32_bf16 v[4:7], v[152:155], v[246:249], v[4:7]
	v_mfma_f32_16x16x32_bf16 v[20:23], v[164:167], v[242:245], v[20:23]
	v_mfma_f32_16x16x32_bf16 v[0:3], v[164:167], v[246:249], v[0:3]
	v_mfma_f32_16x16x32_bf16 v[16:19], v[168:171], v[242:245], v[16:19]
	v_mfma_f32_16x16x32_bf16 v[8:11], v[168:171], v[246:249], v[8:11]
	s_cbranch_scc0 .LBB0_1502
.LBB0_1500:
	s_and_b32 s45, s3, 1
	s_branch .LBB0_1499

.LBB0_1503:
	v_readfirstlane_b32 s46, v208
	s_xor_b32 m0, s45, 1
	s_mul_i32 m0, m0, 0xc000
	s_add_i32 s46, s46, m0
	s_mul_i32 s45, s45, 0xc000
	s_add_i32 s45, s45, 0
	v_add3_u32 v64, s45, v209, v210
	v_add_u32_e32 v234, v64, v212
	v_add3_u32 v238, s45, v211, v210
	v_add_u32_e32 v239, v238, v212
	ds_read_b128 v[214:217], v234 offset:32768
	ds_read_b128 v[218:221], v234 offset:34816
	ds_read_b128 v[230:233], v234 offset:36864
	ds_read_b128 v[234:237], v234 offset:38912
	ds_read_b128 v[222:225], v239
	ds_read_b128 v[226:229], v239 offset:2048
	ds_read_b128 v[242:245], v239 offset:4096
	ds_read_b128 v[246:249], v239 offset:6144
	s_mov_b32 m0, s46
	v_lshl_add_u64 v[254:255], v[130:131], 0, s[12:13]
	global_load_lds_dwordx4 v[254:255], off
	s_add_i32 m0, s46, 0x2000
	v_lshl_add_u64 v[254:255], v[132:133], 0, s[12:13]
	global_load_lds_dwordx4 v[254:255], off
	s_waitcnt lgkmcnt(2)
	v_mfma_f32_16x16x32_bf16 v[60:63], v[214:217], v[222:225], v[60:63]
	v_add_u32_e32 v64, v64, v213
	v_add_u32_e32 v238, v238, v213
	v_mfma_f32_16x16x32_bf16 v[44:47], v[214:217], v[226:229], v[44:47]
	v_mfma_f32_16x16x32_bf16 v[56:59], v[218:221], v[222:225], v[56:59]
	v_mfma_f32_16x16x32_bf16 v[40:43], v[218:221], v[226:229], v[40:43]
	s_add_i32 m0, s46, 0x4000
	v_lshl_add_u64 v[254:255], v[134:135], 0, s[12:13]
	global_load_lds_dwordx4 v[254:255], off
	v_mfma_f32_16x16x32_bf16 v[52:55], v[230:233], v[222:225], v[52:55]
	v_mfma_f32_16x16x32_bf16 v[36:39], v[230:233], v[226:229], v[36:39]
	v_mfma_f32_16x16x32_bf16 v[48:51], v[234:237], v[222:225], v[48:51]
	v_mfma_f32_16x16x32_bf16 v[32:35], v[234:237], v[226:229], v[32:35]
	s_add_i32 m0, s46, 0x6000
	v_lshl_add_u64 v[254:255], v[136:137], 0, s[12:13]
	global_load_lds_dwordx4 v[254:255], off
	ds_read_b128 v[222:225], v238
	ds_read_b128 v[226:229], v238 offset:2048
	s_waitcnt lgkmcnt(2)
	v_mfma_f32_16x16x32_bf16 v[28:31], v[214:217], v[242:245], v[28:31]
	v_mfma_f32_16x16x32_bf16 v[12:15], v[214:217], v[246:249], v[12:15]
	ds_read_b128 v[214:217], v64 offset:32768
	v_mfma_f32_16x16x32_bf16 v[24:27], v[218:221], v[242:245], v[24:27]
	v_mfma_f32_16x16x32_bf16 v[8:11], v[218:221], v[246:249], v[8:11]
	s_add_i32 m0, s46, 0x8000
	v_lshl_add_u64 v[254:255], v[138:139], 0, s[12:13]
	global_load_lds_dwordx4 v[254:255], off
	ds_read_b128 v[218:221], v64 offset:34816
	v_mfma_f32_16x16x32_bf16 v[20:23], v[230:233], v[242:245], v[20:23]
	v_mfma_f32_16x16x32_bf16 v[4:7], v[230:233], v[246:249], v[4:7]
	ds_read_b128 v[230:233], v64 offset:36864
	v_mfma_f32_16x16x32_bf16 v[16:19], v[234:237], v[242:245], v[16:19]
	v_mfma_f32_16x16x32_bf16 v[0:3], v[234:237], v[246:249], v[0:3]
	s_add_i32 m0, s46, 0xa000
	v_lshl_add_u64 v[254:255], v[140:141], 0, s[12:13]
	global_load_lds_dwordx4 v[254:255], off
	s_add_u32 s12, s12, 0x80
	s_addc_u32 s13, s13, 0
	s_add_i32 s3, s3, 1
	s_cmpk_lg_i32 s12, 0x400
	ds_read_b128 v[234:237], v64 offset:38912
	ds_read_b128 v[242:245], v238 offset:4096
	ds_read_b128 v[246:249], v238 offset:6144
	s_waitcnt lgkmcnt(2)
	v_mfma_f32_16x16x32_bf16 v[60:63], v[214:217], v[222:225], v[60:63]
	v_mfma_f32_16x16x32_bf16 v[44:47], v[214:217], v[226:229], v[44:47]
	v_mfma_f32_16x16x32_bf16 v[56:59], v[218:221], v[222:225], v[56:59]
	v_mfma_f32_16x16x32_bf16 v[40:43], v[218:221], v[226:229], v[40:43]
	v_mfma_f32_16x16x32_bf16 v[52:55], v[230:233], v[222:225], v[52:55]
	v_mfma_f32_16x16x32_bf16 v[36:39], v[230:233], v[226:229], v[36:39]
	v_mfma_f32_16x16x32_bf16 v[48:51], v[234:237], v[222:225], v[48:51]
	v_mfma_f32_16x16x32_bf16 v[32:35], v[234:237], v[226:229], v[32:35]
	s_waitcnt vmcnt(0)
	s_waitcnt vmcnt(0) lgkmcnt(0)
	v_mfma_f32_16x16x32_bf16 v[28:31], v[214:217], v[242:245], v[28:31]
	s_barrier
	v_mfma_f32_16x16x32_bf16 v[12:15], v[214:217], v[246:249], v[12:15]
	v_mfma_f32_16x16x32_bf16 v[24:27], v[218:221], v[242:245], v[24:27]
	v_mfma_f32_16x16x32_bf16 v[8:11], v[218:221], v[246:249], v[8:11]
	v_mfma_f32_16x16x32_bf16 v[20:23], v[230:233], v[242:245], v[20:23]
	v_mfma_f32_16x16x32_bf16 v[4:7], v[230:233], v[246:249], v[4:7]
	v_mfma_f32_16x16x32_bf16 v[16:19], v[234:237], v[242:245], v[16:19]
	v_mfma_f32_16x16x32_bf16 v[0:3], v[234:237], v[246:249], v[0:3]
	s_cbranch_scc0 .LBB0_1497

.LBB0_1531:
	v_readfirstlane_b32 s12, v146
	s_xor_b32 m0, s25, 1
	s_lshl_b32 m0, m0, 16
	s_add_i32 s12, s12, m0
	v_add3_u32 v128, s24, v147, v148
	v_add_u32_e32 v172, v128, v150
	v_add3_u32 v176, s24, v149, v148
	v_add_u32_e32 v177, v176, v150
	ds_read_b128 v[152:155], v172 offset:32768
	ds_read_b128 v[156:159], v172 offset:34816
	ds_read_b128 v[168:171], v172 offset:36864
	ds_read_b128 v[172:175], v172 offset:38912
	ds_read_b128 v[160:163], v177
	ds_read_b128 v[164:167], v177 offset:2048
	ds_read_b128 v[242:245], v177 offset:4096
	ds_read_b128 v[246:249], v177 offset:6144
	s_mov_b32 m0, s12
	v_lshl_add_u64 v[254:255], v[130:131], 0, s[10:11]
	global_load_lds_dwordx4 v[254:255], off
	s_add_i32 m0, s12, 0x2000
	v_lshl_add_u64 v[254:255], v[132:133], 0, s[10:11]
	global_load_lds_dwordx4 v[254:255], off
	s_waitcnt lgkmcnt(2)
	v_mfma_f32_16x16x32_bf16 v[124:127], v[152:155], v[160:163], v[124:127]
	v_add_u32_e32 v128, v128, v151
	v_add_u32_e32 v176, v176, v151
	v_mfma_f32_16x16x32_bf16 v[108:111], v[152:155], v[164:167], v[108:111]
	v_mfma_f32_16x16x32_bf16 v[120:123], v[156:159], v[160:163], v[120:123]
	v_mfma_f32_16x16x32_bf16 v[104:107], v[156:159], v[164:167], v[104:107]
	s_add_i32 m0, s12, 0x4000
	v_lshl_add_u64 v[254:255], v[134:135], 0, s[10:11]
	global_load_lds_dwordx4 v[254:255], off
	v_mfma_f32_16x16x32_bf16 v[116:119], v[168:171], v[160:163], v[116:119]
	v_mfma_f32_16x16x32_bf16 v[100:103], v[168:171], v[164:167], v[100:103]
	v_mfma_f32_16x16x32_bf16 v[112:115], v[172:175], v[160:163], v[112:115]
	v_mfma_f32_16x16x32_bf16 v[96:99], v[172:175], v[164:167], v[96:99]
	s_add_i32 m0, s12, 0x6000
	v_lshl_add_u64 v[254:255], v[136:137], 0, s[10:11]
	global_load_lds_dwordx4 v[254:255], off
	ds_read_b128 v[160:163], v177 offset:8192
	ds_read_b128 v[164:167], v177 offset:10240
	s_waitcnt lgkmcnt(2)
	v_mfma_f32_16x16x32_bf16 v[92:95], v[152:155], v[242:245], v[92:95]
	v_mfma_f32_16x16x32_bf16 v[76:79], v[152:155], v[246:249], v[76:79]
	v_mfma_f32_16x16x32_bf16 v[88:91], v[156:159], v[242:245], v[88:91]
	v_mfma_f32_16x16x32_bf16 v[72:75], v[156:159], v[246:249], v[72:75]
	s_add_i32 m0, s12, 0x8000
	v_lshl_add_u64 v[254:255], v[138:139], 0, s[10:11]
	global_load_lds_dwordx4 v[254:255], off
	v_mfma_f32_16x16x32_bf16 v[84:87], v[168:171], v[242:245], v[84:87]
	v_mfma_f32_16x16x32_bf16 v[68:71], v[168:171], v[246:249], v[68:71]
	v_mfma_f32_16x16x32_bf16 v[80:83], v[172:175], v[242:245], v[80:83]
	v_mfma_f32_16x16x32_bf16 v[64:67], v[172:175], v[246:249], v[64:67]
	s_add_i32 m0, s12, 0xa000
	v_lshl_add_u64 v[254:255], v[140:141], 0, s[10:11]
	global_load_lds_dwordx4 v[254:255], off
	ds_read_b128 v[242:245], v177 offset:12288
	ds_read_b128 v[246:249], v177 offset:14336
	s_waitcnt lgkmcnt(2)
	v_mfma_f32_16x16x32_bf16 v[60:63], v[152:155], v[160:163], v[60:63]
	v_mfma_f32_16x16x32_bf16 v[44:47], v[152:155], v[164:167], v[44:47]
	v_mfma_f32_16x16x32_bf16 v[56:59], v[156:159], v[160:163], v[56:59]
	v_mfma_f32_16x16x32_bf16 v[40:43], v[156:159], v[164:167], v[40:43]
	s_add_i32 m0, s12, 0xc000
	v_lshl_add_u64 v[254:255], v[142:143], 0, s[10:11]
	global_load_lds_dwordx4 v[254:255], off
	v_mfma_f32_16x16x32_bf16 v[52:55], v[168:171], v[160:163], v[52:55]
	v_mfma_f32_16x16x32_bf16 v[36:39], v[168:171], v[164:167], v[36:39]
	v_mfma_f32_16x16x32_bf16 v[48:51], v[172:175], v[160:163], v[48:51]
	v_mfma_f32_16x16x32_bf16 v[32:35], v[172:175], v[164:167], v[32:35]
	s_add_i32 m0, s12, 0xe000
	v_lshl_add_u64 v[254:255], v[144:145], 0, s[10:11]
	global_load_lds_dwordx4 v[254:255], off
	s_add_u32 s10, s10, 0x80
	s_addc_u32 s11, s11, 0
	s_add_i32 s9, s9, 1
	s_cmpk_lg_i32 s10, 0x800
	ds_read_b128 v[160:163], v176
	ds_read_b128 v[164:167], v176 offset:2048
	s_waitcnt lgkmcnt(2)
	v_mfma_f32_16x16x32_bf16 v[28:31], v[152:155], v[242:245], v[28:31]
	v_mfma_f32_16x16x32_bf16 v[8:11], v[152:155], v[246:249], v[8:11]
	ds_read_b128 v[152:155], v128 offset:32768
	v_mfma_f32_16x16x32_bf16 v[24:27], v[156:159], v[242:245], v[24:27]
	v_mfma_f32_16x16x32_bf16 v[4:7], v[156:159], v[246:249], v[4:7]
	ds_read_b128 v[156:159], v128 offset:34816
	v_mfma_f32_16x16x32_bf16 v[16:19], v[168:171], v[242:245], v[16:19]
	v_mfma_f32_16x16x32_bf16 v[0:3], v[168:171], v[246:249], v[0:3]
	ds_read_b128 v[168:171], v128 offset:36864
	v_mfma_f32_16x16x32_bf16 v[12:15], v[172:175], v[242:245], v[12:15]
	v_mfma_f32_16x16x32_bf16 v[20:23], v[172:175], v[246:249], v[20:23]
	ds_read_b128 v[172:175], v128 offset:38912
	ds_read_b128 v[242:245], v176 offset:4096
	ds_read_b128 v[246:249], v176 offset:6144
	s_waitcnt lgkmcnt(2)
	v_mfma_f32_16x16x32_bf16 v[124:127], v[152:155], v[160:163], v[124:127]
	v_mfma_f32_16x16x32_bf16 v[108:111], v[152:155], v[164:167], v[108:111]
	v_mfma_f32_16x16x32_bf16 v[120:123], v[156:159], v[160:163], v[120:123]
	v_mfma_f32_16x16x32_bf16 v[104:107], v[156:159], v[164:167], v[104:107]
	v_mfma_f32_16x16x32_bf16 v[116:119], v[168:171], v[160:163], v[116:119]
	v_mfma_f32_16x16x32_bf16 v[100:103], v[168:171], v[164:167], v[100:103]
	v_mfma_f32_16x16x32_bf16 v[112:115], v[172:175], v[160:163], v[112:115]
	v_mfma_f32_16x16x32_bf16 v[96:99], v[172:175], v[164:167], v[96:99]
	ds_read_b128 v[160:163], v176 offset:8192
	ds_read_b128 v[164:167], v176 offset:10240
	s_waitcnt lgkmcnt(2)
	v_mfma_f32_16x16x32_bf16 v[92:95], v[152:155], v[242:245], v[92:95]
	v_mfma_f32_16x16x32_bf16 v[76:79], v[152:155], v[246:249], v[76:79]
	v_mfma_f32_16x16x32_bf16 v[88:91], v[156:159], v[242:245], v[88:91]
	v_mfma_f32_16x16x32_bf16 v[72:75], v[156:159], v[246:249], v[72:75]
	v_mfma_f32_16x16x32_bf16 v[84:87], v[168:171], v[242:245], v[84:87]
	v_mfma_f32_16x16x32_bf16 v[68:71], v[168:171], v[246:249], v[68:71]
	v_mfma_f32_16x16x32_bf16 v[80:83], v[172:175], v[242:245], v[80:83]
	v_mfma_f32_16x16x32_bf16 v[64:67], v[172:175], v[246:249], v[64:67]
	ds_read_b128 v[242:245], v176 offset:12288
	ds_read_b128 v[246:249], v176 offset:14336
	s_waitcnt lgkmcnt(2)
	v_mfma_f32_16x16x32_bf16 v[60:63], v[152:155], v[160:163], v[60:63]
	v_mfma_f32_16x16x32_bf16 v[44:47], v[152:155], v[164:167], v[44:47]
	v_mfma_f32_16x16x32_bf16 v[56:59], v[156:159], v[160:163], v[56:59]
	v_mfma_f32_16x16x32_bf16 v[40:43], v[156:159], v[164:167], v[40:43]
	v_mfma_f32_16x16x32_bf16 v[52:55], v[168:171], v[160:163], v[52:55]
	v_mfma_f32_16x16x32_bf16 v[36:39], v[168:171], v[164:167], v[36:39]
	v_mfma_f32_16x16x32_bf16 v[48:51], v[172:175], v[160:163], v[48:51]
	v_mfma_f32_16x16x32_bf16 v[32:35], v[172:175], v[164:167], v[32:35]
	s_waitcnt vmcnt(0)
	s_waitcnt vmcnt(0) lgkmcnt(0)
	v_mfma_f32_16x16x32_bf16 v[28:31], v[152:155], v[242:245], v[28:31]
	s_barrier
	v_mfma_f32_16x16x32_bf16 v[8:11], v[152:155], v[246:249], v[8:11]
	v_mfma_f32_16x16x32_bf16 v[24:27], v[156:159], v[242:245], v[24:27]
	v_mfma_f32_16x16x32_bf16 v[4:7], v[156:159], v[246:249], v[4:7]
	v_mfma_f32_16x16x32_bf16 v[16:19], v[168:171], v[242:245], v[16:19]
	v_mfma_f32_16x16x32_bf16 v[0:3], v[168:171], v[246:249], v[0:3]
	v_mfma_f32_16x16x32_bf16 v[12:15], v[172:175], v[242:245], v[12:15]
	v_mfma_f32_16x16x32_bf16 v[20:23], v[172:175], v[246:249], v[20:23]
	s_cbranch_scc0 .LBB0_1528
.LBB0_1532:
	s_and_b32 s25, s9, 1
	s_lshl_b32 s24, s25, 16
	s_branch .LBB0_1531
.LBB0_1536:
	v_lshrrev_b32_e32 v131, 2, v198
	v_and_b32_e32 v130, 0xc0, v198
	v_and_b32_e32 v131, 12, v131
	v_or3_b32 v146, v130, v131, s8
	v_ashrrev_i32_e32 v130, 1, v198
	v_and_b32_e32 v130, 0xffffff80, v130
	v_lshl_add_u32 v134, s23, 8, v130
	v_and_or_b32 v132, v198, 15, v134
	v_ashrrev_i32_e32 v128, 13, v134
	v_mul_i32_i24_e32 v134, 0xc00, v128
	v_ashrrev_i32_e32 v133, 31, v132
	v_ashrrev_i32_e32 v135, 31, v134
	v_ashrrev_i32_e32 v147, 31, v146
	v_lshlrev_b64 v[130:131], 12, v[132:133]
	v_lshl_add_u64 v[134:135], v[134:135], 2, s[54:55]
	v_lshl_add_u64 v[134:135], v[134:135], 0, s[6:7]
	v_lshlrev_b64 v[136:137], 2, v[146:147]
	v_lshl_add_u64 v[148:149], v[134:135], 0, v[136:137]
	v_lshl_add_u64 v[150:151], s[52:53], 0, v[130:131]
	v_lshl_add_u64 v[150:151], v[150:151], 0, v[136:137]
	v_lshl_add_u64 v[154:155], s[52:53], 0, v[130:131]
	v_lshl_add_u64 v[154:155], v[154:155], 0, v[136:137]
	global_load_dwordx4 v[138:141], v[148:149], off
	global_load_dwordx4 v[142:145], v[148:149], off offset:64
	global_load_dwordx4 v[156:159], v[148:149], off offset:128
	global_load_dwordx4 v[160:163], v[148:149], off offset:192
	global_load_dwordx4 v[164:167], v[150:151], off
	global_load_dwordx4 v[168:171], v[150:151], off offset:64
	global_load_dwordx4 v[172:175], v[150:151], off offset:128
	global_load_dwordx4 v[242:245], v[150:151], off offset:192
	v_add_co_u32_e32 v150, vcc, 0x10000, v150
	s_nop 1
	v_addc_co_u32_e32 v151, vcc, 0, v151, vcc
	global_load_dwordx4 v[246:249], v[150:151], off
	global_load_dwordx4 v[250:253], v[150:151], off offset:64
	s_waitcnt vmcnt(5)
	v_pk_fma_f32 v[126:127], v[126:127], v[140:141], v[166:167]
	v_pk_fma_f32 v[124:125], v[124:125], v[138:139], v[164:165]
	global_store_dwordx4 v[154:155], v[124:127], off
	global_load_dwordx4 v[164:167], v[150:151], off offset:128
	s_waitcnt vmcnt(6)
	v_pk_fma_f32 v[122:123], v[122:123], v[144:145], v[170:171]
	v_pk_fma_f32 v[120:121], v[120:121], v[142:143], v[168:169]
	global_store_dwordx4 v[154:155], v[120:123], off offset:64
	global_load_dwordx4 v[168:171], v[150:151], off offset:192
	v_add_co_u32_e32 v150, vcc, 0x10000, v150
	s_nop 1
	v_addc_co_u32_e32 v151, vcc, 0, v151, vcc
	s_waitcnt vmcnt(7)
	v_pk_fma_f32 v[118:119], v[118:119], v[158:159], v[174:175]
	v_pk_fma_f32 v[116:117], v[116:117], v[156:157], v[172:173]
	global_store_dwordx4 v[154:155], v[116:119], off offset:128
	global_load_dwordx4 v[172:175], v[150:151], off
	s_waitcnt vmcnt(8)
	v_pk_fma_f32 v[114:115], v[114:115], v[162:163], v[244:245]
	v_pk_fma_f32 v[112:113], v[112:113], v[160:161], v[242:243]
	global_store_dwordx4 v[154:155], v[112:115], off offset:192
	s_nop 0
	v_add_co_u32_e32 v154, vcc, 0x10000, v154
	s_nop 1
	v_addc_co_u32_e32 v155, vcc, 0, v155, vcc
	global_load_dwordx4 v[242:245], v[150:151], off offset:64
	s_waitcnt vmcnt(9)
	v_pk_fma_f32 v[110:111], v[110:111], v[140:141], v[248:249]
	v_pk_fma_f32 v[108:109], v[108:109], v[138:139], v[246:247]
	global_store_dwordx4 v[154:155], v[108:111], off
	global_load_dwordx4 v[246:249], v[150:151], off offset:128
	s_waitcnt vmcnt(10)
	v_pk_fma_f32 v[106:107], v[106:107], v[144:145], v[252:253]
	v_pk_fma_f32 v[104:105], v[104:105], v[142:143], v[250:251]
	global_store_dwordx4 v[154:155], v[104:107], off offset:64
	global_load_dwordx4 v[250:253], v[150:151], off offset:192
	v_add_co_u32_e32 v150, vcc, 0x10000, v150
	s_nop 1
	v_addc_co_u32_e32 v151, vcc, 0, v151, vcc
	s_waitcnt vmcnt(10)
	v_pk_fma_f32 v[102:103], v[102:103], v[158:159], v[166:167]
	v_pk_fma_f32 v[100:101], v[100:101], v[156:157], v[164:165]
	global_store_dwordx4 v[154:155], v[100:103], off offset:128
	global_load_dwordx4 v[164:167], v[150:151], off
	s_waitcnt vmcnt(10)
	v_pk_fma_f32 v[98:99], v[98:99], v[162:163], v[170:171]
	v_pk_fma_f32 v[96:97], v[96:97], v[160:161], v[168:169]
	global_store_dwordx4 v[154:155], v[96:99], off offset:192
	s_nop 0
	v_add_co_u32_e32 v154, vcc, 0x10000, v154
	s_nop 1
	v_addc_co_u32_e32 v155, vcc, 0, v155, vcc
	global_load_dwordx4 v[168:171], v[150:151], off offset:64
	s_waitcnt vmcnt(10)
	v_pk_fma_f32 v[94:95], v[94:95], v[140:141], v[174:175]
	v_pk_fma_f32 v[92:93], v[92:93], v[138:139], v[172:173]
	global_store_dwordx4 v[154:155], v[92:95], off
	global_load_dwordx4 v[172:175], v[150:151], off offset:128
	s_waitcnt vmcnt(10)
	v_pk_fma_f32 v[90:91], v[90:91], v[144:145], v[244:245]
	v_pk_fma_f32 v[88:89], v[88:89], v[142:143], v[242:243]
	global_store_dwordx4 v[154:155], v[88:91], off offset:64
	global_load_dwordx4 v[242:245], v[150:151], off offset:192
	v_add_co_u32_e32 v150, vcc, 0x10000, v150
	s_nop 1
	v_addc_co_u32_e32 v151, vcc, 0, v151, vcc
	s_waitcnt vmcnt(10)
	v_pk_fma_f32 v[86:87], v[86:87], v[158:159], v[248:249]
	v_pk_fma_f32 v[84:85], v[84:85], v[156:157], v[246:247]
	global_store_dwordx4 v[154:155], v[84:87], off offset:128
	global_load_dwordx4 v[246:249], v[150:151], off
	s_waitcnt vmcnt(10)
	v_pk_fma_f32 v[82:83], v[82:83], v[162:163], v[252:253]
	v_pk_fma_f32 v[80:81], v[80:81], v[160:161], v[250:251]
	global_store_dwordx4 v[154:155], v[80:83], off offset:192
	s_nop 0
	v_add_co_u32_e32 v154, vcc, 0x10000, v154
	s_nop 1
	v_addc_co_u32_e32 v155, vcc, 0, v155, vcc
	global_load_dwordx4 v[250:253], v[150:151], off offset:64
	s_waitcnt vmcnt(10)
	v_pk_fma_f32 v[78:79], v[78:79], v[140:141], v[166:167]
	v_pk_fma_f32 v[76:77], v[76:77], v[138:139], v[164:165]
	global_store_dwordx4 v[154:155], v[76:79], off
	global_load_dwordx4 v[164:167], v[150:151], off offset:128
	s_waitcnt vmcnt(10)
	v_pk_fma_f32 v[74:75], v[74:75], v[144:145], v[170:171]
	v_pk_fma_f32 v[72:73], v[72:73], v[142:143], v[168:169]
	global_store_dwordx4 v[154:155], v[72:75], off offset:64
	global_load_dwordx4 v[168:171], v[150:151], off offset:192
	v_add_co_u32_e32 v150, vcc, 0x10000, v150
	s_nop 1
	v_addc_co_u32_e32 v151, vcc, 0, v151, vcc
	s_waitcnt vmcnt(10)
	v_pk_fma_f32 v[70:71], v[70:71], v[158:159], v[174:175]
	v_pk_fma_f32 v[68:69], v[68:69], v[156:157], v[172:173]
	global_store_dwordx4 v[154:155], v[68:71], off offset:128
	global_load_dwordx4 v[172:175], v[150:151], off
	s_waitcnt vmcnt(10)
	v_pk_fma_f32 v[66:67], v[66:67], v[162:163], v[244:245]
	v_pk_fma_f32 v[64:65], v[64:65], v[160:161], v[242:243]
	global_store_dwordx4 v[154:155], v[64:67], off offset:192
	s_nop 0
	v_add_co_u32_e32 v154, vcc, 0x10000, v154
	s_nop 1
	v_addc_co_u32_e32 v155, vcc, 0, v155, vcc
	global_load_dwordx4 v[242:245], v[150:151], off offset:64
	s_waitcnt vmcnt(10)
	v_pk_fma_f32 v[62:63], v[62:63], v[140:141], v[248:249]
	v_pk_fma_f32 v[60:61], v[60:61], v[138:139], v[246:247]
	global_store_dwordx4 v[154:155], v[60:63], off
	global_load_dwordx4 v[246:249], v[150:151], off offset:128
	s_waitcnt vmcnt(10)
	v_pk_fma_f32 v[58:59], v[58:59], v[144:145], v[252:253]
	v_pk_fma_f32 v[56:57], v[56:57], v[142:143], v[250:251]
	global_store_dwordx4 v[154:155], v[56:59], off offset:64
	global_load_dwordx4 v[250:253], v[150:151], off offset:192
	v_add_co_u32_e32 v150, vcc, 0x10000, v150
	s_nop 1
	v_addc_co_u32_e32 v151, vcc, 0, v151, vcc
	s_waitcnt vmcnt(10)
	v_pk_fma_f32 v[54:55], v[54:55], v[158:159], v[166:167]
	v_pk_fma_f32 v[52:53], v[52:53], v[156:157], v[164:165]
	global_store_dwordx4 v[154:155], v[52:55], off offset:128
	global_load_dwordx4 v[164:167], v[150:151], off
	s_waitcnt vmcnt(10)
	v_pk_fma_f32 v[50:51], v[50:51], v[162:163], v[170:171]
	v_pk_fma_f32 v[48:49], v[48:49], v[160:161], v[168:169]
	global_store_dwordx4 v[154:155], v[48:51], off offset:192
	s_nop 0
	v_add_co_u32_e32 v154, vcc, 0x10000, v154
	s_nop 1
	v_addc_co_u32_e32 v155, vcc, 0, v155, vcc
	global_load_dwordx4 v[168:171], v[150:151], off offset:64
	s_waitcnt vmcnt(10)
	v_pk_fma_f32 v[46:47], v[46:47], v[140:141], v[174:175]
	v_pk_fma_f32 v[44:45], v[44:45], v[138:139], v[172:173]
	global_store_dwordx4 v[154:155], v[44:47], off
	global_load_dwordx4 v[172:175], v[150:151], off offset:128
	s_waitcnt vmcnt(10)
	v_pk_fma_f32 v[42:43], v[42:43], v[144:145], v[244:245]
	v_pk_fma_f32 v[40:41], v[40:41], v[142:143], v[242:243]
	global_store_dwordx4 v[154:155], v[40:43], off offset:64
	global_load_dwordx4 v[242:245], v[150:151], off offset:192
	v_add_co_u32_e32 v150, vcc, 0x10000, v150
	s_nop 1
	v_addc_co_u32_e32 v151, vcc, 0, v151, vcc
	s_waitcnt vmcnt(10)
	v_pk_fma_f32 v[38:39], v[38:39], v[158:159], v[248:249]
	v_pk_fma_f32 v[36:37], v[36:37], v[156:157], v[246:247]
	global_store_dwordx4 v[154:155], v[36:39], off offset:128
	global_load_dwordx4 v[246:249], v[150:151], off
	s_waitcnt vmcnt(10)
	v_pk_fma_f32 v[34:35], v[34:35], v[162:163], v[252:253]
	v_pk_fma_f32 v[32:33], v[32:33], v[160:161], v[250:251]
	global_store_dwordx4 v[154:155], v[32:35], off offset:192
	s_nop 0
	v_add_co_u32_e32 v154, vcc, 0x10000, v154
	s_nop 1
	v_addc_co_u32_e32 v155, vcc, 0, v155, vcc
	global_load_dwordx4 v[250:253], v[150:151], off offset:64
	s_waitcnt vmcnt(10)
	v_pk_fma_f32 v[30:31], v[30:31], v[140:141], v[166:167]
	v_pk_fma_f32 v[28:29], v[28:29], v[138:139], v[164:165]
	global_store_dwordx4 v[154:155], v[28:31], off
	global_load_dwordx4 v[164:167], v[150:151], off offset:128
	s_waitcnt vmcnt(10)
	v_pk_fma_f32 v[26:27], v[26:27], v[144:145], v[170:171]
	v_pk_fma_f32 v[24:25], v[24:25], v[142:143], v[168:169]
	global_store_dwordx4 v[154:155], v[24:27], off offset:64
	global_load_dwordx4 v[168:171], v[150:151], off offset:192
	s_waitcnt vmcnt(10)
	v_pk_fma_f32 v[18:19], v[18:19], v[158:159], v[174:175]
	v_pk_fma_f32 v[16:17], v[16:17], v[156:157], v[172:173]
	global_store_dwordx4 v[154:155], v[16:19], off offset:128
	s_waitcnt vmcnt(9)
	v_pk_fma_f32 v[14:15], v[14:15], v[162:163], v[244:245]
	v_pk_fma_f32 v[12:13], v[12:13], v[160:161], v[242:243]
	global_store_dwordx4 v[154:155], v[12:15], off offset:192
	s_nop 0
	v_add_co_u32_e32 v154, vcc, 0x10000, v154
	s_nop 1
	v_addc_co_u32_e32 v155, vcc, 0, v155, vcc
	s_waitcnt vmcnt(8)
	v_pk_fma_f32 v[10:11], v[10:11], v[140:141], v[248:249]
	v_pk_fma_f32 v[8:9], v[8:9], v[138:139], v[246:247]
	global_store_dwordx4 v[154:155], v[8:11], off
	s_waitcnt vmcnt(7)
	v_pk_fma_f32 v[6:7], v[6:7], v[144:145], v[252:253]
	v_pk_fma_f32 v[4:5], v[4:5], v[142:143], v[250:251]
	global_store_dwordx4 v[154:155], v[4:7], off offset:64
	s_waitcnt vmcnt(6)
	v_pk_fma_f32 v[2:3], v[2:3], v[158:159], v[166:167]
	v_pk_fma_f32 v[0:1], v[0:1], v[156:157], v[164:165]
	global_store_dwordx4 v[154:155], v[0:3], off offset:128
	s_waitcnt vmcnt(5)
	v_pk_fma_f32 v[22:23], v[22:23], v[162:163], v[170:171]
	v_pk_fma_f32 v[20:21], v[20:21], v[160:161], v[168:169]
	global_store_dwordx4 v[154:155], v[20:23], off offset:192
	s_branch .LBB0_1529

	.amdhsa_kernel _Z14fwd_megakernel6Params
		.amdhsa_group_segment_fixed_size 0
		.amdhsa_private_segment_fixed_size 0
		.amdhsa_kernarg_size 416
		.amdhsa_user_sgpr_count 2
		.amdhsa_user_sgpr_dispatch_ptr 0
		.amdhsa_user_sgpr_queue_ptr 0
		.amdhsa_user_sgpr_kernarg_segment_ptr 1
		.amdhsa_user_sgpr_dispatch_id 0
		.amdhsa_user_sgpr_kernarg_preload_length 0
		.amdhsa_user_sgpr_kernarg_preload_offset 0
		.amdhsa_user_sgpr_private_segment_size 0
		.amdhsa_uses_dynamic_stack 0
		.amdhsa_enable_private_segment 0
		.amdhsa_system_sgpr_workgroup_id_x 1
		.amdhsa_system_sgpr_workgroup_id_y 0
		.amdhsa_system_sgpr_workgroup_id_z 0
		.amdhsa_system_sgpr_workgroup_info 0
		.amdhsa_system_vgpr_workitem_id 2
		.amdhsa_next_free_vgpr 256
		.amdhsa_next_free_sgpr 102
		.amdhsa_accum_offset 256
		.amdhsa_reserve_vcc 1
		.amdhsa_float_round_mode_32 0
		.amdhsa_float_round_mode_16_64 0
		.amdhsa_float_denorm_mode_32 3
		.amdhsa_float_denorm_mode_16_64 3
		.amdhsa_dx10_clamp 1
		.amdhsa_ieee_mode 1
		.amdhsa_fp16_overflow 0
		.amdhsa_tg_split 0
		.amdhsa_exception_fp_ieee_invalid_op 0
		.amdhsa_exception_fp_denorm_src 0
		.amdhsa_exception_fp_ieee_div_zero 0
		.amdhsa_exception_fp_ieee_overflow 0
		.amdhsa_exception_fp_ieee_underflow 0
		.amdhsa_exception_fp_ieee_inexact 0
		.amdhsa_exception_int_div_zero 0
	.end_amdhsa_kernel

amdhsa.kernels:
  - .agpr_count:     0
    .args:
      - .offset:         0
        .size:           160
        .value_kind:     by_value
      - .offset:         160
        .size:           4
        .value_kind:     hidden_block_count_x
      - .offset:         164
        .size:           4
        .value_kind:     hidden_block_count_y
      - .offset:         168
        .size:           4
        .value_kind:     hidden_block_count_z
      - .offset:         172
        .size:           2
        .value_kind:     hidden_group_size_x
      - .offset:         174
        .size:           2
        .value_kind:     hidden_group_size_y
      - .offset:         176
        .size:           2
        .value_kind:     hidden_group_size_z
      - .offset:         178
        .size:           2
        .value_kind:     hidden_remainder_x
      - .offset:         180
        .size:           2
        .value_kind:     hidden_remainder_y
      - .offset:         182
        .size:           2
        .value_kind:     hidden_remainder_z
      - .offset:         200
        .size:           8
        .value_kind:     hidden_global_offset_x
      - .offset:         208
        .size:           8
        .value_kind:     hidden_global_offset_y
      - .offset:         216
        .size:           8
        .value_kind:     hidden_global_offset_z
      - .offset:         224
        .size:           2
        .value_kind:     hidden_grid_dims
      - .offset:         248
        .size:           8
        .value_kind:     hidden_multigrid_sync_arg
      - .offset:         280
        .size:           4
        .value_kind:     hidden_dynamic_lds_size
    .group_segment_fixed_size: 0
    .kernarg_segment_align: 8
    .kernarg_segment_size: 416
    .language:       OpenCL C
    .language_version:
      - 2
      - 0
    .max_flat_workgroup_size: 512
    .name:           _Z14fwd_megakernel6Params
    .private_segment_fixed_size: 0
    .sgpr_count:     108
    .sgpr_spill_count: 65
    .symbol:         _Z14fwd_megakernel6Params.kd
    .uniform_work_group_size: 1
    .uses_dynamic_stack: false
    .vgpr_count:     256
    .vgpr_spill_count: 0
    .wavefront_size: 64
